# all 6 GEMM K-loops: LDS-DMA loads use SGPR-base+32-bit-offset form (drops 16 64-bit VALU adds/iter); in_proj/ff13 epilogue stores also saddr form
# speedup vs baseline: 1.0493x; 1.0135x over previous
; #define PG8_STAGE(bufoff, gbase, voff) do { _Pragma("unroll") for (int _i = 0; _i < 2; ++_i) \
;         __builtin_amdgcn_global_load_lds((const unsigned*)((const char*)(gbase) + (voff)[_i]), (LAS unsigned*)(lds + (bufoff) + ldsw + _i * 8192), 16, 0, 0); } while (0)
; #define PG8_LDA(dst, b, h) do { _Pragma("unroll") for (int m = 0; m < 4; ++m) _Pragma("unroll") for (int k = 0; k < 2; ++k) dst[m][k] = *(const LAS bf16x8*)(lds + PG8_SA(b, h) + aoff + m * 2048 + k * 1024); } while (0)
; #define PG8_LDB(dst, b, h) do { _Pragma("unroll") for (int n = 0; n < 2; ++n) _Pragma("unroll") for (int k = 0; k < 2; ++k) dst[n][k] = *(const LAS bf16x8*)(lds + PG8_SB(b, h) + boff + n * 2048 + k * 1024); } while (0)
; #define PG8_MMA(ai, bj, At, Bt) do { __builtin_amdgcn_s_setprio(1); _Pragma("unroll") for (int m = 0; m < 4; ++m) _Pragma("unroll") for (int n = 0; n < 2; ++n) _Pragma("unroll") for (int k = 0; k < 2; ++k) \
;         acc[ai][bj][m][n] = __builtin_amdgcn_mfma_f32_16x16x32_bf16(Bt[n][k], At[m][k], acc[ai][bj][m][n], 0, 0, 0); __builtin_amdgcn_s_setprio(0); } while (0)
; #define PG8_WAIT_V(n) asm volatile("s_waitcnt vmcnt(" #n ")" ::: "memory")
; #define PG8_WAIT_L(n) asm volatile("s_waitcnt lgkmcnt(" #n ")" ::: "memory")
; #define PG8_BAR __builtin_amdgcn_s_barrier()
; #define PG8_SCHED __builtin_amdgcn_sched_barrier(0)
; template <class Epi>
; __device__ __forceinline__ void gemm_phase(LAS unsigned char* lds, const Gemm g, const StaticOrder& S, const Epi& E) {
;     ...
;             const char* a1 = cA + (size_t)(t + 1) * kstep;
;             const char* a2 = last ? nA : cA + (size_t)(t + 2) * kstep; const char* b2 = last ? nB : cB + (size_t)(t + 2) * kstep;
;             const char* a3 = a2 + kstep; const char* b3 = b2 + kstep;
;             PG8_LDB(B0, 0, 0); PG8_SCHED; PG8_LDA(At, 0, 0); PG8_STAGE(PG8_SA(1, 1), a1 + hA, voffA);
;             PG8_WAIT_L(8); PG8_BAR; PG8_WAIT_L(0); PG8_MMA(0, 0, At, B0); PG8_BAR; PG8_SCHED;
;             PG8_LDB(B1, 0, 1); PG8_STAGE(PG8_SB(0, 0), b2, voffB);
;             PG8_BAR; PG8_WAIT_L(0); PG8_MMA(0, 1, At, B1); PG8_BAR;
;             PG8_LDA(At, 0, 1); PG8_STAGE(PG8_SA(0, 0), a2, voffA);
;             PG8_BAR; PG8_WAIT_L(0); PG8_MMA(1, 0, At, B0); PG8_BAR; PG8_SCHED;
;             PG8_STAGE(PG8_SB(0, 1), b2 + hB, voffB);
;             PG8_WAIT_V(6); PG8_BAR; PG8_MMA(1, 1, At, B1); PG8_BAR;
.LBB0_63:
	s_add_i32 vcc_lo, s66, 2
	s_add_u32 s64, s62, 0x100
	s_addc_u32 s65, s63, 0
	s_add_i32 s22, 0, 0x10000
	v_add_u32_e32 v142, s22, v188
	ds_read_b128 v[130:133], v142
	ds_read_b128 v[134:137], v142 offset:1024
	ds_read_b128 v[138:141], v142 offset:2048
	ds_read_b128 v[142:145], v142 offset:3072
	s_cmp_eq_u32 s59, s66
	s_cselect_b32 s66, s44, s61
	s_cselect_b32 s69, s43, s65
	s_cselect_b32 s68, s42, s64
	s_cselect_b32 s67, s45, s97
	s_add_i32 m0, s52, 0xc000
	ds_read_b128 v[146:149], v189
	ds_read_b128 v[150:153], v189 offset:1024
	ds_read_b128 v[154:157], v189 offset:2048
	ds_read_b128 v[168:171], v189 offset:3072
	ds_read_b128 v[172:175], v189 offset:4096
	ds_read_b128 v[176:179], v189 offset:5120
	ds_read_b128 v[180:183], v189 offset:6144
	ds_read_b128 v[190:193], v189 offset:7168
	global_load_lds_dwordx4 v164, s[62:63]
	s_add_i32 m0, s52, 0xe000
	s_nop 0
	global_load_lds_dwordx4 v166, s[62:63]
	s_waitcnt lgkmcnt(8)
	s_barrier
	s_waitcnt lgkmcnt(0)
	s_setprio 1
	s_waitcnt lgkmcnt(0)
	v_mfma_f32_16x16x32_bf16 v[126:129], v[130:133], v[146:149], v[126:129]
	v_mfma_f32_16x16x32_bf16 v[122:125], v[138:141], v[146:149], v[122:125]
	v_mfma_f32_16x16x32_bf16 v[110:113], v[130:133], v[154:157], v[110:113]
	v_mfma_f32_16x16x32_bf16 v[106:109], v[138:141], v[154:157], v[106:109]
	v_mfma_f32_16x16x32_bf16 v[94:97], v[130:133], v[172:175], v[94:97]
	v_mfma_f32_16x16x32_bf16 v[90:93], v[138:141], v[172:175], v[90:93]
	v_mfma_f32_16x16x32_bf16 v[78:81], v[130:133], v[180:183], v[78:81]
	v_mfma_f32_16x16x32_bf16 v[74:77], v[138:141], v[180:183], v[74:77]
	v_mfma_f32_16x16x32_bf16 v[126:129], v[134:137], v[150:153], v[126:129]
	v_mfma_f32_16x16x32_bf16 v[122:125], v[142:145], v[150:153], v[122:125]
	v_mfma_f32_16x16x32_bf16 v[110:113], v[134:137], v[168:171], v[110:113]
	v_mfma_f32_16x16x32_bf16 v[106:109], v[142:145], v[168:171], v[106:109]
	v_mfma_f32_16x16x32_bf16 v[94:97], v[134:137], v[176:179], v[94:97]
	v_mfma_f32_16x16x32_bf16 v[90:93], v[142:145], v[176:179], v[90:93]
	v_mfma_f32_16x16x32_bf16 v[78:81], v[134:137], v[190:193], v[78:81]
	v_mfma_f32_16x16x32_bf16 v[74:77], v[142:145], v[190:193], v[74:77]
	s_setprio 0
	s_barrier
	s_add_i32 s62, 0, 0x14000
	v_add_u32_e32 v184, s62, v188
	s_add_i32 s22, s22, s51
	ds_read_b128 v[202:205], v184
	ds_read_b128 v[206:209], v184 offset:1024
	ds_read_b128 v[210:213], v184 offset:2048
	ds_read_b128 v[214:217], v184 offset:3072
	s_mov_b32 m0, s22
	s_nop 0
	global_load_lds_dwordx4 v0, s[66:67]
	s_add_i32 m0, s22, 0x2000
	s_nop 0
	global_load_lds_dwordx4 v162, s[66:67]
	s_barrier
	s_waitcnt lgkmcnt(0)
	s_setprio 1
	s_waitcnt lgkmcnt(0)
	v_mfma_f32_16x16x32_bf16 v[118:121], v[202:205], v[146:149], v[118:121]
	v_mfma_f32_16x16x32_bf16 v[114:117], v[210:213], v[146:149], v[114:117]
	v_mfma_f32_16x16x32_bf16 v[102:105], v[202:205], v[154:157], v[102:105]
	v_mfma_f32_16x16x32_bf16 v[98:101], v[210:213], v[154:157], v[98:101]
	v_mfma_f32_16x16x32_bf16 v[86:89], v[202:205], v[172:175], v[86:89]
	v_mfma_f32_16x16x32_bf16 v[82:85], v[210:213], v[172:175], v[82:85]
	v_mfma_f32_16x16x32_bf16 v[70:73], v[202:205], v[180:183], v[70:73]
	v_mfma_f32_16x16x32_bf16 v[66:69], v[210:213], v[180:183], v[66:69]
	v_mfma_f32_16x16x32_bf16 v[118:121], v[206:209], v[150:153], v[118:121]
	v_mfma_f32_16x16x32_bf16 v[114:117], v[214:217], v[150:153], v[114:117]
	v_mfma_f32_16x16x32_bf16 v[102:105], v[206:209], v[168:171], v[102:105]
	v_mfma_f32_16x16x32_bf16 v[98:101], v[214:217], v[168:171], v[98:101]
	v_mfma_f32_16x16x32_bf16 v[86:89], v[206:209], v[176:179], v[86:89]
	v_mfma_f32_16x16x32_bf16 v[82:85], v[214:217], v[176:179], v[82:85]
	v_mfma_f32_16x16x32_bf16 v[70:73], v[206:209], v[190:193], v[70:73]
	v_mfma_f32_16x16x32_bf16 v[66:69], v[214:217], v[190:193], v[66:69]
	s_setprio 0
	s_mov_b32 m0, s52
	s_barrier
	ds_read_b128 v[146:149], v189 offset:16384
	ds_read_b128 v[150:153], v189 offset:17408
	ds_read_b128 v[154:157], v189 offset:18432
	ds_read_b128 v[168:171], v189 offset:19456
	ds_read_b128 v[172:175], v189 offset:20480
	ds_read_b128 v[176:179], v189 offset:21504
	ds_read_b128 v[180:183], v189 offset:22528
	ds_read_b128 v[190:193], v189 offset:23552
	global_load_lds_dwordx4 v158, s[68:69]
	s_mov_b32 m0, s53
	s_nop 0
	global_load_lds_dwordx4 v160, s[68:69]
	s_barrier
	s_waitcnt lgkmcnt(0)
	s_setprio 1
	s_waitcnt lgkmcnt(0)
	v_mfma_f32_16x16x32_bf16 v[62:65], v[130:133], v[146:149], v[62:65]
	v_mfma_f32_16x16x32_bf16 v[58:61], v[138:141], v[146:149], v[58:61]
	v_mfma_f32_16x16x32_bf16 v[46:49], v[130:133], v[154:157], v[46:49]
	v_mfma_f32_16x16x32_bf16 v[42:45], v[138:141], v[154:157], v[42:45]
	v_mfma_f32_16x16x32_bf16 v[30:33], v[130:133], v[172:175], v[30:33]
	v_mfma_f32_16x16x32_bf16 v[26:29], v[138:141], v[172:175], v[26:29]
	v_mfma_f32_16x16x32_bf16 v[14:17], v[130:133], v[180:183], v[14:17]
	v_mfma_f32_16x16x32_bf16 v[10:13], v[138:141], v[180:183], v[10:13]
	v_mfma_f32_16x16x32_bf16 v[62:65], v[134:137], v[150:153], v[62:65]
	v_mfma_f32_16x16x32_bf16 v[58:61], v[142:145], v[150:153], v[58:61]
	v_mfma_f32_16x16x32_bf16 v[46:49], v[134:137], v[168:171], v[46:49]
	v_mfma_f32_16x16x32_bf16 v[42:45], v[142:145], v[168:171], v[42:45]
	v_mfma_f32_16x16x32_bf16 v[30:33], v[134:137], v[176:179], v[30:33]
	v_mfma_f32_16x16x32_bf16 v[26:29], v[142:145], v[176:179], v[26:29]
	v_mfma_f32_16x16x32_bf16 v[14:17], v[134:137], v[190:193], v[14:17]
	v_mfma_f32_16x16x32_bf16 v[10:13], v[142:145], v[190:193], v[10:13]
	s_setprio 0
	s_barrier
	s_add_u32 s22, s66, 0xb0000
	s_addc_u32 s23, s67, 0
	s_add_i32 s62, s62, s51
	s_mov_b32 m0, s62
	s_nop 0
	global_load_lds_dwordx4 v0, s[22:23]
	s_add_i32 m0, s62, 0x2000
	s_nop 0
	global_load_lds_dwordx4 v162, s[22:23]
	s_waitcnt vmcnt(6)
	s_barrier
; #define PG8_STAGE(bufoff, gbase, voff) do { _Pragma("unroll") for (int _i = 0; _i < 2; ++_i) \
;         __builtin_amdgcn_global_load_lds((const unsigned*)((const char*)(gbase) + (voff)[_i]), (LAS unsigned*)(lds + (bufoff) + ldsw + _i * 8192), 16, 0, 0); } while (0)
; #define PG8_LDA(dst, b, h) do { _Pragma("unroll") for (int m = 0; m < 4; ++m) _Pragma("unroll") for (int k = 0; k < 2; ++k) dst[m][k] = *(const LAS bf16x8*)(lds + PG8_SA(b, h) + aoff + m * 2048 + k * 1024); } while (0)
; #define PG8_LDB(dst, b, h) do { _Pragma("unroll") for (int n = 0; n < 2; ++n) _Pragma("unroll") for (int k = 0; k < 2; ++k) dst[n][k] = *(const LAS bf16x8*)(lds + PG8_SB(b, h) + boff + n * 2048 + k * 1024); } while (0)
; #define PG8_MMA(ai, bj, At, Bt) do { __builtin_amdgcn_s_setprio(1); _Pragma("unroll") for (int m = 0; m < 4; ++m) _Pragma("unroll") for (int n = 0; n < 2; ++n) _Pragma("unroll") for (int k = 0; k < 2; ++k) \
;         acc[ai][bj][m][n] = __builtin_amdgcn_mfma_f32_16x16x32_bf16(Bt[n][k], At[m][k], acc[ai][bj][m][n], 0, 0, 0); __builtin_amdgcn_s_setprio(0); } while (0)
; #define PG8_WAIT_V(n) asm volatile("s_waitcnt vmcnt(" #n ")" ::: "memory")
; #define PG8_WAIT_L(n) asm volatile("s_waitcnt lgkmcnt(" #n ")" ::: "memory")
; #define PG8_BAR __builtin_amdgcn_s_barrier()
; #define PG8_SCHED __builtin_amdgcn_sched_barrier(0)
; template <class Epi>
; __device__ __forceinline__ void gemm_phase(LAS unsigned char* lds, const Gemm g, const StaticOrder& S, const Epi& E) {
;     ...
;             PG8_WAIT_V(6); PG8_BAR; PG8_MMA(1, 1, At, B1); PG8_BAR;
;             PG8_LDB(B0, 1, 0); PG8_SCHED; PG8_LDA(At, 1, 0); PG8_STAGE(PG8_SA(0, 1), a2 + hA, voffA);
;             PG8_WAIT_L(8); PG8_BAR; PG8_WAIT_L(0); PG8_MMA(0, 0, At, B0); PG8_BAR; PG8_SCHED;
;             PG8_LDB(B1, 1, 1); PG8_STAGE(PG8_SB(1, 0), b3, voffB);
;             PG8_BAR; PG8_WAIT_L(0); PG8_MMA(0, 1, At, B1); PG8_BAR;
;             PG8_LDA(At, 1, 1); PG8_STAGE(PG8_SA(1, 0), a3, voffA);
;             PG8_BAR; PG8_WAIT_L(0); PG8_MMA(1, 0, At, B0); PG8_BAR; PG8_SCHED;
	s_setprio 1
	v_mfma_f32_16x16x32_bf16 v[54:57], v[202:205], v[146:149], v[54:57]
	v_mfma_f32_16x16x32_bf16 v[50:53], v[210:213], v[146:149], v[50:53]
	v_mfma_f32_16x16x32_bf16 v[38:41], v[202:205], v[154:157], v[38:41]
	v_mfma_f32_16x16x32_bf16 v[34:37], v[210:213], v[154:157], v[34:37]
	v_mfma_f32_16x16x32_bf16 v[22:25], v[202:205], v[172:175], v[22:25]
	v_mfma_f32_16x16x32_bf16 v[18:21], v[210:213], v[172:175], v[18:21]
	v_mfma_f32_16x16x32_bf16 v[6:9], v[202:205], v[180:183], v[6:9]
	v_mfma_f32_16x16x32_bf16 v[2:5], v[210:213], v[180:183], v[2:5]
	v_mfma_f32_16x16x32_bf16 v[54:57], v[206:209], v[150:153], v[54:57]
	v_mfma_f32_16x16x32_bf16 v[50:53], v[214:217], v[150:153], v[50:53]
	v_mfma_f32_16x16x32_bf16 v[38:41], v[206:209], v[168:171], v[38:41]
	v_mfma_f32_16x16x32_bf16 v[34:37], v[214:217], v[168:171], v[34:37]
	v_mfma_f32_16x16x32_bf16 v[22:25], v[206:209], v[176:179], v[22:25]
	v_mfma_f32_16x16x32_bf16 v[18:21], v[214:217], v[176:179], v[18:21]
	v_mfma_f32_16x16x32_bf16 v[6:9], v[206:209], v[190:193], v[6:9]
	v_mfma_f32_16x16x32_bf16 v[2:5], v[214:217], v[190:193], v[2:5]
	s_setprio 0
	s_add_i32 s62, 0, 0x18000
	v_add_u32_e32 v142, s62, v188
	s_barrier
	ds_read_b128 v[130:133], v142
	ds_read_b128 v[134:137], v142 offset:1024
	ds_read_b128 v[138:141], v142 offset:2048
	ds_read_b128 v[142:145], v142 offset:3072
	s_add_u32 s22, s68, 0xb0000
	s_addc_u32 s23, s69, 0
	s_mov_b32 m0, s56
	ds_read_b128 v[146:149], v189 offset:32768
	ds_read_b128 v[150:153], v189 offset:33792
	ds_read_b128 v[154:157], v189 offset:34816
	ds_read_b128 v[168:171], v189 offset:35840
	ds_read_b128 v[172:175], v189 offset:36864
	ds_read_b128 v[176:179], v189 offset:37888
	ds_read_b128 v[180:183], v189 offset:38912
	ds_read_b128 v[190:193], v189 offset:39936
	global_load_lds_dwordx4 v158, s[22:23]
	s_mov_b32 m0, s57
	s_nop 0
	global_load_lds_dwordx4 v160, s[22:23]
	s_waitcnt lgkmcnt(8)
	s_barrier
	s_waitcnt lgkmcnt(0)
	s_setprio 1
	s_waitcnt lgkmcnt(0)
	v_mfma_f32_16x16x32_bf16 v[126:129], v[130:133], v[146:149], v[126:129]
	v_mfma_f32_16x16x32_bf16 v[122:125], v[138:141], v[146:149], v[122:125]
	v_mfma_f32_16x16x32_bf16 v[110:113], v[130:133], v[154:157], v[110:113]
	v_mfma_f32_16x16x32_bf16 v[106:109], v[138:141], v[154:157], v[106:109]
	v_mfma_f32_16x16x32_bf16 v[94:97], v[130:133], v[172:175], v[94:97]
	v_mfma_f32_16x16x32_bf16 v[90:93], v[138:141], v[172:175], v[90:93]
	v_mfma_f32_16x16x32_bf16 v[78:81], v[130:133], v[180:183], v[78:81]
	v_mfma_f32_16x16x32_bf16 v[74:77], v[138:141], v[180:183], v[74:77]
	v_mfma_f32_16x16x32_bf16 v[126:129], v[134:137], v[150:153], v[126:129]
	v_mfma_f32_16x16x32_bf16 v[122:125], v[142:145], v[150:153], v[122:125]
	v_mfma_f32_16x16x32_bf16 v[110:113], v[134:137], v[168:171], v[110:113]
	v_mfma_f32_16x16x32_bf16 v[106:109], v[142:145], v[168:171], v[106:109]
	v_mfma_f32_16x16x32_bf16 v[94:97], v[134:137], v[176:179], v[94:97]
	v_mfma_f32_16x16x32_bf16 v[90:93], v[142:145], v[176:179], v[90:93]
	v_mfma_f32_16x16x32_bf16 v[78:81], v[134:137], v[190:193], v[78:81]
	v_mfma_f32_16x16x32_bf16 v[74:77], v[142:145], v[190:193], v[74:77]
	s_setprio 0
	s_barrier
	s_add_i32 s63, 0, 0x1c000
	s_add_i32 s22, s62, s51
	v_add_u32_e32 v214, s63, v188
	s_mov_b32 m0, s22
	ds_read_b128 v[202:205], v214
	ds_read_b128 v[206:209], v214 offset:1024
	ds_read_b128 v[210:213], v214 offset:2048
	ds_read_b128 v[214:217], v214 offset:3072
	s_add_u32 s100, s66, 0x80
	s_addc_u32 s101, s67, 0
	global_load_lds_dwordx4 v0, s[100:101]
	s_add_i32 m0, s22, 0x2000
	s_nop 0
	global_load_lds_dwordx4 v162, s[100:101]
	s_barrier
	s_waitcnt lgkmcnt(0)
	s_setprio 1
	s_waitcnt lgkmcnt(0)
	v_mfma_f32_16x16x32_bf16 v[118:121], v[202:205], v[146:149], v[118:121]
	v_mfma_f32_16x16x32_bf16 v[114:117], v[210:213], v[146:149], v[114:117]
	v_mfma_f32_16x16x32_bf16 v[102:105], v[202:205], v[154:157], v[102:105]
	v_mfma_f32_16x16x32_bf16 v[98:101], v[210:213], v[154:157], v[98:101]
	v_mfma_f32_16x16x32_bf16 v[86:89], v[202:205], v[172:175], v[86:89]
	v_mfma_f32_16x16x32_bf16 v[82:85], v[210:213], v[172:175], v[82:85]
	v_mfma_f32_16x16x32_bf16 v[70:73], v[202:205], v[180:183], v[70:73]
	v_mfma_f32_16x16x32_bf16 v[66:69], v[210:213], v[180:183], v[66:69]
	v_mfma_f32_16x16x32_bf16 v[118:121], v[206:209], v[150:153], v[118:121]
	v_mfma_f32_16x16x32_bf16 v[114:117], v[214:217], v[150:153], v[114:117]
	v_mfma_f32_16x16x32_bf16 v[102:105], v[206:209], v[168:171], v[102:105]
	v_mfma_f32_16x16x32_bf16 v[98:101], v[214:217], v[168:171], v[98:101]
	v_mfma_f32_16x16x32_bf16 v[86:89], v[206:209], v[176:179], v[86:89]
	v_mfma_f32_16x16x32_bf16 v[82:85], v[214:217], v[176:179], v[82:85]
	v_mfma_f32_16x16x32_bf16 v[70:73], v[206:209], v[190:193], v[70:73]
	v_mfma_f32_16x16x32_bf16 v[66:69], v[214:217], v[190:193], v[66:69]
	s_setprio 0
	s_mov_b32 m0, s54
	s_barrier
	ds_read_b128 v[146:149], v189 offset:49152
	ds_read_b128 v[150:153], v189 offset:50176
	ds_read_b128 v[154:157], v189 offset:51200
	ds_read_b128 v[168:171], v189 offset:52224
	ds_read_b128 v[172:175], v189 offset:53248
	ds_read_b128 v[176:179], v189 offset:54272
	ds_read_b128 v[180:183], v189 offset:55296
	ds_read_b128 v[190:193], v189 offset:56320
	s_add_u32 s100, s68, 0x80
	s_addc_u32 s101, s69, 0
	global_load_lds_dwordx4 v158, s[100:101]
	s_mov_b32 m0, s55
	s_nop 0
	global_load_lds_dwordx4 v160, s[100:101]
	s_barrier
; #define PG8_STAGE(bufoff, gbase, voff) do { _Pragma("unroll") for (int _i = 0; _i < 2; ++_i) \
;         __builtin_amdgcn_global_load_lds((const unsigned*)((const char*)(gbase) + (voff)[_i]), (LAS unsigned*)(lds + (bufoff) + ldsw + _i * 8192), 16, 0, 0); } while (0)
; #define PG8_MMA(ai, bj, At, Bt) do { __builtin_amdgcn_s_setprio(1); _Pragma("unroll") for (int m = 0; m < 4; ++m) _Pragma("unroll") for (int n = 0; n < 2; ++n) _Pragma("unroll") for (int k = 0; k < 2; ++k) \
;         acc[ai][bj][m][n] = __builtin_amdgcn_mfma_f32_16x16x32_bf16(Bt[n][k], At[m][k], acc[ai][bj][m][n], 0, 0, 0); __builtin_amdgcn_s_setprio(0); } while (0)
; #define PG8_WAIT_V(n) asm volatile("s_waitcnt vmcnt(" #n ")" ::: "memory")
; #define PG8_WAIT_L(n) asm volatile("s_waitcnt lgkmcnt(" #n ")" ::: "memory")
; #define PG8_BAR __builtin_amdgcn_s_barrier()
; #define PG8_SCHED __builtin_amdgcn_sched_barrier(0)
; template <class Epi>
; __device__ __forceinline__ void gemm_phase(LAS unsigned char* lds, const Gemm g, const StaticOrder& S, const Epi& E) {
;     ...
;             PG8_BAR; PG8_WAIT_L(0); PG8_MMA(1, 0, At, B0); PG8_BAR; PG8_SCHED;
;             PG8_STAGE(PG8_SB(1, 1), b3 + hB, voffB);
;             PG8_WAIT_V(6); PG8_BAR; PG8_MMA(1, 1, At, B1); PG8_BAR;
;         }
;     __device__ __forceinline__ void operator()(const Acc& acc, const Unit& u, int wr, int wc, int fr, int fq) const {
;     ...
;         if (u.split) {
;             float* pt = part + (size_t)(u.split - 1) * 256 * DM;
; #pragma unroll
;             for (int ai = 0; ai < 2; ++ai)
; #pragma unroll
;                 for (int m = 0; m < 4; ++m)
; #pragma unroll
;                     for (int bj = 0; bj < 2; ++bj)
; #pragma unroll
;                         for (int n = 0; n < 2; ++n) *(f32x4*)(pt + (size_t)(wr * 64 + fr + ai * 128 + m * 16) * DM + col0 + bj * 128 + n * 4) = acc[ai][bj][m][n] * sc;
;             return; }
	s_waitcnt lgkmcnt(0)
	s_setprio 1
	s_waitcnt lgkmcnt(0)
	v_mfma_f32_16x16x32_bf16 v[62:65], v[130:133], v[146:149], v[62:65]
	v_mfma_f32_16x16x32_bf16 v[58:61], v[138:141], v[146:149], v[58:61]
	v_mfma_f32_16x16x32_bf16 v[46:49], v[130:133], v[154:157], v[46:49]
	v_mfma_f32_16x16x32_bf16 v[42:45], v[138:141], v[154:157], v[42:45]
	v_mfma_f32_16x16x32_bf16 v[30:33], v[130:133], v[172:175], v[30:33]
	v_mfma_f32_16x16x32_bf16 v[26:29], v[138:141], v[172:175], v[26:29]
	v_mfma_f32_16x16x32_bf16 v[14:17], v[130:133], v[180:183], v[14:17]
	v_mfma_f32_16x16x32_bf16 v[10:13], v[138:141], v[180:183], v[10:13]
	v_mfma_f32_16x16x32_bf16 v[62:65], v[134:137], v[150:153], v[62:65]
	v_mfma_f32_16x16x32_bf16 v[58:61], v[142:145], v[150:153], v[58:61]
	v_mfma_f32_16x16x32_bf16 v[46:49], v[134:137], v[168:171], v[46:49]
	v_mfma_f32_16x16x32_bf16 v[42:45], v[142:145], v[168:171], v[42:45]
	v_mfma_f32_16x16x32_bf16 v[30:33], v[134:137], v[176:179], v[30:33]
	v_mfma_f32_16x16x32_bf16 v[26:29], v[142:145], v[176:179], v[26:29]
	v_mfma_f32_16x16x32_bf16 v[14:17], v[134:137], v[190:193], v[14:17]
	v_mfma_f32_16x16x32_bf16 v[10:13], v[142:145], v[190:193], v[10:13]
	s_setprio 0
	s_barrier
	s_add_u32 s22, s66, 0xb0080
	s_addc_u32 s23, s67, 0
	s_add_i32 s62, s63, s51
	s_mov_b32 m0, s62
	s_nop 0
	global_load_lds_dwordx4 v0, s[22:23]
	s_add_i32 m0, s62, 0x2000
	s_nop 0
	global_load_lds_dwordx4 v162, s[22:23]
	s_waitcnt vmcnt(6)
	s_barrier
	s_setprio 1
	v_mfma_f32_16x16x32_bf16 v[54:57], v[202:205], v[146:149], v[54:57]
	v_mfma_f32_16x16x32_bf16 v[50:53], v[210:213], v[146:149], v[50:53]
	v_mfma_f32_16x16x32_bf16 v[38:41], v[202:205], v[154:157], v[38:41]
	v_mfma_f32_16x16x32_bf16 v[34:37], v[210:213], v[154:157], v[34:37]
	v_mfma_f32_16x16x32_bf16 v[22:25], v[202:205], v[172:175], v[22:25]
	v_mfma_f32_16x16x32_bf16 v[18:21], v[210:213], v[172:175], v[18:21]
	v_mfma_f32_16x16x32_bf16 v[6:9], v[202:205], v[180:183], v[6:9]
	v_mfma_f32_16x16x32_bf16 v[2:5], v[210:213], v[180:183], v[2:5]
	v_mfma_f32_16x16x32_bf16 v[54:57], v[206:209], v[150:153], v[54:57]
	v_mfma_f32_16x16x32_bf16 v[50:53], v[214:217], v[150:153], v[50:53]
	v_mfma_f32_16x16x32_bf16 v[38:41], v[206:209], v[168:171], v[38:41]
	v_mfma_f32_16x16x32_bf16 v[34:37], v[214:217], v[168:171], v[34:37]
	v_mfma_f32_16x16x32_bf16 v[22:25], v[206:209], v[176:179], v[22:25]
	v_mfma_f32_16x16x32_bf16 v[18:21], v[214:217], v[176:179], v[18:21]
	v_mfma_f32_16x16x32_bf16 v[6:9], v[206:209], v[190:193], v[6:9]
	v_mfma_f32_16x16x32_bf16 v[2:5], v[214:217], v[190:193], v[2:5]
	s_setprio 0
	s_add_u32 s61, s61, 0x100
	s_addc_u32 s97, s97, 0
	s_cmp_ge_i32 vcc_lo, s33
	s_mov_b64 s[62:63], s[64:65]
	s_mov_b32 s66, vcc_lo
	s_barrier
	s_cbranch_scc0 .LBB0_63
	s_lshl_b32 s22, s46, 8
	v_mov_b32_e32 v133, v186
	v_mov_b32_e32 v132, v187
	s_or_b32 s22, s22, s76
	s_cmp_lg_u32 s60, 0
	v_lshl_add_u32 v168, v132, 3, s22
	v_add_u32_e32 v130, s75, v133
	v_ashrrev_i32_e32 v169, 31, v168
	s_cbranch_scc0 .LBB0_66
	s_ashr_i32 s61, s60, 31
	s_lshl_b64 s[22:23], s[60:61], 20
	s_add_u32 s22, s15, s22
	s_addc_u32 s23, s18, s23
	v_ashrrev_i32_e32 v131, 31, v130
	v_lshl_add_u64 v[134:135], v[168:169], 2, s[22:23]
	v_lshlrev_b64 v[136:137], 12, v[130:131]
	s_mov_b32 s22, 0xfff00000
	v_lshl_add_u64 v[134:135], v[134:135], 0, v[136:137]
	s_mov_b32 s23, -1
	v_lshl_add_u64 v[136:137], v[134:135], 0, s[22:23]
	v_add_co_u32_e32 v138, vcc, s0, v134
	s_mov_b32 s22, 0xfff10000
	s_nop 0
	v_addc_co_u32_e32 v139, vcc, -1, v135, vcc
	s_mov_b32 s23, -1
	global_store_dwordx4 v[138:139], v[126:129], off
	global_store_dwordx4 v[136:137], v[122:125], off offset:16
	global_store_dwordx4 v[136:137], v[118:121], off offset:512
	global_store_dwordx4 v[136:137], v[114:117], off offset:528
	v_lshl_add_u64 v[136:137], v[134:135], 0, s[22:23]
	v_add_co_u32_e32 v138, vcc, s1, v134
	s_mov_b32 s22, 0xfff20000
	s_nop 0
	v_addc_co_u32_e32 v139, vcc, -1, v135, vcc
	s_mov_b32 s23, -1
	global_store_dwordx4 v[138:139], v[110:113], off
	global_store_dwordx4 v[136:137], v[106:109], off offset:16
	global_store_dwordx4 v[136:137], v[102:105], off offset:512
	global_store_dwordx4 v[136:137], v[98:101], off offset:528
	v_lshl_add_u64 v[136:137], v[134:135], 0, s[22:23]
	s_mov_b32 s22, 0xfff20000
	v_add_co_u32_e32 v138, vcc, s22, v134
	s_mov_b32 s22, 0xfff30000
	s_nop 0
	v_addc_co_u32_e32 v139, vcc, -1, v135, vcc
	s_mov_b32 s23, -1
	global_store_dwordx4 v[138:139], v[94:97], off
	global_store_dwordx4 v[136:137], v[90:93], off offset:16
	global_store_dwordx4 v[136:137], v[86:89], off offset:512
	global_store_dwordx4 v[136:137], v[82:85], off offset:528
	v_lshl_add_u64 v[136:137], v[134:135], 0, s[22:23]
	s_mov_b32 s22, 0xfff30000
	v_add_co_u32_e32 v138, vcc, s22, v134
	s_mov_b32 s22, 0xfff80000
	s_nop 0
	v_addc_co_u32_e32 v139, vcc, -1, v135, vcc
	s_mov_b32 s23, -1
	global_store_dwordx4 v[138:139], v[78:81], off
	global_store_dwordx4 v[136:137], v[74:77], off offset:16
	global_store_dwordx4 v[136:137], v[70:73], off offset:512
	global_store_dwordx4 v[136:137], v[66:69], off offset:528
	v_lshl_add_u64 v[136:137], v[134:135], 0, s[22:23]
	s_mov_b32 s22, 0xfff80000
	v_add_co_u32_e32 v138, vcc, s22, v134
	s_mov_b32 s22, 0xfff90000
	s_nop 0
	v_addc_co_u32_e32 v139, vcc, -1, v135, vcc
	s_mov_b32 s23, -1
	global_store_dwordx4 v[138:139], v[62:65], off
	global_store_dwordx4 v[136:137], v[58:61], off offset:16
	global_store_dwordx4 v[136:137], v[54:57], off offset:512
	global_store_dwordx4 v[136:137], v[50:53], off offset:528
	v_lshl_add_u64 v[136:137], v[134:135], 0, s[22:23]
	s_mov_b32 s22, 0xfff90000
	v_add_co_u32_e32 v138, vcc, s22, v134
	s_mov_b32 s22, 0xfffa0000
	s_nop 0
	v_addc_co_u32_e32 v139, vcc, -1, v135, vcc
	s_mov_b32 s23, -1
	global_store_dwordx4 v[138:139], v[46:49], off
	global_store_dwordx4 v[136:137], v[42:45], off offset:16
	global_store_dwordx4 v[136:137], v[38:41], off offset:512
	global_store_dwordx4 v[136:137], v[34:37], off offset:528
	v_lshl_add_u64 v[136:137], v[134:135], 0, s[22:23]
	s_mov_b32 s22, 0xfffa0000
	v_add_co_u32_e32 v138, vcc, s22, v134
	s_mov_b32 s22, 0xfffb0000
	s_nop 0
	v_addc_co_u32_e32 v139, vcc, -1, v135, vcc
	s_mov_b32 s23, -1
	global_store_dwordx4 v[138:139], v[30:33], off
	global_store_dwordx4 v[136:137], v[26:29], off offset:16
	global_store_dwordx4 v[136:137], v[22:25], off offset:512
	global_store_dwordx4 v[136:137], v[18:21], off offset:528
	v_lshl_add_u64 v[136:137], v[134:135], 0, s[22:23]
	v_add_co_u32_e32 v134, vcc, 0xfffb0000, v134
	s_nop 1
	v_addc_co_u32_e32 v135, vcc, -1, v135, vcc
	global_store_dwordx4 v[134:135], v[14:17], off
	global_store_dwordx4 v[136:137], v[10:13], off offset:16
	global_store_dwordx4 v[136:137], v[6:9], off offset:512
	global_store_dwordx4 v[136:137], v[2:5], off offset:528
	s_cbranch_execnz .LBB0_47
	s_branch .LBB0_67

; #define PG8_STAGE(bufoff, gbase, voff) do { _Pragma("unroll") for (int _i = 0; _i < 2; ++_i) \
;         __builtin_amdgcn_global_load_lds((const unsigned*)((const char*)(gbase) + (voff)[_i]), (LAS unsigned*)(lds + (bufoff) + ldsw + _i * 8192), 16, 0, 0); } while (0)
; #define PG8_LDA(dst, b, h) do { _Pragma("unroll") for (int m = 0; m < 4; ++m) _Pragma("unroll") for (int k = 0; k < 2; ++k) dst[m][k] = *(const LAS bf16x8*)(lds + PG8_SA(b, h) + aoff + m * 2048 + k * 1024); } while (0)
; #define PG8_LDB(dst, b, h) do { _Pragma("unroll") for (int n = 0; n < 2; ++n) _Pragma("unroll") for (int k = 0; k < 2; ++k) dst[n][k] = *(const LAS bf16x8*)(lds + PG8_SB(b, h) + boff + n * 2048 + k * 1024); } while (0)
; #define PG8_MMA(ai, bj, At, Bt) do { __builtin_amdgcn_s_setprio(1); _Pragma("unroll") for (int m = 0; m < 4; ++m) _Pragma("unroll") for (int n = 0; n < 2; ++n) _Pragma("unroll") for (int k = 0; k < 2; ++k) \
;         acc[ai][bj][m][n] = __builtin_amdgcn_mfma_f32_16x16x32_bf16(Bt[n][k], At[m][k], acc[ai][bj][m][n], 0, 0, 0); __builtin_amdgcn_s_setprio(0); } while (0)
; #define PG8_WAIT_V(n) asm volatile("s_waitcnt vmcnt(" #n ")" ::: "memory")
; #define PG8_WAIT_L(n) asm volatile("s_waitcnt lgkmcnt(" #n ")" ::: "memory")
; #define PG8_BAR __builtin_amdgcn_s_barrier()
; #define PG8_SCHED __builtin_amdgcn_sched_barrier(0)
; template <class Epi>
; __device__ __forceinline__ void gemm_phase(LAS unsigned char* lds, const Gemm g, const StaticOrder& S, const Epi& E) {
;     ...
;             const char* a1 = cA + (size_t)(t + 1) * kstep;
;             const char* a2 = last ? nA : cA + (size_t)(t + 2) * kstep; const char* b2 = last ? nB : cB + (size_t)(t + 2) * kstep;
;             const char* a3 = a2 + kstep; const char* b3 = b2 + kstep;
;             PG8_LDB(B0, 0, 0); PG8_SCHED; PG8_LDA(At, 0, 0); PG8_STAGE(PG8_SA(1, 1), a1 + hA, voffA);
;             PG8_WAIT_L(8); PG8_BAR; PG8_WAIT_L(0); PG8_MMA(0, 0, At, B0); PG8_BAR; PG8_SCHED;
;             PG8_LDB(B1, 0, 1); PG8_STAGE(PG8_SB(0, 0), b2, voffB);
;             PG8_BAR; PG8_WAIT_L(0); PG8_MMA(0, 1, At, B1); PG8_BAR;
;             PG8_LDA(At, 0, 1); PG8_STAGE(PG8_SA(0, 0), a2, voffA);
;             PG8_BAR; PG8_WAIT_L(0); PG8_MMA(1, 0, At, B0); PG8_BAR; PG8_SCHED;
;             PG8_STAGE(PG8_SB(0, 1), b2 + hB, voffB);
;             PG8_WAIT_V(6); PG8_BAR; PG8_MMA(1, 1, At, B1); PG8_BAR;
.LBB0_104:
	s_add_u32 s22, s62, 0xfffc0080
	s_addc_u32 s23, s63, -1
	s_add_i32 s75, 0, 0x10000
	v_add_u32_e32 v151, s75, v147
	ds_read_b128 v[156:159], v151
	ds_read_b128 v[160:163], v151 offset:1024
	ds_read_b128 v[164:167], v151 offset:2048
	ds_read_b128 v[168:171], v151 offset:3072
	s_cmp_eq_u32 s74, 12
	s_cselect_b32 s67, s43, s23
	s_cselect_b32 s66, s61, s22
	s_cselect_b32 s65, s41, s71
	s_cselect_b32 s64, s69, s70
	s_add_i32 m0, s50, 0xc000
	ds_read_b128 v[172:175], v149
	ds_read_b128 v[176:179], v149 offset:1024
	ds_read_b128 v[180:183], v149 offset:2048
	ds_read_b128 v[184:187], v149 offset:3072
	ds_read_b128 v[188:191], v149 offset:4096
	ds_read_b128 v[192:195], v149 offset:5120
	ds_read_b128 v[202:205], v149 offset:6144
	ds_read_b128 v[206:209], v149 offset:7168
	global_load_lds_dwordx4 v138, s[62:63]
	s_add_i32 m0, s50, 0xe000
	s_nop 0
	global_load_lds_dwordx4 v140, s[62:63]
	s_waitcnt lgkmcnt(8)
	s_barrier
	s_waitcnt lgkmcnt(0)
	s_setprio 1
	s_waitcnt lgkmcnt(0)
	v_mfma_f32_16x16x32_bf16 v[126:129], v[156:159], v[172:175], v[126:129]
	v_mfma_f32_16x16x32_bf16 v[118:121], v[164:167], v[172:175], v[118:121]
	v_mfma_f32_16x16x32_bf16 v[110:113], v[156:159], v[180:183], v[110:113]
	v_mfma_f32_16x16x32_bf16 v[102:105], v[164:167], v[180:183], v[102:105]
	v_mfma_f32_16x16x32_bf16 v[94:97], v[156:159], v[188:191], v[94:97]
	v_mfma_f32_16x16x32_bf16 v[86:89], v[164:167], v[188:191], v[86:89]
	v_mfma_f32_16x16x32_bf16 v[78:81], v[156:159], v[202:205], v[78:81]
	v_mfma_f32_16x16x32_bf16 v[70:73], v[164:167], v[202:205], v[70:73]
	v_mfma_f32_16x16x32_bf16 v[126:129], v[160:163], v[176:179], v[126:129]
	v_mfma_f32_16x16x32_bf16 v[118:121], v[168:171], v[176:179], v[118:121]
	v_mfma_f32_16x16x32_bf16 v[110:113], v[160:163], v[184:187], v[110:113]
	v_mfma_f32_16x16x32_bf16 v[102:105], v[168:171], v[184:187], v[102:105]
	v_mfma_f32_16x16x32_bf16 v[94:97], v[160:163], v[192:195], v[94:97]
	v_mfma_f32_16x16x32_bf16 v[86:89], v[168:171], v[192:195], v[86:89]
	v_mfma_f32_16x16x32_bf16 v[78:81], v[160:163], v[206:209], v[78:81]
	v_mfma_f32_16x16x32_bf16 v[70:73], v[168:171], v[206:209], v[70:73]
	s_setprio 0
	s_barrier
	s_add_i32 s76, 0, 0x14000
	s_add_i32 s22, s75, s48
	v_add_u32_e32 v151, s76, v147
	s_mov_b32 m0, s22
	ds_read_b128 v[210:213], v151
	ds_read_b128 v[214:217], v151 offset:1024
	ds_read_b128 v[218:221], v151 offset:2048
	ds_read_b128 v[222:225], v151 offset:3072
	global_load_lds_dwordx4 v0, s[64:65]
	s_add_i32 m0, s22, 0x2000
	s_nop 0
	global_load_lds_dwordx4 v134, s[64:65]
	s_barrier
	s_waitcnt lgkmcnt(0)
	s_setprio 1
	s_waitcnt lgkmcnt(0)
	v_mfma_f32_16x16x32_bf16 v[122:125], v[210:213], v[172:175], v[122:125]
	v_mfma_f32_16x16x32_bf16 v[114:117], v[218:221], v[172:175], v[114:117]
	v_mfma_f32_16x16x32_bf16 v[106:109], v[210:213], v[180:183], v[106:109]
	v_mfma_f32_16x16x32_bf16 v[98:101], v[218:221], v[180:183], v[98:101]
	v_mfma_f32_16x16x32_bf16 v[90:93], v[210:213], v[188:191], v[90:93]
	v_mfma_f32_16x16x32_bf16 v[82:85], v[218:221], v[188:191], v[82:85]
	v_mfma_f32_16x16x32_bf16 v[74:77], v[210:213], v[202:205], v[74:77]
	v_mfma_f32_16x16x32_bf16 v[66:69], v[218:221], v[202:205], v[66:69]
	v_mfma_f32_16x16x32_bf16 v[122:125], v[214:217], v[176:179], v[122:125]
	v_mfma_f32_16x16x32_bf16 v[114:117], v[222:225], v[176:179], v[114:117]
	v_mfma_f32_16x16x32_bf16 v[106:109], v[214:217], v[184:187], v[106:109]
	v_mfma_f32_16x16x32_bf16 v[98:101], v[222:225], v[184:187], v[98:101]
	v_mfma_f32_16x16x32_bf16 v[90:93], v[214:217], v[192:195], v[90:93]
	v_mfma_f32_16x16x32_bf16 v[82:85], v[222:225], v[192:195], v[82:85]
	v_mfma_f32_16x16x32_bf16 v[74:77], v[214:217], v[206:209], v[74:77]
	v_mfma_f32_16x16x32_bf16 v[66:69], v[222:225], v[206:209], v[66:69]
	s_setprio 0
	s_mov_b32 m0, s50
	s_barrier
	ds_read_b128 v[172:175], v149 offset:16384
	ds_read_b128 v[176:179], v149 offset:17408
	ds_read_b128 v[180:183], v149 offset:18432
	ds_read_b128 v[184:187], v149 offset:19456
	ds_read_b128 v[188:191], v149 offset:20480
	ds_read_b128 v[192:195], v149 offset:21504
	ds_read_b128 v[202:205], v149 offset:22528
	ds_read_b128 v[206:209], v149 offset:23552
	global_load_lds_dwordx4 v130, s[66:67]
	s_mov_b32 m0, s51
	s_nop 0
	global_load_lds_dwordx4 v132, s[66:67]
	s_barrier
	s_waitcnt lgkmcnt(0)
	s_setprio 1
	s_waitcnt lgkmcnt(0)
	v_mfma_f32_16x16x32_bf16 v[62:65], v[156:159], v[172:175], v[62:65]
	v_mfma_f32_16x16x32_bf16 v[54:57], v[164:167], v[172:175], v[54:57]
	v_mfma_f32_16x16x32_bf16 v[46:49], v[156:159], v[180:183], v[46:49]
	v_mfma_f32_16x16x32_bf16 v[38:41], v[164:167], v[180:183], v[38:41]
	v_mfma_f32_16x16x32_bf16 v[30:33], v[156:159], v[188:191], v[30:33]
	v_mfma_f32_16x16x32_bf16 v[22:25], v[164:167], v[188:191], v[22:25]
	v_mfma_f32_16x16x32_bf16 v[14:17], v[156:159], v[202:205], v[14:17]
	v_mfma_f32_16x16x32_bf16 v[6:9], v[164:167], v[202:205], v[6:9]
	v_mfma_f32_16x16x32_bf16 v[62:65], v[160:163], v[176:179], v[62:65]
	v_mfma_f32_16x16x32_bf16 v[54:57], v[168:171], v[176:179], v[54:57]
	v_mfma_f32_16x16x32_bf16 v[46:49], v[160:163], v[184:187], v[46:49]
	v_mfma_f32_16x16x32_bf16 v[38:41], v[168:171], v[184:187], v[38:41]
	v_mfma_f32_16x16x32_bf16 v[30:33], v[160:163], v[192:195], v[30:33]
	v_mfma_f32_16x16x32_bf16 v[22:25], v[168:171], v[192:195], v[22:25]
	v_mfma_f32_16x16x32_bf16 v[14:17], v[160:163], v[206:209], v[14:17]
	v_mfma_f32_16x16x32_bf16 v[6:9], v[168:171], v[206:209], v[6:9]
	s_setprio 0
	s_barrier
	s_add_u32 s22, s64, 0x40000
	s_addc_u32 s23, s65, 0
	s_add_i32 s75, s76, s48
	s_mov_b32 m0, s75
	s_nop 0
	global_load_lds_dwordx4 v0, s[22:23]
	s_add_i32 m0, s75, 0x2000
	s_nop 0
	global_load_lds_dwordx4 v134, s[22:23]
	s_waitcnt vmcnt(6)
	s_barrier
; #define PG8_STAGE(bufoff, gbase, voff) do { _Pragma("unroll") for (int _i = 0; _i < 2; ++_i) \
;         __builtin_amdgcn_global_load_lds((const unsigned*)((const char*)(gbase) + (voff)[_i]), (LAS unsigned*)(lds + (bufoff) + ldsw + _i * 8192), 16, 0, 0); } while (0)
; #define PG8_LDA(dst, b, h) do { _Pragma("unroll") for (int m = 0; m < 4; ++m) _Pragma("unroll") for (int k = 0; k < 2; ++k) dst[m][k] = *(const LAS bf16x8*)(lds + PG8_SA(b, h) + aoff + m * 2048 + k * 1024); } while (0)
; #define PG8_LDB(dst, b, h) do { _Pragma("unroll") for (int n = 0; n < 2; ++n) _Pragma("unroll") for (int k = 0; k < 2; ++k) dst[n][k] = *(const LAS bf16x8*)(lds + PG8_SB(b, h) + boff + n * 2048 + k * 1024); } while (0)
; #define PG8_MMA(ai, bj, At, Bt) do { __builtin_amdgcn_s_setprio(1); _Pragma("unroll") for (int m = 0; m < 4; ++m) _Pragma("unroll") for (int n = 0; n < 2; ++n) _Pragma("unroll") for (int k = 0; k < 2; ++k) \
;         acc[ai][bj][m][n] = __builtin_amdgcn_mfma_f32_16x16x32_bf16(Bt[n][k], At[m][k], acc[ai][bj][m][n], 0, 0, 0); __builtin_amdgcn_s_setprio(0); } while (0)
; #define PG8_WAIT_V(n) asm volatile("s_waitcnt vmcnt(" #n ")" ::: "memory")
; #define PG8_WAIT_L(n) asm volatile("s_waitcnt lgkmcnt(" #n ")" ::: "memory")
; #define PG8_BAR __builtin_amdgcn_s_barrier()
; #define PG8_SCHED __builtin_amdgcn_sched_barrier(0)
; template <class Epi>
; __device__ __forceinline__ void gemm_phase(LAS unsigned char* lds, const Gemm g, const StaticOrder& S, const Epi& E) {
;     ...
;             PG8_WAIT_V(6); PG8_BAR; PG8_MMA(1, 1, At, B1); PG8_BAR;
;             PG8_LDB(B0, 1, 0); PG8_SCHED; PG8_LDA(At, 1, 0); PG8_STAGE(PG8_SA(0, 1), a2 + hA, voffA);
;             PG8_WAIT_L(8); PG8_BAR; PG8_WAIT_L(0); PG8_MMA(0, 0, At, B0); PG8_BAR; PG8_SCHED;
;             PG8_LDB(B1, 1, 1); PG8_STAGE(PG8_SB(1, 0), b3, voffB);
;             PG8_BAR; PG8_WAIT_L(0); PG8_MMA(0, 1, At, B1); PG8_BAR;
;             PG8_LDA(At, 1, 1); PG8_STAGE(PG8_SA(1, 0), a3, voffA);
;             PG8_BAR; PG8_WAIT_L(0); PG8_MMA(1, 0, At, B0); PG8_BAR; PG8_SCHED;
	s_setprio 1
	v_mfma_f32_16x16x32_bf16 v[58:61], v[210:213], v[172:175], v[58:61]
	v_mfma_f32_16x16x32_bf16 v[50:53], v[218:221], v[172:175], v[50:53]
	v_mfma_f32_16x16x32_bf16 v[42:45], v[210:213], v[180:183], v[42:45]
	v_mfma_f32_16x16x32_bf16 v[34:37], v[218:221], v[180:183], v[34:37]
	v_mfma_f32_16x16x32_bf16 v[26:29], v[210:213], v[188:191], v[26:29]
	v_mfma_f32_16x16x32_bf16 v[18:21], v[218:221], v[188:191], v[18:21]
	v_mfma_f32_16x16x32_bf16 v[10:13], v[210:213], v[202:205], v[10:13]
	v_mfma_f32_16x16x32_bf16 v[2:5], v[218:221], v[202:205], v[2:5]
	v_mfma_f32_16x16x32_bf16 v[58:61], v[214:217], v[176:179], v[58:61]
	v_mfma_f32_16x16x32_bf16 v[50:53], v[222:225], v[176:179], v[50:53]
	v_mfma_f32_16x16x32_bf16 v[42:45], v[214:217], v[184:187], v[42:45]
	v_mfma_f32_16x16x32_bf16 v[34:37], v[222:225], v[184:187], v[34:37]
	v_mfma_f32_16x16x32_bf16 v[26:29], v[214:217], v[192:195], v[26:29]
	v_mfma_f32_16x16x32_bf16 v[18:21], v[222:225], v[192:195], v[18:21]
	v_mfma_f32_16x16x32_bf16 v[10:13], v[214:217], v[206:209], v[10:13]
	v_mfma_f32_16x16x32_bf16 v[2:5], v[222:225], v[206:209], v[2:5]
	s_setprio 0
	s_add_i32 s75, 0, 0x18000
	v_add_u32_e32 v151, s75, v147
	s_barrier
	ds_read_b128 v[156:159], v151
	ds_read_b128 v[160:163], v151 offset:1024
	ds_read_b128 v[164:167], v151 offset:2048
	ds_read_b128 v[168:171], v151 offset:3072
	s_add_u32 s22, s66, 0x40000
	s_addc_u32 s23, s67, 0
	s_mov_b32 m0, s53
	ds_read_b128 v[172:175], v149 offset:32768
	ds_read_b128 v[176:179], v149 offset:33792
	ds_read_b128 v[180:183], v149 offset:34816
	ds_read_b128 v[184:187], v149 offset:35840
	ds_read_b128 v[188:191], v149 offset:36864
	ds_read_b128 v[192:195], v149 offset:37888
	ds_read_b128 v[202:205], v149 offset:38912
	ds_read_b128 v[206:209], v149 offset:39936
	global_load_lds_dwordx4 v130, s[22:23]
	s_mov_b32 m0, s54
	s_nop 0
	global_load_lds_dwordx4 v132, s[22:23]
	s_waitcnt lgkmcnt(8)
	s_barrier
	s_waitcnt lgkmcnt(0)
	s_setprio 1
	s_waitcnt lgkmcnt(0)
	v_mfma_f32_16x16x32_bf16 v[126:129], v[156:159], v[172:175], v[126:129]
	v_mfma_f32_16x16x32_bf16 v[118:121], v[164:167], v[172:175], v[118:121]
	v_mfma_f32_16x16x32_bf16 v[110:113], v[156:159], v[180:183], v[110:113]
	v_mfma_f32_16x16x32_bf16 v[102:105], v[164:167], v[180:183], v[102:105]
	v_mfma_f32_16x16x32_bf16 v[94:97], v[156:159], v[188:191], v[94:97]
	v_mfma_f32_16x16x32_bf16 v[86:89], v[164:167], v[188:191], v[86:89]
	v_mfma_f32_16x16x32_bf16 v[78:81], v[156:159], v[202:205], v[78:81]
	v_mfma_f32_16x16x32_bf16 v[70:73], v[164:167], v[202:205], v[70:73]
	v_mfma_f32_16x16x32_bf16 v[126:129], v[160:163], v[176:179], v[126:129]
	v_mfma_f32_16x16x32_bf16 v[118:121], v[168:171], v[176:179], v[118:121]
	v_mfma_f32_16x16x32_bf16 v[110:113], v[160:163], v[184:187], v[110:113]
	v_mfma_f32_16x16x32_bf16 v[102:105], v[168:171], v[184:187], v[102:105]
	v_mfma_f32_16x16x32_bf16 v[94:97], v[160:163], v[192:195], v[94:97]
	v_mfma_f32_16x16x32_bf16 v[86:89], v[168:171], v[192:195], v[86:89]
	v_mfma_f32_16x16x32_bf16 v[78:81], v[160:163], v[206:209], v[78:81]
	v_mfma_f32_16x16x32_bf16 v[70:73], v[168:171], v[206:209], v[70:73]
	s_setprio 0
	s_barrier
	s_add_i32 s22, s75, s48
	v_add_u32_e32 v151, 0x1c000, v147
	s_add_u32 s100, s64, 0x80
	s_addc_u32 s101, s65, 0
	s_mov_b32 m0, s22
	ds_read_b128 v[210:213], v151
	ds_read_b128 v[214:217], v151 offset:1024
	ds_read_b128 v[218:221], v151 offset:2048
	ds_read_b128 v[222:225], v151 offset:3072
	global_load_lds_dwordx4 v0, s[100:101]
	s_add_i32 m0, s22, 0x2000
	s_nop 0
	global_load_lds_dwordx4 v134, s[100:101]
	s_barrier
	s_waitcnt lgkmcnt(0)
	s_setprio 1
	s_waitcnt lgkmcnt(0)
	v_mfma_f32_16x16x32_bf16 v[122:125], v[210:213], v[172:175], v[122:125]
	v_mfma_f32_16x16x32_bf16 v[114:117], v[218:221], v[172:175], v[114:117]
	v_mfma_f32_16x16x32_bf16 v[106:109], v[210:213], v[180:183], v[106:109]
	v_mfma_f32_16x16x32_bf16 v[98:101], v[218:221], v[180:183], v[98:101]
	v_mfma_f32_16x16x32_bf16 v[90:93], v[210:213], v[188:191], v[90:93]
	v_mfma_f32_16x16x32_bf16 v[82:85], v[218:221], v[188:191], v[82:85]
	v_mfma_f32_16x16x32_bf16 v[74:77], v[210:213], v[202:205], v[74:77]
	v_mfma_f32_16x16x32_bf16 v[66:69], v[218:221], v[202:205], v[66:69]
	v_mfma_f32_16x16x32_bf16 v[122:125], v[214:217], v[176:179], v[122:125]
	v_mfma_f32_16x16x32_bf16 v[114:117], v[222:225], v[176:179], v[114:117]
	v_mfma_f32_16x16x32_bf16 v[106:109], v[214:217], v[184:187], v[106:109]
	v_mfma_f32_16x16x32_bf16 v[98:101], v[222:225], v[184:187], v[98:101]
	v_mfma_f32_16x16x32_bf16 v[90:93], v[214:217], v[192:195], v[90:93]
	v_mfma_f32_16x16x32_bf16 v[82:85], v[222:225], v[192:195], v[82:85]
	v_mfma_f32_16x16x32_bf16 v[74:77], v[214:217], v[206:209], v[74:77]
	v_mfma_f32_16x16x32_bf16 v[66:69], v[222:225], v[206:209], v[66:69]
	s_setprio 0
	s_mov_b32 m0, s56
	s_add_u32 s100, s66, 0x80
	s_addc_u32 s101, s67, 0
	s_barrier
	ds_read_b128 v[172:175], v149 offset:49152
	ds_read_b128 v[176:179], v149 offset:50176
	ds_read_b128 v[180:183], v149 offset:51200
	ds_read_b128 v[184:187], v149 offset:52224
	ds_read_b128 v[188:191], v149 offset:53248
	ds_read_b128 v[192:195], v149 offset:54272
	ds_read_b128 v[202:205], v149 offset:55296
	ds_read_b128 v[206:209], v149 offset:56320
	global_load_lds_dwordx4 v130, s[100:101]
	s_mov_b32 m0, s57
	s_nop 0
	global_load_lds_dwordx4 v132, s[100:101]
	s_barrier
; __device__ __forceinline__ float siluf_(float x) { return x * sigmoidf_(x); }
; #define PG8_STAGE(bufoff, gbase, voff) do { _Pragma("unroll") for (int _i = 0; _i < 2; ++_i) \
;         __builtin_amdgcn_global_load_lds((const unsigned*)((const char*)(gbase) + (voff)[_i]), (LAS unsigned*)(lds + (bufoff) + ldsw + _i * 8192), 16, 0, 0); } while (0)
; #define PG8_MMA(ai, bj, At, Bt) do { __builtin_amdgcn_s_setprio(1); _Pragma("unroll") for (int m = 0; m < 4; ++m) _Pragma("unroll") for (int n = 0; n < 2; ++n) _Pragma("unroll") for (int k = 0; k < 2; ++k) \
;         acc[ai][bj][m][n] = __builtin_amdgcn_mfma_f32_16x16x32_bf16(Bt[n][k], At[m][k], acc[ai][bj][m][n], 0, 0, 0); __builtin_amdgcn_s_setprio(0); } while (0)
; #define PG8_WAIT_V(n) asm volatile("s_waitcnt vmcnt(" #n ")" ::: "memory")
; #define PG8_WAIT_L(n) asm volatile("s_waitcnt lgkmcnt(" #n ")" ::: "memory")
; #define PG8_BAR __builtin_amdgcn_s_barrier()
; #define PG8_SCHED __builtin_amdgcn_sched_barrier(0)
; template <class Epi>
; __device__ __forceinline__ void gemm_phase(LAS unsigned char* lds, const Gemm g, const StaticOrder& S, const Epi& E) {
;     ...
;             PG8_BAR; PG8_WAIT_L(0); PG8_MMA(1, 0, At, B0); PG8_BAR; PG8_SCHED;
;             PG8_STAGE(PG8_SB(1, 1), b3 + hB, voffB);
;             PG8_WAIT_V(6); PG8_BAR; PG8_MMA(1, 1, At, B1); PG8_BAR;
;         }
;         if constexpr (Epi::HAS_PRE) { E(acc, cur, wr, wc, fr, fq, pre); if (has_next) E.pre(pre, nxt, wr, fr); } else E(acc, cur, wr, wc, fr, fq);
;         if (!has_next) break;
;     __device__ __forceinline__ void operator()(const Acc& acc, const Unit& u, int wr, int wc, int fr, int fq, const RsPre& pr) const {
;         asm volatile("" : "+v"(fr), "+v"(fq));
;         const int row0 = u.pm * 256 + wr * 64 + fr, col0 = u.pn * 128 + wc * 32 + 8 * fq;
;         const float (&rs)[2][4] = pr.rs;
; #pragma unroll
;         for (int ai = 0; ai < 2; ++ai)
; #pragma unroll
;             for (int m = 0; m < 4; ++m) { f32x4 o[2];
; #pragma unroll
;                 for (int n = 0; n < 2; ++n) { const f32x4 a1 = acc[ai][0][m][n] * rs[ai][m], a3 = acc[ai][1][m][n] * rs[ai][m];
;                     o[n] = (f32x4){siluf_(a1[0]) * a3[0], siluf_(a1[1]) * a3[1], siluf_(a1[2]) * a3[2], siluf_(a1[3]) * a3[3]}; }
	s_waitcnt lgkmcnt(0)
	s_setprio 1
	s_waitcnt lgkmcnt(0)
	v_mfma_f32_16x16x32_bf16 v[62:65], v[156:159], v[172:175], v[62:65]
	v_mfma_f32_16x16x32_bf16 v[54:57], v[164:167], v[172:175], v[54:57]
	v_mfma_f32_16x16x32_bf16 v[46:49], v[156:159], v[180:183], v[46:49]
	v_mfma_f32_16x16x32_bf16 v[38:41], v[164:167], v[180:183], v[38:41]
	v_mfma_f32_16x16x32_bf16 v[30:33], v[156:159], v[188:191], v[30:33]
	v_mfma_f32_16x16x32_bf16 v[22:25], v[164:167], v[188:191], v[22:25]
	v_mfma_f32_16x16x32_bf16 v[14:17], v[156:159], v[202:205], v[14:17]
	v_mfma_f32_16x16x32_bf16 v[6:9], v[164:167], v[202:205], v[6:9]
	v_mfma_f32_16x16x32_bf16 v[62:65], v[160:163], v[176:179], v[62:65]
	v_mfma_f32_16x16x32_bf16 v[54:57], v[168:171], v[176:179], v[54:57]
	v_mfma_f32_16x16x32_bf16 v[46:49], v[160:163], v[184:187], v[46:49]
	v_mfma_f32_16x16x32_bf16 v[38:41], v[168:171], v[184:187], v[38:41]
	v_mfma_f32_16x16x32_bf16 v[30:33], v[160:163], v[192:195], v[30:33]
	v_mfma_f32_16x16x32_bf16 v[22:25], v[168:171], v[192:195], v[22:25]
	v_mfma_f32_16x16x32_bf16 v[14:17], v[160:163], v[206:209], v[14:17]
	v_mfma_f32_16x16x32_bf16 v[6:9], v[168:171], v[206:209], v[6:9]
	s_setprio 0
	s_barrier
	s_add_u32 s22, s64, 0x40080
	s_addc_u32 s23, s65, 0
	s_add_i32 s64, s48, 0x1c000
	s_mov_b32 m0, s64
	s_nop 0
	global_load_lds_dwordx4 v0, s[22:23]
	s_add_i32 m0, s64, 0x2000
	s_nop 0
	global_load_lds_dwordx4 v134, s[22:23]
	s_waitcnt vmcnt(6)
	s_barrier
	s_setprio 1
	v_mfma_f32_16x16x32_bf16 v[58:61], v[210:213], v[172:175], v[58:61]
	v_mfma_f32_16x16x32_bf16 v[50:53], v[218:221], v[172:175], v[50:53]
	v_mfma_f32_16x16x32_bf16 v[42:45], v[210:213], v[180:183], v[42:45]
	v_mfma_f32_16x16x32_bf16 v[34:37], v[218:221], v[180:183], v[34:37]
	v_mfma_f32_16x16x32_bf16 v[26:29], v[210:213], v[188:191], v[26:29]
	v_mfma_f32_16x16x32_bf16 v[18:21], v[218:221], v[188:191], v[18:21]
	v_mfma_f32_16x16x32_bf16 v[10:13], v[210:213], v[202:205], v[10:13]
	v_mfma_f32_16x16x32_bf16 v[2:5], v[218:221], v[202:205], v[2:5]
	v_mfma_f32_16x16x32_bf16 v[58:61], v[214:217], v[176:179], v[58:61]
	v_mfma_f32_16x16x32_bf16 v[50:53], v[222:225], v[176:179], v[50:53]
	v_mfma_f32_16x16x32_bf16 v[42:45], v[214:217], v[184:187], v[42:45]
	v_mfma_f32_16x16x32_bf16 v[34:37], v[222:225], v[184:187], v[34:37]
	v_mfma_f32_16x16x32_bf16 v[26:29], v[214:217], v[192:195], v[26:29]
	v_mfma_f32_16x16x32_bf16 v[18:21], v[222:225], v[192:195], v[18:21]
	v_mfma_f32_16x16x32_bf16 v[10:13], v[214:217], v[206:209], v[10:13]
	v_mfma_f32_16x16x32_bf16 v[2:5], v[222:225], v[206:209], v[2:5]
	s_setprio 0
	s_add_i32 s74, s74, 2
	s_add_u32 s62, s62, 0x100
	s_addc_u32 s63, s63, 0
	s_add_u32 s70, s70, 0x100
	s_addc_u32 s71, s71, 0
	s_cmp_gt_u32 s74, 13
	s_barrier
	s_cbranch_scc0 .LBB0_104
	v_mov_b32_e32 v151, v137
	v_mov_b32_e32 v153, v143
	s_lshl_b32 s22, s60, 8
	s_add_i32 s22, s22, s49
	v_add_u32_e32 v151, s22, v151
	s_lshl_b32 s22, s33, 7
	s_or_b32 s22, s22, s55
	s_waitcnt vmcnt(0)
	v_pk_mul_f32 v[126:127], v[154:155], v[126:127] op_sel_hi:[0,1]
	v_lshl_add_u32 v156, v153, 3, s22
	v_mul_f32_e32 v153, 0xbfb8aa3b, v126
	v_exp_f32_e32 v153, v153
	v_pk_mul_f32 v[128:129], v[154:155], v[128:129] op_sel_hi:[0,1]
	v_pk_mul_f32 v[122:123], v[154:155], v[122:123] op_sel_hi:[0,1]
	v_pk_mul_f32 v[124:125], v[154:155], v[124:125] op_sel_hi:[0,1]
	v_add_f32_e32 v153, 1.0, v153
	v_rcp_f32_e32 v158, v153
	v_mul_f32_e32 v153, 0xbfb8aa3b, v127
	v_exp_f32_e32 v153, v153
	v_pk_mul_f32 v[118:119], v[154:155], v[118:119] op_sel_hi:[0,1]
	v_pk_mul_f32 v[120:121], v[154:155], v[120:121] op_sel_hi:[0,1]
	v_pk_mul_f32 v[114:115], v[154:155], v[114:115] op_sel_hi:[0,1]
	v_add_f32_e32 v153, 1.0, v153
	v_rcp_f32_e32 v159, v153
	v_pk_mul_f32 v[116:117], v[154:155], v[116:117] op_sel_hi:[0,1]
	s_movk_i32 s0, 0x1600
	v_pk_mul_f32 v[126:127], v[126:127], v[158:159]
	v_pk_mul_f32 v[110:111], v[152:153], v[110:111] op_sel_hi:[0,1]
	v_pk_mul_f32 v[122:123], v[126:127], v[122:123]
	v_mul_f32_e32 v126, 0xbfb8aa3b, v128
	v_mul_f32_e32 v127, 0xbfb8aa3b, v129
	v_exp_f32_e32 v126, v126
	v_exp_f32_e32 v127, v127
	v_pk_mul_f32 v[112:113], v[152:153], v[112:113] op_sel_hi:[0,1]
	v_pk_mul_f32 v[106:107], v[152:153], v[106:107] op_sel_hi:[0,1]
	v_add_f32_e32 v126, 1.0, v126
	v_add_f32_e32 v127, 1.0, v127
	v_rcp_f32_e32 v126, v126
	v_rcp_f32_e32 v127, v127
	v_pk_mul_f32 v[108:109], v[152:153], v[108:109] op_sel_hi:[0,1]
	v_pk_mul_f32 v[102:103], v[152:153], v[102:103] op_sel_hi:[0,1]
	v_pk_mul_f32 v[104:105], v[152:153], v[104:105] op_sel_hi:[0,1]
	v_pk_mul_f32 v[126:127], v[128:129], v[126:127]
	v_pk_mul_f32 v[98:99], v[152:153], v[98:99] op_sel_hi:[0,1]
	v_pk_mul_f32 v[124:125], v[126:127], v[124:125]
	v_mul_f32_e32 v126, 0xbfb8aa3b, v118
	v_mul_f32_e32 v127, 0xbfb8aa3b, v119
	v_exp_f32_e32 v126, v126
	v_exp_f32_e32 v127, v127
	v_pk_mul_f32 v[100:101], v[152:153], v[100:101] op_sel_hi:[0,1]
	v_pk_mul_f32 v[94:95], v[150:151], v[94:95] op_sel_hi:[0,1]
	v_add_f32_e32 v126, 1.0, v126
	v_add_f32_e32 v127, 1.0, v127
	v_rcp_f32_e32 v126, v126
	v_rcp_f32_e32 v127, v127
	v_pk_mul_f32 v[96:97], v[150:151], v[96:97] op_sel_hi:[0,1]
	v_pk_mul_f32 v[90:91], v[150:151], v[90:91] op_sel_hi:[0,1]
	v_pk_mul_f32 v[92:93], v[150:151], v[92:93] op_sel_hi:[0,1]
	v_pk_mul_f32 v[118:119], v[118:119], v[126:127]
	v_pk_mul_f32 v[86:87], v[150:151], v[86:87] op_sel_hi:[0,1]
	v_pk_mul_f32 v[114:115], v[118:119], v[114:115]
	v_mul_f32_e32 v118, 0xbfb8aa3b, v120
	v_mul_f32_e32 v119, 0xbfb8aa3b, v121
	v_exp_f32_e32 v118, v118
	v_exp_f32_e32 v119, v119
	v_pk_mul_f32 v[88:89], v[150:151], v[88:89] op_sel_hi:[0,1]
	v_pk_mul_f32 v[82:83], v[150:151], v[82:83] op_sel_hi:[0,1]
	v_add_f32_e32 v118, 1.0, v118
; __device__ __forceinline__ float siluf_(float x) { return x * sigmoidf_(x); }
; __device__ __forceinline__ u32x4 pack8(const f32x4 a, const f32x4 b) { u32x4 w; w.x = cvt_pk_bf16(a[0], a[1]); w.y = cvt_pk_bf16(a[2], a[3]); w.z = cvt_pk_bf16(b[0], b[1]); w.w = cvt_pk_bf16(b[2], b[3]); return w; }
;     __device__ __forceinline__ void operator()(const Acc& acc, const Unit& u, int wr, int wc, int fr, int fq, const RsPre& pr) const {
;         asm volatile("" : "+v"(fr), "+v"(fq));
;         const int row0 = u.pm * 256 + wr * 64 + fr, col0 = u.pn * 128 + wc * 32 + 8 * fq;
;         const float (&rs)[2][4] = pr.rs;
; #pragma unroll
;         for (int ai = 0; ai < 2; ++ai)
; #pragma unroll
;             for (int m = 0; m < 4; ++m) { f32x4 o[2];
; #pragma unroll
;                 for (int n = 0; n < 2; ++n) { const f32x4 a1 = acc[ai][0][m][n] * rs[ai][m], a3 = acc[ai][1][m][n] * rs[ai][m];
;                     o[n] = (f32x4){siluf_(a1[0]) * a3[0], siluf_(a1[1]) * a3[1], siluf_(a1[2]) * a3[2], siluf_(a1[3]) * a3[3]}; }
;                 *(u32x4*)(ff + (size_t)(row0 + ai * 128 + m * 16) * DFF + col0) = pack8(o[0], o[1]); }
	v_add_f32_e32 v119, 1.0, v119
	v_rcp_f32_e32 v118, v118
	v_rcp_f32_e32 v119, v119
	v_pk_mul_f32 v[84:85], v[150:151], v[84:85] op_sel_hi:[0,1]
	v_pk_mul_f32 v[78:79], v[148:149], v[78:79] op_sel_hi:[0,1]
	v_pk_mul_f32 v[80:81], v[148:149], v[80:81] op_sel_hi:[0,1]
	v_pk_mul_f32 v[118:119], v[120:121], v[118:119]
	v_cvt_pk_bf16_f32 v120, v114, v115
	v_pk_mul_f32 v[116:117], v[118:119], v[116:117]
	v_cvt_pk_bf16_f32 v118, v122, v123
	v_cvt_pk_bf16_f32 v121, v116, v117
	v_lshlrev_b32_e32 v116, 1, v156
	v_mad_u32_u24 v114, v151, s0, v116
	v_cvt_pk_bf16_f32 v119, v124, v125
	global_store_dwordx4 v114, v[118:121], s[20:21]
	v_pk_mul_f32 v[74:75], v[148:149], v[74:75] op_sel_hi:[0,1]
	v_pk_mul_f32 v[76:77], v[148:149], v[76:77] op_sel_hi:[0,1]
	v_mul_f32_e32 v118, 0xbfb8aa3b, v110
	v_mul_f32_e32 v119, 0xbfb8aa3b, v111
	v_exp_f32_e32 v118, v118
	v_exp_f32_e32 v119, v119
	v_pk_mul_f32 v[70:71], v[148:149], v[70:71] op_sel_hi:[0,1]
	v_pk_mul_f32 v[72:73], v[148:149], v[72:73] op_sel_hi:[0,1]
	v_add_f32_e32 v118, 1.0, v118
	v_add_f32_e32 v119, 1.0, v119
	v_rcp_f32_e32 v118, v118
	v_rcp_f32_e32 v119, v119
	v_pk_mul_f32 v[66:67], v[148:149], v[66:67] op_sel_hi:[0,1]
	v_pk_mul_f32 v[68:69], v[148:149], v[68:69] op_sel_hi:[0,1]
	v_pk_mul_f32 v[62:63], v[146:147], v[62:63] op_sel_hi:[0,1]
	v_pk_mul_f32 v[110:111], v[110:111], v[118:119]
	v_pk_mul_f32 v[64:65], v[146:147], v[64:65] op_sel_hi:[0,1]
	v_pk_mul_f32 v[106:107], v[110:111], v[106:107]
	v_mul_f32_e32 v110, 0xbfb8aa3b, v112
	v_mul_f32_e32 v111, 0xbfb8aa3b, v113
	v_exp_f32_e32 v110, v110
	v_exp_f32_e32 v111, v111
	v_pk_mul_f32 v[58:59], v[146:147], v[58:59] op_sel_hi:[0,1]
	v_pk_mul_f32 v[60:61], v[146:147], v[60:61] op_sel_hi:[0,1]
	v_add_f32_e32 v110, 1.0, v110
	v_add_f32_e32 v111, 1.0, v111
	v_rcp_f32_e32 v110, v110
	v_rcp_f32_e32 v111, v111
	v_pk_mul_f32 v[54:55], v[146:147], v[54:55] op_sel_hi:[0,1]
	v_pk_mul_f32 v[56:57], v[146:147], v[56:57] op_sel_hi:[0,1]
	v_pk_mul_f32 v[50:51], v[146:147], v[50:51] op_sel_hi:[0,1]
	v_pk_mul_f32 v[110:111], v[112:113], v[110:111]
	v_pk_mul_f32 v[52:53], v[146:147], v[52:53] op_sel_hi:[0,1]
	v_pk_mul_f32 v[108:109], v[110:111], v[108:109]
	v_mul_f32_e32 v110, 0xbfb8aa3b, v102
	v_mul_f32_e32 v111, 0xbfb8aa3b, v103
	v_exp_f32_e32 v110, v110
	v_exp_f32_e32 v111, v111
	v_pk_mul_f32 v[46:47], v[144:145], v[46:47] op_sel_hi:[0,1]
	v_pk_mul_f32 v[48:49], v[144:145], v[48:49] op_sel_hi:[0,1]
	v_add_f32_e32 v110, 1.0, v110
	v_add_f32_e32 v111, 1.0, v111
	v_rcp_f32_e32 v110, v110
	v_rcp_f32_e32 v111, v111
	v_pk_mul_f32 v[42:43], v[144:145], v[42:43] op_sel_hi:[0,1]
	v_pk_mul_f32 v[44:45], v[144:145], v[44:45] op_sel_hi:[0,1]
	v_pk_mul_f32 v[38:39], v[144:145], v[38:39] op_sel_hi:[0,1]
	v_pk_mul_f32 v[102:103], v[102:103], v[110:111]
	v_pk_mul_f32 v[40:41], v[144:145], v[40:41] op_sel_hi:[0,1]
	v_pk_mul_f32 v[102:103], v[102:103], v[98:99]
	v_mul_f32_e32 v98, 0xbfb8aa3b, v104
	v_mul_f32_e32 v99, 0xbfb8aa3b, v105
	v_exp_f32_e32 v98, v98
	v_exp_f32_e32 v99, v99
	v_pk_mul_f32 v[34:35], v[144:145], v[34:35] op_sel_hi:[0,1]
	v_pk_mul_f32 v[36:37], v[144:145], v[36:37] op_sel_hi:[0,1]
	v_add_f32_e32 v98, 1.0, v98
	v_add_f32_e32 v99, 1.0, v99
	v_rcp_f32_e32 v98, v98
	v_rcp_f32_e32 v99, v99
	v_pk_mul_f32 v[30:31], v[142:143], v[30:31] op_sel_hi:[0,1]
	v_pk_mul_f32 v[32:33], v[142:143], v[32:33] op_sel_hi:[0,1]
	v_pk_mul_f32 v[26:27], v[142:143], v[26:27] op_sel_hi:[0,1]
	v_pk_mul_f32 v[98:99], v[104:105], v[98:99]
	v_pk_mul_f32 v[28:29], v[142:143], v[28:29] op_sel_hi:[0,1]
	v_pk_mul_f32 v[104:105], v[98:99], v[100:101]
	v_cvt_pk_bf16_f32 v100, v102, v103
	v_cvt_pk_bf16_f32 v98, v106, v107
	v_cvt_pk_bf16_f32 v99, v108, v109
	v_cvt_pk_bf16_f32 v101, v104, v105
	v_add_u32_e32 v102, 0x16000, v114
	global_store_dwordx4 v102, v[98:101], s[20:21]
	v_pk_mul_f32 v[22:23], v[142:143], v[22:23] op_sel_hi:[0,1]
	v_pk_mul_f32 v[24:25], v[142:143], v[24:25] op_sel_hi:[0,1]
	v_mul_f32_e32 v98, 0xbfb8aa3b, v94
	v_mul_f32_e32 v99, 0xbfb8aa3b, v95
	v_exp_f32_e32 v98, v98
	v_exp_f32_e32 v99, v99
	v_pk_mul_f32 v[18:19], v[142:143], v[18:19] op_sel_hi:[0,1]
	v_pk_mul_f32 v[20:21], v[142:143], v[20:21] op_sel_hi:[0,1]
	v_add_f32_e32 v98, 1.0, v98
	v_add_f32_e32 v99, 1.0, v99
	v_rcp_f32_e32 v98, v98
	v_rcp_f32_e32 v99, v99
	v_pk_mul_f32 v[14:15], v[136:137], v[14:15] op_sel_hi:[0,1]
	v_pk_mul_f32 v[16:17], v[136:137], v[16:17] op_sel_hi:[0,1]
	v_pk_mul_f32 v[10:11], v[136:137], v[10:11] op_sel_hi:[0,1]
	v_pk_mul_f32 v[94:95], v[94:95], v[98:99]
	v_pk_mul_f32 v[12:13], v[136:137], v[12:13] op_sel_hi:[0,1]
	v_pk_mul_f32 v[90:91], v[94:95], v[90:91]
	v_mul_f32_e32 v94, 0xbfb8aa3b, v96
	v_mul_f32_e32 v95, 0xbfb8aa3b, v97
	v_exp_f32_e32 v94, v94
	v_exp_f32_e32 v95, v95
	v_pk_mul_f32 v[6:7], v[136:137], v[6:7] op_sel_hi:[0,1]
	v_pk_mul_f32 v[8:9], v[136:137], v[8:9] op_sel_hi:[0,1]
	v_add_f32_e32 v94, 1.0, v94
	v_add_f32_e32 v95, 1.0, v95
	v_rcp_f32_e32 v94, v94
	v_rcp_f32_e32 v95, v95
	v_pk_mul_f32 v[2:3], v[136:137], v[2:3] op_sel_hi:[0,1]
	v_pk_mul_f32 v[4:5], v[136:137], v[4:5] op_sel_hi:[0,1]
	s_mov_b64 s[60:61], -1
	v_pk_mul_f32 v[94:95], v[96:97], v[94:95]
	s_and_b64 vcc, vcc, exec
	v_pk_mul_f32 v[92:93], v[94:95], v[92:93]
	v_mul_f32_e32 v94, 0xbfb8aa3b, v86
	v_mul_f32_e32 v95, 0xbfb8aa3b, v87
	v_exp_f32_e32 v94, v94
	v_exp_f32_e32 v95, v95
	v_add_f32_e32 v94, 1.0, v94
	v_add_f32_e32 v95, 1.0, v95
	v_rcp_f32_e32 v94, v94
	v_rcp_f32_e32 v95, v95
	s_nop 0
	v_pk_mul_f32 v[86:87], v[86:87], v[94:95]
	s_nop 0
	v_pk_mul_f32 v[86:87], v[86:87], v[82:83]
	v_mul_f32_e32 v82, 0xbfb8aa3b, v88
	v_mul_f32_e32 v83, 0xbfb8aa3b, v89
	v_exp_f32_e32 v82, v82
	v_exp_f32_e32 v83, v83
	v_add_f32_e32 v82, 1.0, v82
; __device__ __forceinline__ float siluf_(float x) { return x * sigmoidf_(x); }
; __device__ __forceinline__ u32x4 pack8(const f32x4 a, const f32x4 b) { u32x4 w; w.x = cvt_pk_bf16(a[0], a[1]); w.y = cvt_pk_bf16(a[2], a[3]); w.z = cvt_pk_bf16(b[0], b[1]); w.w = cvt_pk_bf16(b[2], b[3]); return w; }
;     __device__ __forceinline__ void operator()(const Acc& acc, const Unit& u, int wr, int wc, int fr, int fq, const RsPre& pr) const {
;     ...
;             for (int m = 0; m < 4; ++m) { f32x4 o[2];
; #pragma unroll
;                 for (int n = 0; n < 2; ++n) { const f32x4 a1 = acc[ai][0][m][n] * rs[ai][m], a3 = acc[ai][1][m][n] * rs[ai][m];
;                     o[n] = (f32x4){siluf_(a1[0]) * a3[0], siluf_(a1[1]) * a3[1], siluf_(a1[2]) * a3[2], siluf_(a1[3]) * a3[3]}; }
;                 *(u32x4*)(ff + (size_t)(row0 + ai * 128 + m * 16) * DFF + col0) = pack8(o[0], o[1]); }
	v_add_f32_e32 v83, 1.0, v83
	v_rcp_f32_e32 v82, v82
	v_rcp_f32_e32 v83, v83
	s_nop 0
	v_pk_mul_f32 v[82:83], v[88:89], v[82:83]
	s_nop 0
	v_pk_mul_f32 v[88:89], v[82:83], v[84:85]
	v_cvt_pk_bf16_f32 v84, v86, v87
	v_cvt_pk_bf16_f32 v82, v90, v91
	v_cvt_pk_bf16_f32 v83, v92, v93
	v_cvt_pk_bf16_f32 v85, v88, v89
	v_add_u32_e32 v86, 0x2c000, v114
	global_store_dwordx4 v86, v[82:85], s[20:21]
	s_nop 1
	v_mul_f32_e32 v82, 0xbfb8aa3b, v78
	v_mul_f32_e32 v83, 0xbfb8aa3b, v79
	v_exp_f32_e32 v82, v82
	v_exp_f32_e32 v83, v83
	v_add_f32_e32 v82, 1.0, v82
	v_add_f32_e32 v83, 1.0, v83
	v_rcp_f32_e32 v82, v82
	v_rcp_f32_e32 v83, v83
	s_nop 0
	v_pk_mul_f32 v[78:79], v[78:79], v[82:83]
	s_nop 0
	v_pk_mul_f32 v[74:75], v[78:79], v[74:75]
	v_mul_f32_e32 v78, 0xbfb8aa3b, v80
	v_mul_f32_e32 v79, 0xbfb8aa3b, v81
	v_exp_f32_e32 v78, v78
	v_exp_f32_e32 v79, v79
	v_add_f32_e32 v78, 1.0, v78
	v_add_f32_e32 v79, 1.0, v79
	v_rcp_f32_e32 v78, v78
	v_rcp_f32_e32 v79, v79
	s_nop 0
	v_pk_mul_f32 v[78:79], v[80:81], v[78:79]
	s_nop 0
	v_pk_mul_f32 v[76:77], v[78:79], v[76:77]
	v_mul_f32_e32 v78, 0xbfb8aa3b, v70
	v_mul_f32_e32 v79, 0xbfb8aa3b, v71
	v_exp_f32_e32 v78, v78
	v_exp_f32_e32 v79, v79
	v_add_f32_e32 v78, 1.0, v78
	v_add_f32_e32 v79, 1.0, v79
	v_rcp_f32_e32 v78, v78
	v_rcp_f32_e32 v79, v79
	s_nop 0
	v_pk_mul_f32 v[70:71], v[70:71], v[78:79]
	s_nop 0
	v_pk_mul_f32 v[70:71], v[70:71], v[66:67]
	v_mul_f32_e32 v66, 0xbfb8aa3b, v72
	v_mul_f32_e32 v67, 0xbfb8aa3b, v73
	v_exp_f32_e32 v66, v66
	v_exp_f32_e32 v67, v67
	v_add_f32_e32 v66, 1.0, v66
	v_add_f32_e32 v67, 1.0, v67
	v_rcp_f32_e32 v66, v66
	v_rcp_f32_e32 v67, v67
	s_nop 0
	v_pk_mul_f32 v[66:67], v[72:73], v[66:67]
	s_nop 0
	v_pk_mul_f32 v[72:73], v[66:67], v[68:69]
	v_cvt_pk_bf16_f32 v68, v70, v71
	v_cvt_pk_bf16_f32 v66, v74, v75
	v_cvt_pk_bf16_f32 v67, v76, v77
	v_cvt_pk_bf16_f32 v69, v72, v73
	v_add_u32_e32 v70, 0x42000, v114
	global_store_dwordx4 v70, v[66:69], s[20:21]
	s_nop 1
	v_mul_f32_e32 v66, 0xbfb8aa3b, v62
	v_mul_f32_e32 v67, 0xbfb8aa3b, v63
	v_exp_f32_e32 v66, v66
	v_exp_f32_e32 v67, v67
	v_add_f32_e32 v66, 1.0, v66
	v_add_f32_e32 v67, 1.0, v67
	v_rcp_f32_e32 v66, v66
	v_rcp_f32_e32 v67, v67
	s_nop 0
	v_pk_mul_f32 v[62:63], v[62:63], v[66:67]
	s_nop 0
	v_pk_mul_f32 v[58:59], v[62:63], v[58:59]
	v_mul_f32_e32 v62, 0xbfb8aa3b, v64
	v_mul_f32_e32 v63, 0xbfb8aa3b, v65
	v_exp_f32_e32 v62, v62
	v_exp_f32_e32 v63, v63
	v_add_f32_e32 v62, 1.0, v62
	v_add_f32_e32 v63, 1.0, v63
	v_rcp_f32_e32 v62, v62
	v_rcp_f32_e32 v63, v63
	s_nop 0
	v_pk_mul_f32 v[62:63], v[64:65], v[62:63]
	s_nop 0
	v_pk_mul_f32 v[60:61], v[62:63], v[60:61]
	v_mul_f32_e32 v62, 0xbfb8aa3b, v54
	v_mul_f32_e32 v63, 0xbfb8aa3b, v55
	v_exp_f32_e32 v62, v62
	v_exp_f32_e32 v63, v63
	v_add_f32_e32 v62, 1.0, v62
	v_add_f32_e32 v63, 1.0, v63
	v_rcp_f32_e32 v62, v62
	v_rcp_f32_e32 v63, v63
	s_nop 0
	v_pk_mul_f32 v[54:55], v[54:55], v[62:63]
	s_nop 0
	v_pk_mul_f32 v[54:55], v[54:55], v[50:51]
	v_mul_f32_e32 v50, 0xbfb8aa3b, v56
	v_mul_f32_e32 v51, 0xbfb8aa3b, v57
	v_exp_f32_e32 v50, v50
	v_exp_f32_e32 v51, v51
	v_add_f32_e32 v50, 1.0, v50
	v_add_f32_e32 v51, 1.0, v51
	v_rcp_f32_e32 v50, v50
	v_rcp_f32_e32 v51, v51
	s_nop 0
	v_pk_mul_f32 v[50:51], v[56:57], v[50:51]
	s_nop 0
	v_pk_mul_f32 v[56:57], v[50:51], v[52:53]
	v_cvt_pk_bf16_f32 v52, v54, v55
	v_cvt_pk_bf16_f32 v50, v58, v59
	v_cvt_pk_bf16_f32 v51, v60, v61
	v_cvt_pk_bf16_f32 v53, v56, v57
	v_add_u32_e32 v54, 0xb0000, v114
	global_store_dwordx4 v54, v[50:53], s[20:21]
	s_nop 1
	v_mul_f32_e32 v50, 0xbfb8aa3b, v46
	v_mul_f32_e32 v51, 0xbfb8aa3b, v47
	v_exp_f32_e32 v50, v50
	v_exp_f32_e32 v51, v51
	v_add_f32_e32 v50, 1.0, v50
	v_add_f32_e32 v51, 1.0, v51
	v_rcp_f32_e32 v50, v50
	v_rcp_f32_e32 v51, v51
	s_nop 0
	v_pk_mul_f32 v[46:47], v[46:47], v[50:51]
	s_nop 0
	v_pk_mul_f32 v[42:43], v[46:47], v[42:43]
	v_mul_f32_e32 v46, 0xbfb8aa3b, v48
	v_mul_f32_e32 v47, 0xbfb8aa3b, v49
	v_exp_f32_e32 v46, v46
	v_exp_f32_e32 v47, v47
	v_add_f32_e32 v46, 1.0, v46
	v_add_f32_e32 v47, 1.0, v47
	v_rcp_f32_e32 v46, v46
	v_rcp_f32_e32 v47, v47
	s_nop 0
	v_pk_mul_f32 v[46:47], v[48:49], v[46:47]
	s_nop 0
	v_pk_mul_f32 v[44:45], v[46:47], v[44:45]
	v_mul_f32_e32 v46, 0xbfb8aa3b, v38
	v_mul_f32_e32 v47, 0xbfb8aa3b, v39
	v_exp_f32_e32 v46, v46
	v_exp_f32_e32 v47, v47
	v_add_f32_e32 v46, 1.0, v46
; __device__ __forceinline__ float siluf_(float x) { return x * sigmoidf_(x); }
; __device__ __forceinline__ u32x4 pack8(const f32x4 a, const f32x4 b) { u32x4 w; w.x = cvt_pk_bf16(a[0], a[1]); w.y = cvt_pk_bf16(a[2], a[3]); w.z = cvt_pk_bf16(b[0], b[1]); w.w = cvt_pk_bf16(b[2], b[3]); return w; }
;     __device__ __forceinline__ void pre(RsPre& r, const Unit& u, int wr, int fr) const {
; #pragma unroll
;         for (int ai = 0; ai < 2; ++ai)
; #pragma unroll
;             for (int m = 0; m < 4; ++m) r.rs[ai][m] = rsv[u.pm * 256 + wr * 64 + fr + ai * 128 + m * 16]; }
;     __device__ __forceinline__ void operator()(const Acc& acc, const Unit& u, int wr, int wc, int fr, int fq, const RsPre& pr) const {
;     ...
;             for (int m = 0; m < 4; ++m) { f32x4 o[2];
; #pragma unroll
;                 for (int n = 0; n < 2; ++n) { const f32x4 a1 = acc[ai][0][m][n] * rs[ai][m], a3 = acc[ai][1][m][n] * rs[ai][m];
;                     o[n] = (f32x4){siluf_(a1[0]) * a3[0], siluf_(a1[1]) * a3[1], siluf_(a1[2]) * a3[2], siluf_(a1[3]) * a3[3]}; }
;                 *(u32x4*)(ff + (size_t)(row0 + ai * 128 + m * 16) * DFF + col0) = pack8(o[0], o[1]); }
	v_add_f32_e32 v47, 1.0, v47
	v_rcp_f32_e32 v46, v46
	v_rcp_f32_e32 v47, v47
	s_nop 0
	v_pk_mul_f32 v[38:39], v[38:39], v[46:47]
	s_nop 0
	v_pk_mul_f32 v[38:39], v[38:39], v[34:35]
	v_mul_f32_e32 v34, 0xbfb8aa3b, v40
	v_mul_f32_e32 v35, 0xbfb8aa3b, v41
	v_exp_f32_e32 v34, v34
	v_exp_f32_e32 v35, v35
	v_add_f32_e32 v34, 1.0, v34
	v_add_f32_e32 v35, 1.0, v35
	v_rcp_f32_e32 v34, v34
	v_rcp_f32_e32 v35, v35
	s_nop 0
	v_pk_mul_f32 v[34:35], v[40:41], v[34:35]
	s_nop 0
	v_pk_mul_f32 v[40:41], v[34:35], v[36:37]
	v_cvt_pk_bf16_f32 v36, v38, v39
	v_cvt_pk_bf16_f32 v34, v42, v43
	v_cvt_pk_bf16_f32 v35, v44, v45
	v_cvt_pk_bf16_f32 v37, v40, v41
	v_add_u32_e32 v38, 0xc6000, v114
	global_store_dwordx4 v38, v[34:37], s[20:21]
	s_nop 1
	v_mul_f32_e32 v34, 0xbfb8aa3b, v30
	v_mul_f32_e32 v35, 0xbfb8aa3b, v31
	v_exp_f32_e32 v34, v34
	v_exp_f32_e32 v35, v35
	v_add_f32_e32 v34, 1.0, v34
	v_add_f32_e32 v35, 1.0, v35
	v_rcp_f32_e32 v34, v34
	v_rcp_f32_e32 v35, v35
	s_nop 0
	v_pk_mul_f32 v[30:31], v[30:31], v[34:35]
	s_nop 0
	v_pk_mul_f32 v[26:27], v[30:31], v[26:27]
	v_mul_f32_e32 v30, 0xbfb8aa3b, v32
	v_mul_f32_e32 v31, 0xbfb8aa3b, v33
	v_exp_f32_e32 v30, v30
	v_exp_f32_e32 v31, v31
	v_add_f32_e32 v30, 1.0, v30
	v_add_f32_e32 v31, 1.0, v31
	v_rcp_f32_e32 v30, v30
	v_rcp_f32_e32 v31, v31
	s_nop 0
	v_pk_mul_f32 v[30:31], v[32:33], v[30:31]
	s_nop 0
	v_pk_mul_f32 v[28:29], v[30:31], v[28:29]
	v_mul_f32_e32 v30, 0xbfb8aa3b, v22
	v_mul_f32_e32 v31, 0xbfb8aa3b, v23
	v_exp_f32_e32 v30, v30
	v_exp_f32_e32 v31, v31
	v_add_f32_e32 v30, 1.0, v30
	v_add_f32_e32 v31, 1.0, v31
	v_rcp_f32_e32 v30, v30
	v_rcp_f32_e32 v31, v31
	s_nop 0
	v_pk_mul_f32 v[22:23], v[22:23], v[30:31]
	s_nop 0
	v_pk_mul_f32 v[22:23], v[22:23], v[18:19]
	v_mul_f32_e32 v18, 0xbfb8aa3b, v24
	v_mul_f32_e32 v19, 0xbfb8aa3b, v25
	v_exp_f32_e32 v18, v18
	v_exp_f32_e32 v19, v19
	v_add_f32_e32 v18, 1.0, v18
	v_add_f32_e32 v19, 1.0, v19
	v_rcp_f32_e32 v18, v18
	v_rcp_f32_e32 v19, v19
	s_nop 0
	v_pk_mul_f32 v[18:19], v[24:25], v[18:19]
	s_nop 0
	v_pk_mul_f32 v[24:25], v[18:19], v[20:21]
	v_cvt_pk_bf16_f32 v20, v22, v23
	v_cvt_pk_bf16_f32 v18, v26, v27
	v_cvt_pk_bf16_f32 v19, v28, v29
	v_cvt_pk_bf16_f32 v21, v24, v25
	v_add_u32_e32 v22, 0xdc000, v114
	global_store_dwordx4 v22, v[18:21], s[20:21]
	s_nop 1
	v_mul_f32_e32 v18, 0xbfb8aa3b, v14
	v_mul_f32_e32 v19, 0xbfb8aa3b, v15
	v_exp_f32_e32 v18, v18
	v_exp_f32_e32 v19, v19
	v_add_f32_e32 v18, 1.0, v18
	v_add_f32_e32 v19, 1.0, v19
	v_rcp_f32_e32 v18, v18
	v_rcp_f32_e32 v19, v19
	s_nop 0
	v_pk_mul_f32 v[14:15], v[14:15], v[18:19]
	s_nop 0
	v_pk_mul_f32 v[10:11], v[14:15], v[10:11]
	v_mul_f32_e32 v14, 0xbfb8aa3b, v16
	v_mul_f32_e32 v15, 0xbfb8aa3b, v17
	v_exp_f32_e32 v14, v14
	v_exp_f32_e32 v15, v15
	v_add_f32_e32 v14, 1.0, v14
	v_add_f32_e32 v15, 1.0, v15
	v_rcp_f32_e32 v14, v14
	v_rcp_f32_e32 v15, v15
	s_nop 0
	v_pk_mul_f32 v[14:15], v[16:17], v[14:15]
	s_nop 0
	v_pk_mul_f32 v[12:13], v[14:15], v[12:13]
	v_mul_f32_e32 v14, 0xbfb8aa3b, v6
	v_mul_f32_e32 v15, 0xbfb8aa3b, v7
	v_exp_f32_e32 v14, v14
	v_exp_f32_e32 v15, v15
	v_add_f32_e32 v14, 1.0, v14
	v_add_f32_e32 v15, 1.0, v15
	v_rcp_f32_e32 v14, v14
	v_rcp_f32_e32 v15, v15
	s_nop 0
	v_pk_mul_f32 v[6:7], v[6:7], v[14:15]
	s_nop 0
	v_pk_mul_f32 v[6:7], v[6:7], v[2:3]
	v_mul_f32_e32 v2, 0xbfb8aa3b, v8
	v_mul_f32_e32 v3, 0xbfb8aa3b, v9
	v_exp_f32_e32 v2, v2
	v_exp_f32_e32 v3, v3
	v_add_f32_e32 v2, 1.0, v2
	v_add_f32_e32 v3, 1.0, v3
	v_rcp_f32_e32 v2, v2
	v_rcp_f32_e32 v3, v3
	s_nop 0
	v_pk_mul_f32 v[2:3], v[8:9], v[2:3]
	s_nop 0
	v_pk_mul_f32 v[8:9], v[2:3], v[4:5]
	v_cvt_pk_bf16_f32 v4, v6, v7
	v_cvt_pk_bf16_f32 v2, v10, v11
	v_cvt_pk_bf16_f32 v3, v12, v13
	v_cvt_pk_bf16_f32 v5, v8, v9
	v_add_u32_e32 v6, 0xf2000, v114
	global_store_dwordx4 v6, v[2:5], s[20:21]
	s_cbranch_vccz .LBB0_96
	s_nop 0
	v_lshl_add_u32 v2, s42, 8, v145
	v_ashrrev_i32_e32 v3, 31, v2
	v_lshl_add_u64 v[2:3], v[2:3], 2, s[4:5]
	global_load_dword v154, v[2:3], off
	global_load_dword v152, v[2:3], off offset:64
	global_load_dword v150, v[2:3], off offset:128
	global_load_dword v148, v[2:3], off offset:192
	global_load_dword v146, v[2:3], off offset:512
	global_load_dword v144, v[2:3], off offset:576
	global_load_dword v142, v[2:3], off offset:640
	global_load_dword v136, v[2:3], off offset:704
	s_mov_b64 s[60:61], 0
	s_branch .LBB0_96

; #define PG8_STAGE(bufoff, gbase, voff) do { _Pragma("unroll") for (int _i = 0; _i < 2; ++_i) \
;         __builtin_amdgcn_global_load_lds((const unsigned*)((const char*)(gbase) + (voff)[_i]), (LAS unsigned*)(lds + (bufoff) + ldsw + _i * 8192), 16, 0, 0); } while (0)
; #define PG8_LDA(dst, b, h) do { _Pragma("unroll") for (int m = 0; m < 4; ++m) _Pragma("unroll") for (int k = 0; k < 2; ++k) dst[m][k] = *(const LAS bf16x8*)(lds + PG8_SA(b, h) + aoff + m * 2048 + k * 1024); } while (0)
; #define PG8_LDB(dst, b, h) do { _Pragma("unroll") for (int n = 0; n < 2; ++n) _Pragma("unroll") for (int k = 0; k < 2; ++k) dst[n][k] = *(const LAS bf16x8*)(lds + PG8_SB(b, h) + boff + n * 2048 + k * 1024); } while (0)
; #define PG8_MMA(ai, bj, At, Bt) do { __builtin_amdgcn_s_setprio(1); _Pragma("unroll") for (int m = 0; m < 4; ++m) _Pragma("unroll") for (int n = 0; n < 2; ++n) _Pragma("unroll") for (int k = 0; k < 2; ++k) \
;         acc[ai][bj][m][n] = __builtin_amdgcn_mfma_f32_16x16x32_bf16(Bt[n][k], At[m][k], acc[ai][bj][m][n], 0, 0, 0); __builtin_amdgcn_s_setprio(0); } while (0)
; #define PG8_WAIT_V(n) asm volatile("s_waitcnt vmcnt(" #n ")" ::: "memory")
; #define PG8_WAIT_L(n) asm volatile("s_waitcnt lgkmcnt(" #n ")" ::: "memory")
; #define PG8_BAR __builtin_amdgcn_s_barrier()
; template <class Epi>
; __device__ __forceinline__ void gemm_phase(LAS unsigned char* lds, const Gemm g, const StaticOrder& S, const Epi& E) {
;     ...
;         for (int t = 0; t < nt; t += 2) {
;             const bool last = (t == nt - 2);
;             const char* a1 = cA + (size_t)(t + 1) * kstep;
;             const char* a2 = last ? nA : cA + (size_t)(t + 2) * kstep; const char* b2 = last ? nB : cB + (size_t)(t + 2) * kstep;
;             const char* a3 = a2 + kstep; const char* b3 = b2 + kstep;
;             PG8_LDB(B0, 0, 0); PG8_SCHED; PG8_LDA(At, 0, 0); PG8_STAGE(PG8_SA(1, 1), a1 + hA, voffA);
;             PG8_WAIT_L(8); PG8_BAR; PG8_WAIT_L(0); PG8_MMA(0, 0, At, B0); PG8_BAR; PG8_SCHED;
;             PG8_LDB(B1, 0, 1); PG8_STAGE(PG8_SB(0, 0), b2, voffB);
;             PG8_BAR; PG8_WAIT_L(0); PG8_MMA(0, 1, At, B1); PG8_BAR;
;             PG8_LDA(At, 0, 1); PG8_STAGE(PG8_SA(0, 0), a2, voffA);
;             PG8_BAR; PG8_WAIT_L(0); PG8_MMA(1, 0, At, B0); PG8_BAR; PG8_SCHED;
;             PG8_STAGE(PG8_SB(0, 1), b2 + hB, voffB);
;             PG8_WAIT_V(6); PG8_BAR; PG8_MMA(1, 1, At, B1); PG8_BAR;
.LBB0_209:
	s_add_i32 vcc_lo, s70, 2
	s_add_u32 s22, s68, 0xfffc0080
	s_addc_u32 s23, s69, -1
	s_add_i32 vcc_hi, 0, 0x10000
	v_add_u32_e32 v142, vcc_hi, v188
	ds_read_b128 v[130:133], v142
	ds_read_b128 v[134:137], v142 offset:1024
	ds_read_b128 v[138:141], v142 offset:2048
	ds_read_b128 v[142:145], v142 offset:3072
	s_cmp_eq_u32 s65, s70
	s_cselect_b32 s70, s59, s67
	s_cselect_b32 s75, s33, s23
	s_cselect_b32 s74, s45, s22
	s_cselect_b32 s71, s57, s97
	s_add_i32 m0, s43, 0xc000
	ds_read_b128 v[146:149], v189
	ds_read_b128 v[150:153], v189 offset:1024
	ds_read_b128 v[154:157], v189 offset:2048
	ds_read_b128 v[168:171], v189 offset:3072
	ds_read_b128 v[172:175], v189 offset:4096
	ds_read_b128 v[176:179], v189 offset:5120
	ds_read_b128 v[180:183], v189 offset:6144
	ds_read_b128 v[190:193], v189 offset:7168
	global_load_lds_dwordx4 v164, s[68:69]
	s_add_i32 m0, s43, 0xe000
	s_nop 0
	global_load_lds_dwordx4 v166, s[68:69]
	s_waitcnt lgkmcnt(8)
	s_barrier
	s_waitcnt lgkmcnt(0)
	s_setprio 1
	s_waitcnt lgkmcnt(0)
	v_mfma_f32_16x16x32_bf16 v[126:129], v[130:133], v[146:149], v[126:129]
	v_mfma_f32_16x16x32_bf16 v[122:125], v[138:141], v[146:149], v[122:125]
	v_mfma_f32_16x16x32_bf16 v[110:113], v[130:133], v[154:157], v[110:113]
	v_mfma_f32_16x16x32_bf16 v[106:109], v[138:141], v[154:157], v[106:109]
	v_mfma_f32_16x16x32_bf16 v[94:97], v[130:133], v[172:175], v[94:97]
	v_mfma_f32_16x16x32_bf16 v[90:93], v[138:141], v[172:175], v[90:93]
	v_mfma_f32_16x16x32_bf16 v[78:81], v[130:133], v[180:183], v[78:81]
	v_mfma_f32_16x16x32_bf16 v[74:77], v[138:141], v[180:183], v[74:77]
	v_mfma_f32_16x16x32_bf16 v[126:129], v[134:137], v[150:153], v[126:129]
	v_mfma_f32_16x16x32_bf16 v[122:125], v[142:145], v[150:153], v[122:125]
	v_mfma_f32_16x16x32_bf16 v[110:113], v[134:137], v[168:171], v[110:113]
	v_mfma_f32_16x16x32_bf16 v[106:109], v[142:145], v[168:171], v[106:109]
	v_mfma_f32_16x16x32_bf16 v[94:97], v[134:137], v[176:179], v[94:97]
	v_mfma_f32_16x16x32_bf16 v[90:93], v[142:145], v[176:179], v[90:93]
	v_mfma_f32_16x16x32_bf16 v[78:81], v[134:137], v[190:193], v[78:81]
	v_mfma_f32_16x16x32_bf16 v[74:77], v[142:145], v[190:193], v[74:77]
	s_setprio 0
	s_barrier
	s_add_i32 s77, 0, 0x14000
	v_add_u32_e32 v184, s77, v188
	s_add_i32 s22, vcc_hi, s50
	ds_read_b128 v[202:205], v184
	ds_read_b128 v[206:209], v184 offset:1024
	ds_read_b128 v[210:213], v184 offset:2048
	ds_read_b128 v[214:217], v184 offset:3072
	s_mov_b32 m0, s22
	s_nop 0
	global_load_lds_dwordx4 v0, s[70:71]
	s_add_i32 m0, s22, 0x2000
	s_nop 0
	global_load_lds_dwordx4 v162, s[70:71]
	s_barrier
	s_waitcnt lgkmcnt(0)
	s_setprio 1
	s_waitcnt lgkmcnt(0)
	v_mfma_f32_16x16x32_bf16 v[118:121], v[202:205], v[146:149], v[118:121]
	v_mfma_f32_16x16x32_bf16 v[114:117], v[210:213], v[146:149], v[114:117]
	v_mfma_f32_16x16x32_bf16 v[102:105], v[202:205], v[154:157], v[102:105]
	v_mfma_f32_16x16x32_bf16 v[98:101], v[210:213], v[154:157], v[98:101]
	v_mfma_f32_16x16x32_bf16 v[86:89], v[202:205], v[172:175], v[86:89]
	v_mfma_f32_16x16x32_bf16 v[82:85], v[210:213], v[172:175], v[82:85]
	v_mfma_f32_16x16x32_bf16 v[70:73], v[202:205], v[180:183], v[70:73]
	v_mfma_f32_16x16x32_bf16 v[66:69], v[210:213], v[180:183], v[66:69]
	v_mfma_f32_16x16x32_bf16 v[118:121], v[206:209], v[150:153], v[118:121]
	v_mfma_f32_16x16x32_bf16 v[114:117], v[214:217], v[150:153], v[114:117]
	v_mfma_f32_16x16x32_bf16 v[102:105], v[206:209], v[168:171], v[102:105]
	v_mfma_f32_16x16x32_bf16 v[98:101], v[214:217], v[168:171], v[98:101]
	v_mfma_f32_16x16x32_bf16 v[86:89], v[206:209], v[176:179], v[86:89]
	v_mfma_f32_16x16x32_bf16 v[82:85], v[214:217], v[176:179], v[82:85]
	v_mfma_f32_16x16x32_bf16 v[70:73], v[206:209], v[190:193], v[70:73]
	v_mfma_f32_16x16x32_bf16 v[66:69], v[214:217], v[190:193], v[66:69]
	s_setprio 0
	s_mov_b32 m0, s43
	s_barrier
	ds_read_b128 v[146:149], v189 offset:16384
	ds_read_b128 v[150:153], v189 offset:17408
	ds_read_b128 v[154:157], v189 offset:18432
	ds_read_b128 v[168:171], v189 offset:19456
	ds_read_b128 v[172:175], v189 offset:20480
	ds_read_b128 v[176:179], v189 offset:21504
	ds_read_b128 v[180:183], v189 offset:22528
	ds_read_b128 v[190:193], v189 offset:23552
	global_load_lds_dwordx4 v158, s[74:75]
	s_mov_b32 m0, s51
	s_nop 0
	global_load_lds_dwordx4 v160, s[74:75]
	s_barrier
	s_waitcnt lgkmcnt(0)
	s_setprio 1
	s_waitcnt lgkmcnt(0)
	v_mfma_f32_16x16x32_bf16 v[62:65], v[130:133], v[146:149], v[62:65]
	v_mfma_f32_16x16x32_bf16 v[58:61], v[138:141], v[146:149], v[58:61]
	v_mfma_f32_16x16x32_bf16 v[46:49], v[130:133], v[154:157], v[46:49]
	v_mfma_f32_16x16x32_bf16 v[42:45], v[138:141], v[154:157], v[42:45]
	v_mfma_f32_16x16x32_bf16 v[30:33], v[130:133], v[172:175], v[30:33]
	v_mfma_f32_16x16x32_bf16 v[26:29], v[138:141], v[172:175], v[26:29]
	v_mfma_f32_16x16x32_bf16 v[14:17], v[130:133], v[180:183], v[14:17]
	v_mfma_f32_16x16x32_bf16 v[10:13], v[138:141], v[180:183], v[10:13]
	v_mfma_f32_16x16x32_bf16 v[62:65], v[134:137], v[150:153], v[62:65]
	v_mfma_f32_16x16x32_bf16 v[58:61], v[142:145], v[150:153], v[58:61]
	v_mfma_f32_16x16x32_bf16 v[46:49], v[134:137], v[168:171], v[46:49]
	v_mfma_f32_16x16x32_bf16 v[42:45], v[142:145], v[168:171], v[42:45]
	v_mfma_f32_16x16x32_bf16 v[30:33], v[134:137], v[176:179], v[30:33]
	v_mfma_f32_16x16x32_bf16 v[26:29], v[142:145], v[176:179], v[26:29]
	v_mfma_f32_16x16x32_bf16 v[14:17], v[134:137], v[190:193], v[14:17]
	v_mfma_f32_16x16x32_bf16 v[10:13], v[142:145], v[190:193], v[10:13]
	s_setprio 0
	s_barrier
	s_add_u32 s22, s70, 0x40000
	s_addc_u32 s23, s71, 0
	s_add_i32 s77, s77, s50
	s_mov_b32 m0, s77
	s_nop 0
	global_load_lds_dwordx4 v0, s[22:23]
	s_add_i32 m0, s77, 0x2000
	s_nop 0
	global_load_lds_dwordx4 v162, s[22:23]
	s_waitcnt vmcnt(6)
	s_barrier
; #define PG8_STAGE(bufoff, gbase, voff) do { _Pragma("unroll") for (int _i = 0; _i < 2; ++_i) \
;         __builtin_amdgcn_global_load_lds((const unsigned*)((const char*)(gbase) + (voff)[_i]), (LAS unsigned*)(lds + (bufoff) + ldsw + _i * 8192), 16, 0, 0); } while (0)
; #define PG8_LDA(dst, b, h) do { _Pragma("unroll") for (int m = 0; m < 4; ++m) _Pragma("unroll") for (int k = 0; k < 2; ++k) dst[m][k] = *(const LAS bf16x8*)(lds + PG8_SA(b, h) + aoff + m * 2048 + k * 1024); } while (0)
; #define PG8_LDB(dst, b, h) do { _Pragma("unroll") for (int n = 0; n < 2; ++n) _Pragma("unroll") for (int k = 0; k < 2; ++k) dst[n][k] = *(const LAS bf16x8*)(lds + PG8_SB(b, h) + boff + n * 2048 + k * 1024); } while (0)
; #define PG8_MMA(ai, bj, At, Bt) do { __builtin_amdgcn_s_setprio(1); _Pragma("unroll") for (int m = 0; m < 4; ++m) _Pragma("unroll") for (int n = 0; n < 2; ++n) _Pragma("unroll") for (int k = 0; k < 2; ++k) \
;         acc[ai][bj][m][n] = __builtin_amdgcn_mfma_f32_16x16x32_bf16(Bt[n][k], At[m][k], acc[ai][bj][m][n], 0, 0, 0); __builtin_amdgcn_s_setprio(0); } while (0)
; #define PG8_WAIT_V(n) asm volatile("s_waitcnt vmcnt(" #n ")" ::: "memory")
; #define PG8_WAIT_L(n) asm volatile("s_waitcnt lgkmcnt(" #n ")" ::: "memory")
; #define PG8_BAR __builtin_amdgcn_s_barrier()
; #define PG8_SCHED __builtin_amdgcn_sched_barrier(0)
; template <class Epi>
; __device__ __forceinline__ void gemm_phase(LAS unsigned char* lds, const Gemm g, const StaticOrder& S, const Epi& E) {
;     ...
;             PG8_WAIT_V(6); PG8_BAR; PG8_MMA(1, 1, At, B1); PG8_BAR;
;             PG8_LDB(B0, 1, 0); PG8_SCHED; PG8_LDA(At, 1, 0); PG8_STAGE(PG8_SA(0, 1), a2 + hA, voffA);
;             PG8_WAIT_L(8); PG8_BAR; PG8_WAIT_L(0); PG8_MMA(0, 0, At, B0); PG8_BAR; PG8_SCHED;
;             PG8_LDB(B1, 1, 1); PG8_STAGE(PG8_SB(1, 0), b3, voffB);
;             PG8_BAR; PG8_WAIT_L(0); PG8_MMA(0, 1, At, B1); PG8_BAR;
;             PG8_LDA(At, 1, 1); PG8_STAGE(PG8_SA(1, 0), a3, voffA);
;             PG8_BAR; PG8_WAIT_L(0); PG8_MMA(1, 0, At, B0); PG8_BAR; PG8_SCHED;
;             PG8_STAGE(PG8_SB(1, 1), b3 + hB, voffB);
	s_setprio 1
	v_mfma_f32_16x16x32_bf16 v[54:57], v[202:205], v[146:149], v[54:57]
	v_mfma_f32_16x16x32_bf16 v[50:53], v[210:213], v[146:149], v[50:53]
	v_mfma_f32_16x16x32_bf16 v[38:41], v[202:205], v[154:157], v[38:41]
	v_mfma_f32_16x16x32_bf16 v[34:37], v[210:213], v[154:157], v[34:37]
	v_mfma_f32_16x16x32_bf16 v[22:25], v[202:205], v[172:175], v[22:25]
	v_mfma_f32_16x16x32_bf16 v[18:21], v[210:213], v[172:175], v[18:21]
	v_mfma_f32_16x16x32_bf16 v[6:9], v[202:205], v[180:183], v[6:9]
	v_mfma_f32_16x16x32_bf16 v[2:5], v[210:213], v[180:183], v[2:5]
	v_mfma_f32_16x16x32_bf16 v[54:57], v[206:209], v[150:153], v[54:57]
	v_mfma_f32_16x16x32_bf16 v[50:53], v[214:217], v[150:153], v[50:53]
	v_mfma_f32_16x16x32_bf16 v[38:41], v[206:209], v[168:171], v[38:41]
	v_mfma_f32_16x16x32_bf16 v[34:37], v[214:217], v[168:171], v[34:37]
	v_mfma_f32_16x16x32_bf16 v[22:25], v[206:209], v[176:179], v[22:25]
	v_mfma_f32_16x16x32_bf16 v[18:21], v[214:217], v[176:179], v[18:21]
	v_mfma_f32_16x16x32_bf16 v[6:9], v[206:209], v[190:193], v[6:9]
	v_mfma_f32_16x16x32_bf16 v[2:5], v[214:217], v[190:193], v[2:5]
	s_setprio 0
	s_add_i32 s77, 0, 0x18000
	v_add_u32_e32 v142, s77, v188
	s_barrier
	ds_read_b128 v[130:133], v142
	ds_read_b128 v[134:137], v142 offset:1024
	ds_read_b128 v[138:141], v142 offset:2048
	ds_read_b128 v[142:145], v142 offset:3072
	s_add_u32 s22, s74, 0x40000
	s_addc_u32 s23, s75, 0
	s_mov_b32 m0, s52
	ds_read_b128 v[146:149], v189 offset:32768
	ds_read_b128 v[150:153], v189 offset:33792
	ds_read_b128 v[154:157], v189 offset:34816
	ds_read_b128 v[168:171], v189 offset:35840
	ds_read_b128 v[172:175], v189 offset:36864
	ds_read_b128 v[176:179], v189 offset:37888
	ds_read_b128 v[180:183], v189 offset:38912
	ds_read_b128 v[190:193], v189 offset:39936
	global_load_lds_dwordx4 v158, s[22:23]
	s_mov_b32 m0, s53
	s_nop 0
	global_load_lds_dwordx4 v160, s[22:23]
	s_waitcnt lgkmcnt(8)
	s_barrier
	s_waitcnt lgkmcnt(0)
	s_setprio 1
	s_waitcnt lgkmcnt(0)
	v_mfma_f32_16x16x32_bf16 v[126:129], v[130:133], v[146:149], v[126:129]
	v_mfma_f32_16x16x32_bf16 v[122:125], v[138:141], v[146:149], v[122:125]
	v_mfma_f32_16x16x32_bf16 v[110:113], v[130:133], v[154:157], v[110:113]
	v_mfma_f32_16x16x32_bf16 v[106:109], v[138:141], v[154:157], v[106:109]
	v_mfma_f32_16x16x32_bf16 v[94:97], v[130:133], v[172:175], v[94:97]
	v_mfma_f32_16x16x32_bf16 v[90:93], v[138:141], v[172:175], v[90:93]
	v_mfma_f32_16x16x32_bf16 v[78:81], v[130:133], v[180:183], v[78:81]
	v_mfma_f32_16x16x32_bf16 v[74:77], v[138:141], v[180:183], v[74:77]
	v_mfma_f32_16x16x32_bf16 v[126:129], v[134:137], v[150:153], v[126:129]
	v_mfma_f32_16x16x32_bf16 v[122:125], v[142:145], v[150:153], v[122:125]
	v_mfma_f32_16x16x32_bf16 v[110:113], v[134:137], v[168:171], v[110:113]
	v_mfma_f32_16x16x32_bf16 v[106:109], v[142:145], v[168:171], v[106:109]
	v_mfma_f32_16x16x32_bf16 v[94:97], v[134:137], v[176:179], v[94:97]
	v_mfma_f32_16x16x32_bf16 v[90:93], v[142:145], v[176:179], v[90:93]
	v_mfma_f32_16x16x32_bf16 v[78:81], v[134:137], v[190:193], v[78:81]
	v_mfma_f32_16x16x32_bf16 v[74:77], v[142:145], v[190:193], v[74:77]
	s_setprio 0
	s_barrier
	s_add_i32 s22, s77, s50
	v_add_u32_e32 v214, 0x1c000, v188
	s_mov_b32 m0, s22
	ds_read_b128 v[202:205], v214
	ds_read_b128 v[206:209], v214 offset:1024
	ds_read_b128 v[210:213], v214 offset:2048
	ds_read_b128 v[214:217], v214 offset:3072
	s_add_u32 s100, s70, 0x80
	s_addc_u32 s101, s71, 0
	global_load_lds_dwordx4 v0, s[100:101]
	s_add_i32 m0, s22, 0x2000
	s_nop 0
	global_load_lds_dwordx4 v162, s[100:101]
	s_barrier
	s_waitcnt lgkmcnt(0)
	s_setprio 1
	s_waitcnt lgkmcnt(0)
	v_mfma_f32_16x16x32_bf16 v[118:121], v[202:205], v[146:149], v[118:121]
	v_mfma_f32_16x16x32_bf16 v[114:117], v[210:213], v[146:149], v[114:117]
	v_mfma_f32_16x16x32_bf16 v[102:105], v[202:205], v[154:157], v[102:105]
	v_mfma_f32_16x16x32_bf16 v[98:101], v[210:213], v[154:157], v[98:101]
	v_mfma_f32_16x16x32_bf16 v[86:89], v[202:205], v[172:175], v[86:89]
	v_mfma_f32_16x16x32_bf16 v[82:85], v[210:213], v[172:175], v[82:85]
	v_mfma_f32_16x16x32_bf16 v[70:73], v[202:205], v[180:183], v[70:73]
	v_mfma_f32_16x16x32_bf16 v[66:69], v[210:213], v[180:183], v[66:69]
	v_mfma_f32_16x16x32_bf16 v[118:121], v[206:209], v[150:153], v[118:121]
	v_mfma_f32_16x16x32_bf16 v[114:117], v[214:217], v[150:153], v[114:117]
	v_mfma_f32_16x16x32_bf16 v[102:105], v[206:209], v[168:171], v[102:105]
	v_mfma_f32_16x16x32_bf16 v[98:101], v[214:217], v[168:171], v[98:101]
	v_mfma_f32_16x16x32_bf16 v[86:89], v[206:209], v[176:179], v[86:89]
	v_mfma_f32_16x16x32_bf16 v[82:85], v[214:217], v[176:179], v[82:85]
	v_mfma_f32_16x16x32_bf16 v[70:73], v[206:209], v[190:193], v[70:73]
	v_mfma_f32_16x16x32_bf16 v[66:69], v[214:217], v[190:193], v[66:69]
	s_setprio 0
	s_mov_b32 m0, s55
	s_barrier
	ds_read_b128 v[146:149], v189 offset:49152
	ds_read_b128 v[150:153], v189 offset:50176
	ds_read_b128 v[154:157], v189 offset:51200
	ds_read_b128 v[168:171], v189 offset:52224
	ds_read_b128 v[172:175], v189 offset:53248
	ds_read_b128 v[176:179], v189 offset:54272
	ds_read_b128 v[180:183], v189 offset:55296
	ds_read_b128 v[190:193], v189 offset:56320
	s_add_u32 s100, s74, 0x80
	s_addc_u32 s101, s75, 0
	global_load_lds_dwordx4 v158, s[100:101]
	s_mov_b32 m0, s48
	s_nop 0
	global_load_lds_dwordx4 v160, s[100:101]
	s_barrier
; #define PG8_STAGE(bufoff, gbase, voff) do { _Pragma("unroll") for (int _i = 0; _i < 2; ++_i) \
;         __builtin_amdgcn_global_load_lds((const unsigned*)((const char*)(gbase) + (voff)[_i]), (LAS unsigned*)(lds + (bufoff) + ldsw + _i * 8192), 16, 0, 0); } while (0)
; #define PG8_LDA(dst, b, h) do { _Pragma("unroll") for (int m = 0; m < 4; ++m) _Pragma("unroll") for (int k = 0; k < 2; ++k) dst[m][k] = *(const LAS bf16x8*)(lds + PG8_SA(b, h) + aoff + m * 2048 + k * 1024); } while (0)
; #define PG8_MMA(ai, bj, At, Bt) do { __builtin_amdgcn_s_setprio(1); _Pragma("unroll") for (int m = 0; m < 4; ++m) _Pragma("unroll") for (int n = 0; n < 2; ++n) _Pragma("unroll") for (int k = 0; k < 2; ++k) \
;         acc[ai][bj][m][n] = __builtin_amdgcn_mfma_f32_16x16x32_bf16(Bt[n][k], At[m][k], acc[ai][bj][m][n], 0, 0, 0); __builtin_amdgcn_s_setprio(0); } while (0)
; #define PG8_WAIT_V(n) asm volatile("s_waitcnt vmcnt(" #n ")" ::: "memory")
; #define PG8_WAIT_L(n) asm volatile("s_waitcnt lgkmcnt(" #n ")" ::: "memory")
; #define PG8_BAR __builtin_amdgcn_s_barrier()
; #define PG8_SCHED __builtin_amdgcn_sched_barrier(0)
; template <class Epi>
; __device__ __forceinline__ void gemm_phase(LAS unsigned char* lds, const Gemm g, const StaticOrder& S, const Epi& E) {
;     ...
;             PG8_LDA(At, 1, 1); PG8_STAGE(PG8_SA(1, 0), a3, voffA);
;             PG8_BAR; PG8_WAIT_L(0); PG8_MMA(1, 0, At, B0); PG8_BAR; PG8_SCHED;
;             PG8_STAGE(PG8_SB(1, 1), b3 + hB, voffB);
;             PG8_WAIT_V(6); PG8_BAR; PG8_MMA(1, 1, At, B1); PG8_BAR;
;         }
;         if constexpr (Epi::HAS_PRE) { E(acc, cur, wr, wc, fr, fq, pre); if (has_next) E.pre(pre, nxt, wr, fr); } else E(acc, cur, wr, wc, fr, fq);
;     __device__ __forceinline__ void operator()(const Acc& acc, const Unit& u, int wr, int wc, int fr, int fq) const {
;     ...
;         if (u.split) {
;             float* pt = part + (size_t)(u.split - 1) * 256 * DM;
; #pragma unroll
;             for (int ai = 0; ai < 2; ++ai)
; #pragma unroll
;                 for (int m = 0; m < 4; ++m)
; #pragma unroll
;                     for (int bj = 0; bj < 2; ++bj)
; #pragma unroll
;                         for (int n = 0; n < 2; ++n) *(f32x4*)(pt + (size_t)(wr * 64 + fr + ai * 128 + m * 16) * DM + col0 + bj * 128 + n * 4) = acc[ai][bj][m][n] * sc;
;             return; }
	s_waitcnt lgkmcnt(0)
	s_setprio 1
	s_waitcnt lgkmcnt(0)
	v_mfma_f32_16x16x32_bf16 v[62:65], v[130:133], v[146:149], v[62:65]
	v_mfma_f32_16x16x32_bf16 v[58:61], v[138:141], v[146:149], v[58:61]
	v_mfma_f32_16x16x32_bf16 v[46:49], v[130:133], v[154:157], v[46:49]
	v_mfma_f32_16x16x32_bf16 v[42:45], v[138:141], v[154:157], v[42:45]
	v_mfma_f32_16x16x32_bf16 v[30:33], v[130:133], v[172:175], v[30:33]
	v_mfma_f32_16x16x32_bf16 v[26:29], v[138:141], v[172:175], v[26:29]
	v_mfma_f32_16x16x32_bf16 v[14:17], v[130:133], v[180:183], v[14:17]
	v_mfma_f32_16x16x32_bf16 v[10:13], v[138:141], v[180:183], v[10:13]
	v_mfma_f32_16x16x32_bf16 v[62:65], v[134:137], v[150:153], v[62:65]
	v_mfma_f32_16x16x32_bf16 v[58:61], v[142:145], v[150:153], v[58:61]
	v_mfma_f32_16x16x32_bf16 v[46:49], v[134:137], v[168:171], v[46:49]
	v_mfma_f32_16x16x32_bf16 v[42:45], v[142:145], v[168:171], v[42:45]
	v_mfma_f32_16x16x32_bf16 v[30:33], v[134:137], v[176:179], v[30:33]
	v_mfma_f32_16x16x32_bf16 v[26:29], v[142:145], v[176:179], v[26:29]
	v_mfma_f32_16x16x32_bf16 v[14:17], v[134:137], v[190:193], v[14:17]
	v_mfma_f32_16x16x32_bf16 v[10:13], v[142:145], v[190:193], v[10:13]
	s_setprio 0
	s_barrier
	s_add_u32 s22, s70, 0x40080
	s_addc_u32 s23, s71, 0
	s_add_i32 s70, s50, 0x1c000
	s_mov_b32 m0, s70
	s_nop 0
	global_load_lds_dwordx4 v0, s[22:23]
	s_add_i32 m0, s70, 0x2000
	s_nop 0
	global_load_lds_dwordx4 v162, s[22:23]
	s_waitcnt vmcnt(6)
	s_barrier
	s_setprio 1
	v_mfma_f32_16x16x32_bf16 v[54:57], v[202:205], v[146:149], v[54:57]
	v_mfma_f32_16x16x32_bf16 v[50:53], v[210:213], v[146:149], v[50:53]
	v_mfma_f32_16x16x32_bf16 v[38:41], v[202:205], v[154:157], v[38:41]
	v_mfma_f32_16x16x32_bf16 v[34:37], v[210:213], v[154:157], v[34:37]
	v_mfma_f32_16x16x32_bf16 v[22:25], v[202:205], v[172:175], v[22:25]
	v_mfma_f32_16x16x32_bf16 v[18:21], v[210:213], v[172:175], v[18:21]
	v_mfma_f32_16x16x32_bf16 v[6:9], v[202:205], v[180:183], v[6:9]
	v_mfma_f32_16x16x32_bf16 v[2:5], v[210:213], v[180:183], v[2:5]
	v_mfma_f32_16x16x32_bf16 v[54:57], v[206:209], v[150:153], v[54:57]
	v_mfma_f32_16x16x32_bf16 v[50:53], v[214:217], v[150:153], v[50:53]
	v_mfma_f32_16x16x32_bf16 v[38:41], v[206:209], v[168:171], v[38:41]
	v_mfma_f32_16x16x32_bf16 v[34:37], v[214:217], v[168:171], v[34:37]
	v_mfma_f32_16x16x32_bf16 v[22:25], v[206:209], v[176:179], v[22:25]
	v_mfma_f32_16x16x32_bf16 v[18:21], v[214:217], v[176:179], v[18:21]
	v_mfma_f32_16x16x32_bf16 v[6:9], v[206:209], v[190:193], v[6:9]
	v_mfma_f32_16x16x32_bf16 v[2:5], v[214:217], v[190:193], v[2:5]
	s_setprio 0
	s_add_u32 s68, s68, 0x100
	s_addc_u32 s69, s69, 0
	s_add_u32 s67, s67, 0x100
	s_addc_u32 s97, s97, 0
	s_cmp_ge_i32 vcc_lo, s30
	s_mov_b32 s70, vcc_lo
	s_barrier
	s_cbranch_scc0 .LBB0_209
	s_lshl_b32 s22, s42, 8
	v_mov_b32_e32 v133, v186
	v_mov_b32_e32 v132, v187
	s_or_b32 s22, s22, s82
	s_cmp_lg_u32 s66, 0
	v_lshl_add_u32 v168, v132, 3, s22
	v_add_u32_e32 v130, s81, v133
	v_ashrrev_i32_e32 v169, 31, v168
	s_cbranch_scc0 .LBB0_212
	s_ashr_i32 s67, s66, 31
	s_lshl_b64 s[66:67], s[66:67], 20
	s_add_u32 s66, s19, s66
	s_addc_u32 s67, s80, s67
	v_ashrrev_i32_e32 v131, 31, v130
	v_lshl_add_u64 v[134:135], v[168:169], 2, s[66:67]
	v_lshlrev_b64 v[136:137], 12, v[130:131]
	s_mov_b32 s22, 0xfff00000
	v_lshl_add_u64 v[134:135], v[134:135], 0, v[136:137]
	s_mov_b32 s23, -1
	v_lshl_add_u64 v[136:137], v[134:135], 0, s[22:23]
	v_add_co_u32_e32 v138, vcc, s83, v134
	s_mov_b32 s22, 0xfff10000
	s_nop 0
	v_addc_co_u32_e32 v139, vcc, -1, v135, vcc
	s_mov_b32 s23, -1
	global_store_dwordx4 v[138:139], v[126:129], off
	global_store_dwordx4 v[136:137], v[122:125], off offset:16
	global_store_dwordx4 v[136:137], v[118:121], off offset:512
	global_store_dwordx4 v[136:137], v[114:117], off offset:528
	v_lshl_add_u64 v[136:137], v[134:135], 0, s[22:23]
	v_add_co_u32_e32 v138, vcc, s1, v134
	s_mov_b32 s22, 0xfff20000
	s_nop 0
	v_addc_co_u32_e32 v139, vcc, -1, v135, vcc
	s_mov_b32 s23, -1
	global_store_dwordx4 v[138:139], v[110:113], off
	global_store_dwordx4 v[136:137], v[106:109], off offset:16
	global_store_dwordx4 v[136:137], v[102:105], off offset:512
	global_store_dwordx4 v[136:137], v[98:101], off offset:528
	v_lshl_add_u64 v[136:137], v[134:135], 0, s[22:23]
	s_mov_b32 s22, 0xfff20000
	v_add_co_u32_e32 v138, vcc, s22, v134
	s_mov_b32 s22, 0xfff30000
	s_nop 0
	v_addc_co_u32_e32 v139, vcc, -1, v135, vcc
	s_mov_b32 s23, -1
	global_store_dwordx4 v[138:139], v[94:97], off
	global_store_dwordx4 v[136:137], v[90:93], off offset:16
	global_store_dwordx4 v[136:137], v[86:89], off offset:512
	global_store_dwordx4 v[136:137], v[82:85], off offset:528
	v_lshl_add_u64 v[136:137], v[134:135], 0, s[22:23]
	s_mov_b32 s22, 0xfff30000
	v_add_co_u32_e32 v138, vcc, s22, v134
	s_mov_b32 s22, 0xfff80000
	s_nop 0
	v_addc_co_u32_e32 v139, vcc, -1, v135, vcc
	s_mov_b32 s23, -1
	global_store_dwordx4 v[138:139], v[78:81], off
	global_store_dwordx4 v[136:137], v[74:77], off offset:16
	global_store_dwordx4 v[136:137], v[70:73], off offset:512
	global_store_dwordx4 v[136:137], v[66:69], off offset:528
	v_lshl_add_u64 v[136:137], v[134:135], 0, s[22:23]
	s_mov_b32 s22, 0xfff80000
	v_add_co_u32_e32 v138, vcc, s22, v134
	s_mov_b32 s22, 0xfff90000
	s_nop 0
	v_addc_co_u32_e32 v139, vcc, -1, v135, vcc
	s_mov_b32 s23, -1
	global_store_dwordx4 v[138:139], v[62:65], off
	global_store_dwordx4 v[136:137], v[58:61], off offset:16
	global_store_dwordx4 v[136:137], v[54:57], off offset:512
	global_store_dwordx4 v[136:137], v[50:53], off offset:528
	v_lshl_add_u64 v[136:137], v[134:135], 0, s[22:23]
	s_mov_b32 s22, 0xfff90000
	v_add_co_u32_e32 v138, vcc, s22, v134
	s_mov_b32 s22, 0xfffa0000
	s_nop 0
	v_addc_co_u32_e32 v139, vcc, -1, v135, vcc
	s_mov_b32 s23, -1
	global_store_dwordx4 v[138:139], v[46:49], off
	global_store_dwordx4 v[136:137], v[42:45], off offset:16
	global_store_dwordx4 v[136:137], v[38:41], off offset:512
	global_store_dwordx4 v[136:137], v[34:37], off offset:528
	v_lshl_add_u64 v[136:137], v[134:135], 0, s[22:23]
	s_mov_b32 s22, 0xfffa0000
	v_add_co_u32_e32 v138, vcc, s22, v134
	s_mov_b32 s22, 0xfffb0000
	s_nop 0
	v_addc_co_u32_e32 v139, vcc, -1, v135, vcc
	s_mov_b32 s23, -1
	global_store_dwordx4 v[138:139], v[30:33], off
	global_store_dwordx4 v[136:137], v[26:29], off offset:16
	global_store_dwordx4 v[136:137], v[22:25], off offset:512
	global_store_dwordx4 v[136:137], v[18:21], off offset:528
	v_lshl_add_u64 v[136:137], v[134:135], 0, s[22:23]
	v_add_co_u32_e32 v134, vcc, 0xfffb0000, v134
	s_mov_b64 s[66:67], 0
	s_nop 0
	v_addc_co_u32_e32 v135, vcc, -1, v135, vcc
	global_store_dwordx4 v[134:135], v[14:17], off
	global_store_dwordx4 v[136:137], v[10:13], off offset:16
	global_store_dwordx4 v[136:137], v[6:9], off offset:512
	global_store_dwordx4 v[136:137], v[2:5], off offset:528
	s_branch .LBB0_213

; #define PG8_STAGE(bufoff, gbase, voff) do { _Pragma("unroll") for (int _i = 0; _i < 2; ++_i) \
;         __builtin_amdgcn_global_load_lds((const unsigned*)((const char*)(gbase) + (voff)[_i]), (LAS unsigned*)(lds + (bufoff) + ldsw + _i * 8192), 16, 0, 0); } while (0)
; #define PG8_LDA(dst, b, h) do { _Pragma("unroll") for (int m = 0; m < 4; ++m) _Pragma("unroll") for (int k = 0; k < 2; ++k) dst[m][k] = *(const LAS bf16x8*)(lds + PG8_SA(b, h) + aoff + m * 2048 + k * 1024); } while (0)
; #define PG8_LDB(dst, b, h) do { _Pragma("unroll") for (int n = 0; n < 2; ++n) _Pragma("unroll") for (int k = 0; k < 2; ++k) dst[n][k] = *(const LAS bf16x8*)(lds + PG8_SB(b, h) + boff + n * 2048 + k * 1024); } while (0)
; #define PG8_MMA(ai, bj, At, Bt) do { __builtin_amdgcn_s_setprio(1); _Pragma("unroll") for (int m = 0; m < 4; ++m) _Pragma("unroll") for (int n = 0; n < 2; ++n) _Pragma("unroll") for (int k = 0; k < 2; ++k) \
;         acc[ai][bj][m][n] = __builtin_amdgcn_mfma_f32_16x16x32_bf16(Bt[n][k], At[m][k], acc[ai][bj][m][n], 0, 0, 0); __builtin_amdgcn_s_setprio(0); } while (0)
; #define PG8_WAIT_V(n) asm volatile("s_waitcnt vmcnt(" #n ")" ::: "memory")
; #define PG8_WAIT_L(n) asm volatile("s_waitcnt lgkmcnt(" #n ")" ::: "memory")
; #define PG8_BAR __builtin_amdgcn_s_barrier()
; template <class Epi>
; __device__ __forceinline__ void gemm_phase(LAS unsigned char* lds, const Gemm g, const StaticOrder& S, const Epi& E) {
;     ...
;         for (int t = 0; t < nt; t += 2) {
;             const bool last = (t == nt - 2);
;             const char* a1 = cA + (size_t)(t + 1) * kstep;
;             const char* a2 = last ? nA : cA + (size_t)(t + 2) * kstep; const char* b2 = last ? nB : cB + (size_t)(t + 2) * kstep;
;             const char* a3 = a2 + kstep; const char* b3 = b2 + kstep;
;             PG8_LDB(B0, 0, 0); PG8_SCHED; PG8_LDA(At, 0, 0); PG8_STAGE(PG8_SA(1, 1), a1 + hA, voffA);
;             PG8_WAIT_L(8); PG8_BAR; PG8_WAIT_L(0); PG8_MMA(0, 0, At, B0); PG8_BAR; PG8_SCHED;
;             PG8_LDB(B1, 0, 1); PG8_STAGE(PG8_SB(0, 0), b2, voffB);
;             PG8_BAR; PG8_WAIT_L(0); PG8_MMA(0, 1, At, B1); PG8_BAR;
;             PG8_LDA(At, 0, 1); PG8_STAGE(PG8_SA(0, 0), a2, voffA);
;             PG8_BAR; PG8_WAIT_L(0); PG8_MMA(1, 0, At, B0); PG8_BAR; PG8_SCHED;
;             PG8_STAGE(PG8_SB(0, 1), b2 + hB, voffB);
;             PG8_WAIT_V(6); PG8_BAR; PG8_MMA(1, 1, At, B1); PG8_BAR;
.LBB0_263:
	s_add_u32 s64, s44, 0x100
	s_addc_u32 s65, s45, 0
	s_add_i32 s22, 0, 0x10000
	v_add_u32_e32 v0, s22, v241
	ds_read_b128 v[132:135], v0
	ds_read_b128 v[136:139], v0 offset:1024
	ds_read_b128 v[140:143], v0 offset:2048
	ds_read_b128 v[144:147], v0 offset:3072
	s_cmp_eq_u32 vcc_lo, 4
	s_cselect_b32 s69, s61, s65
	s_cselect_b32 s68, s60, s64
	s_cselect_b32 s67, s43, s97
	s_cselect_b32 s66, s49, s59
	s_add_i32 m0, s70, 0xc000
	ds_read_b128 v[148:151], v242
	ds_read_b128 v[152:155], v242 offset:1024
	ds_read_b128 v[156:159], v242 offset:2048
	ds_read_b128 v[160:163], v242 offset:3072
	ds_read_b128 v[164:167], v242 offset:4096
	ds_read_b128 v[168:171], v242 offset:5120
	ds_read_b128 v[172:175], v242 offset:6144
	ds_read_b128 v[176:179], v242 offset:7168
	global_load_lds_dwordx4 v210, s[44:45]
	s_add_i32 m0, s70, 0xe000
	s_nop 0
	global_load_lds_dwordx4 v212, s[44:45]
	s_waitcnt lgkmcnt(8)
	s_barrier
	s_waitcnt lgkmcnt(0)
	s_setprio 1
	s_waitcnt lgkmcnt(0)
	v_mfma_f32_16x16x32_bf16 v[2:5], v[132:135], v[148:151], v[4:7]
	v_mfma_f32_16x16x32_bf16 v[6:9], v[140:143], v[148:151], v[8:11]
	v_mfma_f32_16x16x32_bf16 v[128:131], v[132:135], v[156:159], v[128:131]
	v_mfma_f32_16x16x32_bf16 v[124:127], v[140:143], v[156:159], v[124:127]
	v_mfma_f32_16x16x32_bf16 v[120:123], v[132:135], v[164:167], v[120:123]
	v_mfma_f32_16x16x32_bf16 v[116:119], v[140:143], v[164:167], v[116:119]
	v_mfma_f32_16x16x32_bf16 v[112:115], v[132:135], v[172:175], v[112:115]
	v_mfma_f32_16x16x32_bf16 v[108:111], v[140:143], v[172:175], v[108:111]
	v_mfma_f32_16x16x32_bf16 v[2:5], v[136:139], v[152:155], v[2:5]
	v_mfma_f32_16x16x32_bf16 v[8:11], v[144:147], v[152:155], v[6:9]
	v_mfma_f32_16x16x32_bf16 v[128:131], v[136:139], v[160:163], v[128:131]
	v_mfma_f32_16x16x32_bf16 v[124:127], v[144:147], v[160:163], v[124:127]
	v_mfma_f32_16x16x32_bf16 v[120:123], v[136:139], v[168:171], v[120:123]
	v_mfma_f32_16x16x32_bf16 v[116:119], v[144:147], v[168:171], v[116:119]
	v_mfma_f32_16x16x32_bf16 v[112:115], v[136:139], v[176:179], v[112:115]
	v_mfma_f32_16x16x32_bf16 v[108:111], v[144:147], v[176:179], v[108:111]
	s_setprio 0
	s_barrier
	s_add_i32 s23, 0, 0x14000
	s_add_i32 s22, s22, s53
	v_add_u32_e32 v0, s23, v241
	s_mov_b32 m0, s22
	ds_read_b128 v[180:183], v0
	ds_read_b128 v[184:187], v0 offset:1024
	ds_read_b128 v[188:191], v0 offset:2048
	ds_read_b128 v[192:195], v0 offset:3072
	global_load_lds_dwordx4 v204, s[66:67]
	s_add_i32 m0, s22, 0x2000
	s_nop 0
	global_load_lds_dwordx4 v208, s[66:67]
	s_barrier
	s_waitcnt lgkmcnt(0)
	s_setprio 1
	s_waitcnt lgkmcnt(0)
	v_mfma_f32_16x16x32_bf16 v[104:107], v[180:183], v[148:151], v[104:107]
	v_mfma_f32_16x16x32_bf16 v[100:103], v[188:191], v[148:151], v[100:103]
	v_mfma_f32_16x16x32_bf16 v[96:99], v[180:183], v[156:159], v[96:99]
	v_mfma_f32_16x16x32_bf16 v[92:95], v[188:191], v[156:159], v[92:95]
	v_mfma_f32_16x16x32_bf16 v[88:91], v[180:183], v[164:167], v[88:91]
	v_mfma_f32_16x16x32_bf16 v[84:87], v[188:191], v[164:167], v[84:87]
	v_mfma_f32_16x16x32_bf16 v[80:83], v[180:183], v[172:175], v[80:83]
	v_mfma_f32_16x16x32_bf16 v[76:79], v[188:191], v[172:175], v[76:79]
	v_mfma_f32_16x16x32_bf16 v[104:107], v[184:187], v[152:155], v[104:107]
	v_mfma_f32_16x16x32_bf16 v[100:103], v[192:195], v[152:155], v[100:103]
	v_mfma_f32_16x16x32_bf16 v[96:99], v[184:187], v[160:163], v[96:99]
	v_mfma_f32_16x16x32_bf16 v[92:95], v[192:195], v[160:163], v[92:95]
	v_mfma_f32_16x16x32_bf16 v[88:91], v[184:187], v[168:171], v[88:91]
	v_mfma_f32_16x16x32_bf16 v[84:87], v[192:195], v[168:171], v[84:87]
	v_mfma_f32_16x16x32_bf16 v[80:83], v[184:187], v[176:179], v[80:83]
	v_mfma_f32_16x16x32_bf16 v[76:79], v[192:195], v[176:179], v[76:79]
	s_setprio 0
	s_mov_b32 m0, s70
	s_barrier
	ds_read_b128 v[148:151], v242 offset:16384
	ds_read_b128 v[152:155], v242 offset:17408
	ds_read_b128 v[156:159], v242 offset:18432
	ds_read_b128 v[160:163], v242 offset:19456
	ds_read_b128 v[164:167], v242 offset:20480
	ds_read_b128 v[168:171], v242 offset:21504
	ds_read_b128 v[172:175], v242 offset:22528
	ds_read_b128 v[176:179], v242 offset:23552
	global_load_lds_dwordx4 v202, s[68:69]
	s_mov_b32 m0, s71
	s_nop 0
	global_load_lds_dwordx4 v206, s[68:69]
	s_barrier
	s_waitcnt lgkmcnt(0)
	s_setprio 1
	s_waitcnt lgkmcnt(0)
	v_mfma_f32_16x16x32_bf16 v[72:75], v[132:135], v[148:151], v[72:75]
	v_mfma_f32_16x16x32_bf16 v[68:71], v[140:143], v[148:151], v[68:71]
	v_mfma_f32_16x16x32_bf16 v[64:67], v[132:135], v[156:159], v[64:67]
	v_mfma_f32_16x16x32_bf16 v[60:63], v[140:143], v[156:159], v[60:63]
	v_mfma_f32_16x16x32_bf16 v[56:59], v[132:135], v[164:167], v[56:59]
	v_mfma_f32_16x16x32_bf16 v[52:55], v[140:143], v[164:167], v[52:55]
	v_mfma_f32_16x16x32_bf16 v[48:51], v[132:135], v[172:175], v[48:51]
	v_mfma_f32_16x16x32_bf16 v[44:47], v[140:143], v[172:175], v[44:47]
	v_mfma_f32_16x16x32_bf16 v[72:75], v[136:139], v[152:155], v[72:75]
	v_mfma_f32_16x16x32_bf16 v[68:71], v[144:147], v[152:155], v[68:71]
	v_mfma_f32_16x16x32_bf16 v[64:67], v[136:139], v[160:163], v[64:67]
	v_mfma_f32_16x16x32_bf16 v[60:63], v[144:147], v[160:163], v[60:63]
	v_mfma_f32_16x16x32_bf16 v[56:59], v[136:139], v[168:171], v[56:59]
	v_mfma_f32_16x16x32_bf16 v[52:55], v[144:147], v[168:171], v[52:55]
	v_mfma_f32_16x16x32_bf16 v[48:51], v[136:139], v[176:179], v[48:51]
	v_mfma_f32_16x16x32_bf16 v[44:47], v[144:147], v[176:179], v[44:47]
	s_setprio 0
	s_barrier
	s_add_u32 s44, s66, 0x20000
	s_addc_u32 s45, s67, 0
	s_add_i32 s22, s23, s53
	s_mov_b32 m0, s22
	s_nop 0
	global_load_lds_dwordx4 v204, s[44:45]
	s_add_i32 m0, s22, 0x2000
	s_nop 0
	global_load_lds_dwordx4 v208, s[44:45]
	s_waitcnt vmcnt(6)
	s_barrier
; #define PG8_STAGE(bufoff, gbase, voff) do { _Pragma("unroll") for (int _i = 0; _i < 2; ++_i) \
;         __builtin_amdgcn_global_load_lds((const unsigned*)((const char*)(gbase) + (voff)[_i]), (LAS unsigned*)(lds + (bufoff) + ldsw + _i * 8192), 16, 0, 0); } while (0)
; #define PG8_LDA(dst, b, h) do { _Pragma("unroll") for (int m = 0; m < 4; ++m) _Pragma("unroll") for (int k = 0; k < 2; ++k) dst[m][k] = *(const LAS bf16x8*)(lds + PG8_SA(b, h) + aoff + m * 2048 + k * 1024); } while (0)
; #define PG8_LDB(dst, b, h) do { _Pragma("unroll") for (int n = 0; n < 2; ++n) _Pragma("unroll") for (int k = 0; k < 2; ++k) dst[n][k] = *(const LAS bf16x8*)(lds + PG8_SB(b, h) + boff + n * 2048 + k * 1024); } while (0)
; #define PG8_MMA(ai, bj, At, Bt) do { __builtin_amdgcn_s_setprio(1); _Pragma("unroll") for (int m = 0; m < 4; ++m) _Pragma("unroll") for (int n = 0; n < 2; ++n) _Pragma("unroll") for (int k = 0; k < 2; ++k) \
;         acc[ai][bj][m][n] = __builtin_amdgcn_mfma_f32_16x16x32_bf16(Bt[n][k], At[m][k], acc[ai][bj][m][n], 0, 0, 0); __builtin_amdgcn_s_setprio(0); } while (0)
; #define PG8_WAIT_V(n) asm volatile("s_waitcnt vmcnt(" #n ")" ::: "memory")
; #define PG8_WAIT_L(n) asm volatile("s_waitcnt lgkmcnt(" #n ")" ::: "memory")
; #define PG8_BAR __builtin_amdgcn_s_barrier()
; #define PG8_SCHED __builtin_amdgcn_sched_barrier(0)
; template <class Epi>
; __device__ __forceinline__ void gemm_phase(LAS unsigned char* lds, const Gemm g, const StaticOrder& S, const Epi& E) {
;     ...
;             PG8_WAIT_V(6); PG8_BAR; PG8_MMA(1, 1, At, B1); PG8_BAR;
;             PG8_LDB(B0, 1, 0); PG8_SCHED; PG8_LDA(At, 1, 0); PG8_STAGE(PG8_SA(0, 1), a2 + hA, voffA);
;             PG8_WAIT_L(8); PG8_BAR; PG8_WAIT_L(0); PG8_MMA(0, 0, At, B0); PG8_BAR; PG8_SCHED;
;             PG8_LDB(B1, 1, 1); PG8_STAGE(PG8_SB(1, 0), b3, voffB);
;             PG8_BAR; PG8_WAIT_L(0); PG8_MMA(0, 1, At, B1); PG8_BAR;
;             PG8_LDA(At, 1, 1); PG8_STAGE(PG8_SA(1, 0), a3, voffA);
;             PG8_BAR; PG8_WAIT_L(0); PG8_MMA(1, 0, At, B0); PG8_BAR; PG8_SCHED;
;             PG8_STAGE(PG8_SB(1, 1), b3 + hB, voffB);
	s_setprio 1
	v_mfma_f32_16x16x32_bf16 v[40:43], v[180:183], v[148:151], v[40:43]
	v_mfma_f32_16x16x32_bf16 v[36:39], v[188:191], v[148:151], v[36:39]
	v_mfma_f32_16x16x32_bf16 v[32:35], v[180:183], v[156:159], v[32:35]
	v_mfma_f32_16x16x32_bf16 v[28:31], v[188:191], v[156:159], v[28:31]
	v_mfma_f32_16x16x32_bf16 v[24:27], v[180:183], v[164:167], v[24:27]
	v_mfma_f32_16x16x32_bf16 v[20:23], v[188:191], v[164:167], v[20:23]
	v_mfma_f32_16x16x32_bf16 v[16:19], v[180:183], v[172:175], v[16:19]
	v_mfma_f32_16x16x32_bf16 v[12:15], v[188:191], v[172:175], v[12:15]
	v_mfma_f32_16x16x32_bf16 v[40:43], v[184:187], v[152:155], v[40:43]
	v_mfma_f32_16x16x32_bf16 v[36:39], v[192:195], v[152:155], v[36:39]
	v_mfma_f32_16x16x32_bf16 v[32:35], v[184:187], v[160:163], v[32:35]
	v_mfma_f32_16x16x32_bf16 v[28:31], v[192:195], v[160:163], v[28:31]
	v_mfma_f32_16x16x32_bf16 v[24:27], v[184:187], v[168:171], v[24:27]
	v_mfma_f32_16x16x32_bf16 v[20:23], v[192:195], v[168:171], v[20:23]
	v_mfma_f32_16x16x32_bf16 v[16:19], v[184:187], v[176:179], v[16:19]
	v_mfma_f32_16x16x32_bf16 v[12:15], v[192:195], v[176:179], v[12:15]
	s_setprio 0
	s_add_i32 s22, 0, 0x18000
	v_add_u32_e32 v0, s22, v241
	s_barrier
	ds_read_b128 v[132:135], v0
	ds_read_b128 v[136:139], v0 offset:1024
	ds_read_b128 v[140:143], v0 offset:2048
	ds_read_b128 v[144:147], v0 offset:3072
	s_add_u32 s44, s68, 0x110000
	s_addc_u32 s45, s69, 0
	s_mov_b32 m0, s74
	ds_read_b128 v[148:151], v242 offset:32768
	ds_read_b128 v[152:155], v242 offset:33792
	ds_read_b128 v[156:159], v242 offset:34816
	ds_read_b128 v[160:163], v242 offset:35840
	ds_read_b128 v[164:167], v242 offset:36864
	ds_read_b128 v[168:171], v242 offset:37888
	ds_read_b128 v[172:175], v242 offset:38912
	ds_read_b128 v[176:179], v242 offset:39936
	global_load_lds_dwordx4 v202, s[44:45]
	s_mov_b32 m0, s75
	s_nop 0
	global_load_lds_dwordx4 v206, s[44:45]
	s_waitcnt lgkmcnt(8)
	s_barrier
	s_waitcnt lgkmcnt(0)
	s_setprio 1
	s_waitcnt lgkmcnt(0)
	v_mfma_f32_16x16x32_bf16 v[2:5], v[132:135], v[148:151], v[2:5]
	v_mfma_f32_16x16x32_bf16 v[8:11], v[140:143], v[148:151], v[8:11]
	v_mfma_f32_16x16x32_bf16 v[128:131], v[132:135], v[156:159], v[128:131]
	v_mfma_f32_16x16x32_bf16 v[124:127], v[140:143], v[156:159], v[124:127]
	v_mfma_f32_16x16x32_bf16 v[120:123], v[132:135], v[164:167], v[120:123]
	v_mfma_f32_16x16x32_bf16 v[116:119], v[140:143], v[164:167], v[116:119]
	v_mfma_f32_16x16x32_bf16 v[112:115], v[132:135], v[172:175], v[112:115]
	v_mfma_f32_16x16x32_bf16 v[108:111], v[140:143], v[172:175], v[108:111]
	v_mfma_f32_16x16x32_bf16 v[4:7], v[136:139], v[152:155], v[2:5]
	v_mfma_f32_16x16x32_bf16 v[8:11], v[144:147], v[152:155], v[8:11]
	v_mfma_f32_16x16x32_bf16 v[128:131], v[136:139], v[160:163], v[128:131]
	v_mfma_f32_16x16x32_bf16 v[124:127], v[144:147], v[160:163], v[124:127]
	v_mfma_f32_16x16x32_bf16 v[120:123], v[136:139], v[168:171], v[120:123]
	v_mfma_f32_16x16x32_bf16 v[116:119], v[144:147], v[168:171], v[116:119]
	v_mfma_f32_16x16x32_bf16 v[112:115], v[136:139], v[176:179], v[112:115]
	v_mfma_f32_16x16x32_bf16 v[108:111], v[144:147], v[176:179], v[108:111]
	s_setprio 0
	s_barrier
	s_add_i32 s23, 0, 0x1c000
	s_add_i32 s22, s22, s53
	v_add_u32_e32 v0, s23, v241
	s_mov_b32 m0, s22
	ds_read_b128 v[180:183], v0
	ds_read_b128 v[184:187], v0 offset:1024
	ds_read_b128 v[188:191], v0 offset:2048
	ds_read_b128 v[192:195], v0 offset:3072
	s_add_u32 s100, s66, 0x80
	s_addc_u32 s101, s67, 0
	global_load_lds_dwordx4 v204, s[100:101]
	s_add_i32 m0, s22, 0x2000
	s_nop 0
	global_load_lds_dwordx4 v208, s[100:101]
	s_barrier
	s_waitcnt lgkmcnt(0)
	s_setprio 1
	s_waitcnt lgkmcnt(0)
	v_mfma_f32_16x16x32_bf16 v[104:107], v[180:183], v[148:151], v[104:107]
	v_mfma_f32_16x16x32_bf16 v[100:103], v[188:191], v[148:151], v[100:103]
	v_mfma_f32_16x16x32_bf16 v[96:99], v[180:183], v[156:159], v[96:99]
	v_mfma_f32_16x16x32_bf16 v[92:95], v[188:191], v[156:159], v[92:95]
	v_mfma_f32_16x16x32_bf16 v[88:91], v[180:183], v[164:167], v[88:91]
	v_mfma_f32_16x16x32_bf16 v[84:87], v[188:191], v[164:167], v[84:87]
	v_mfma_f32_16x16x32_bf16 v[80:83], v[180:183], v[172:175], v[80:83]
	v_mfma_f32_16x16x32_bf16 v[76:79], v[188:191], v[172:175], v[76:79]
	v_mfma_f32_16x16x32_bf16 v[104:107], v[184:187], v[152:155], v[104:107]
	v_mfma_f32_16x16x32_bf16 v[100:103], v[192:195], v[152:155], v[100:103]
	v_mfma_f32_16x16x32_bf16 v[96:99], v[184:187], v[160:163], v[96:99]
	v_mfma_f32_16x16x32_bf16 v[92:95], v[192:195], v[160:163], v[92:95]
	v_mfma_f32_16x16x32_bf16 v[88:91], v[184:187], v[168:171], v[88:91]
	v_mfma_f32_16x16x32_bf16 v[84:87], v[192:195], v[168:171], v[84:87]
	v_mfma_f32_16x16x32_bf16 v[80:83], v[184:187], v[176:179], v[80:83]
	v_mfma_f32_16x16x32_bf16 v[76:79], v[192:195], v[176:179], v[76:79]
	s_setprio 0
	s_mov_b32 m0, s30
	s_barrier
; #define PG8_STAGE(bufoff, gbase, voff) do { _Pragma("unroll") for (int _i = 0; _i < 2; ++_i) \
;         __builtin_amdgcn_global_load_lds((const unsigned*)((const char*)(gbase) + (voff)[_i]), (LAS unsigned*)(lds + (bufoff) + ldsw + _i * 8192), 16, 0, 0); } while (0)
; #define PG8_LDA(dst, b, h) do { _Pragma("unroll") for (int m = 0; m < 4; ++m) _Pragma("unroll") for (int k = 0; k < 2; ++k) dst[m][k] = *(const LAS bf16x8*)(lds + PG8_SA(b, h) + aoff + m * 2048 + k * 1024); } while (0)
; #define PG8_MMA(ai, bj, At, Bt) do { __builtin_amdgcn_s_setprio(1); _Pragma("unroll") for (int m = 0; m < 4; ++m) _Pragma("unroll") for (int n = 0; n < 2; ++n) _Pragma("unroll") for (int k = 0; k < 2; ++k) \
;         acc[ai][bj][m][n] = __builtin_amdgcn_mfma_f32_16x16x32_bf16(Bt[n][k], At[m][k], acc[ai][bj][m][n], 0, 0, 0); __builtin_amdgcn_s_setprio(0); } while (0)
; #define PG8_WAIT_V(n) asm volatile("s_waitcnt vmcnt(" #n ")" ::: "memory")
; #define PG8_WAIT_L(n) asm volatile("s_waitcnt lgkmcnt(" #n ")" ::: "memory")
; #define PG8_BAR __builtin_amdgcn_s_barrier()
; #define PG8_SCHED __builtin_amdgcn_sched_barrier(0)
; template <class Epi>
; __device__ __forceinline__ void gemm_phase(LAS unsigned char* lds, const Gemm g, const StaticOrder& S, const Epi& E) {
;     ...
;             PG8_LDA(At, 1, 1); PG8_STAGE(PG8_SA(1, 0), a3, voffA);
;             PG8_BAR; PG8_WAIT_L(0); PG8_MMA(1, 0, At, B0); PG8_BAR; PG8_SCHED;
;             PG8_STAGE(PG8_SB(1, 1), b3 + hB, voffB);
;             PG8_WAIT_V(6); PG8_BAR; PG8_MMA(1, 1, At, B1); PG8_BAR;
;         }
;         if constexpr (Epi::HAS_PRE) { E(acc, cur, wr, wc, fr, fq, pre); if (has_next) E.pre(pre, nxt, wr, fr); } else E(acc, cur, wr, wc, fr, fq);
;     __device__ __forceinline__ void operator()(Acc& acc, const Unit& u, int wr, int wc, int fr, int fq) const {
;         asm volatile("" : "+v"(fr), "+v"(fq));
;         const int row0 = u.pm * 256 + wr * 64 + fr, col0 = u.pn * 256 + wc * 32 + 8 * fq;
; #pragma unroll
;         for (int ai = 0; ai < 2; ++ai) {
;             u32x4 av[4][2], bv[4][2];
; #pragma unroll
;             for (int m = 0; m < 4; ++m)
; #pragma unroll
;                 for (int bj = 0; bj < 2; ++bj) { const size_t off = (size_t)(row0 + ai * 128 + m * 16) * NPROJ + col0 + bj * 128;
;                     bv[m][bj] = *(const u32x4*)(gb + off); if (u.alt == 0) av[m][bj] = *(const u32x4*)(ga + off); }
	ds_read_b128 v[148:151], v242 offset:49152
	ds_read_b128 v[152:155], v242 offset:50176
	ds_read_b128 v[156:159], v242 offset:51200
	ds_read_b128 v[160:163], v242 offset:52224
	ds_read_b128 v[164:167], v242 offset:53248
	ds_read_b128 v[168:171], v242 offset:54272
	ds_read_b128 v[172:175], v242 offset:55296
	ds_read_b128 v[176:179], v242 offset:56320
	s_add_u32 s100, s68, 0x80
	s_addc_u32 s101, s69, 0
	global_load_lds_dwordx4 v202, s[100:101]
	s_mov_b32 m0, s46
	s_nop 0
	global_load_lds_dwordx4 v206, s[100:101]
	s_barrier
	s_waitcnt lgkmcnt(0)
	s_setprio 1
	s_waitcnt lgkmcnt(0)
	v_mfma_f32_16x16x32_bf16 v[72:75], v[132:135], v[148:151], v[72:75]
	v_mfma_f32_16x16x32_bf16 v[68:71], v[140:143], v[148:151], v[68:71]
	v_mfma_f32_16x16x32_bf16 v[64:67], v[132:135], v[156:159], v[64:67]
	v_mfma_f32_16x16x32_bf16 v[60:63], v[140:143], v[156:159], v[60:63]
	v_mfma_f32_16x16x32_bf16 v[56:59], v[132:135], v[164:167], v[56:59]
	v_mfma_f32_16x16x32_bf16 v[52:55], v[140:143], v[164:167], v[52:55]
	v_mfma_f32_16x16x32_bf16 v[48:51], v[132:135], v[172:175], v[48:51]
	v_mfma_f32_16x16x32_bf16 v[44:47], v[140:143], v[172:175], v[44:47]
	v_mfma_f32_16x16x32_bf16 v[72:75], v[136:139], v[152:155], v[72:75]
	v_mfma_f32_16x16x32_bf16 v[68:71], v[144:147], v[152:155], v[68:71]
	v_mfma_f32_16x16x32_bf16 v[64:67], v[136:139], v[160:163], v[64:67]
	v_mfma_f32_16x16x32_bf16 v[60:63], v[144:147], v[160:163], v[60:63]
	v_mfma_f32_16x16x32_bf16 v[56:59], v[136:139], v[168:171], v[56:59]
	v_mfma_f32_16x16x32_bf16 v[52:55], v[144:147], v[168:171], v[52:55]
	v_mfma_f32_16x16x32_bf16 v[48:51], v[136:139], v[176:179], v[48:51]
	v_mfma_f32_16x16x32_bf16 v[44:47], v[144:147], v[176:179], v[44:47]
	s_setprio 0
	s_barrier
	s_add_u32 s44, s66, 0x20080
	s_addc_u32 s45, s67, 0
	s_add_i32 s22, s23, s53
	s_mov_b32 m0, s22
	s_nop 0
	global_load_lds_dwordx4 v204, s[44:45]
	s_add_i32 m0, s22, 0x2000
	s_nop 0
	global_load_lds_dwordx4 v208, s[44:45]
	s_waitcnt vmcnt(6)
	s_barrier
	s_setprio 1
	v_mfma_f32_16x16x32_bf16 v[40:43], v[180:183], v[148:151], v[40:43]
	v_mfma_f32_16x16x32_bf16 v[36:39], v[188:191], v[148:151], v[36:39]
	v_mfma_f32_16x16x32_bf16 v[32:35], v[180:183], v[156:159], v[32:35]
	v_mfma_f32_16x16x32_bf16 v[28:31], v[188:191], v[156:159], v[28:31]
	v_mfma_f32_16x16x32_bf16 v[24:27], v[180:183], v[164:167], v[24:27]
	v_mfma_f32_16x16x32_bf16 v[20:23], v[188:191], v[164:167], v[20:23]
	v_mfma_f32_16x16x32_bf16 v[16:19], v[180:183], v[172:175], v[16:19]
	v_mfma_f32_16x16x32_bf16 v[12:15], v[188:191], v[172:175], v[12:15]
	v_mfma_f32_16x16x32_bf16 v[40:43], v[184:187], v[152:155], v[40:43]
	v_mfma_f32_16x16x32_bf16 v[36:39], v[192:195], v[152:155], v[36:39]
	v_mfma_f32_16x16x32_bf16 v[32:35], v[184:187], v[160:163], v[32:35]
	v_mfma_f32_16x16x32_bf16 v[28:31], v[192:195], v[160:163], v[28:31]
	v_mfma_f32_16x16x32_bf16 v[24:27], v[184:187], v[168:171], v[24:27]
	v_mfma_f32_16x16x32_bf16 v[20:23], v[192:195], v[168:171], v[20:23]
	v_mfma_f32_16x16x32_bf16 v[16:19], v[184:187], v[176:179], v[16:19]
	v_mfma_f32_16x16x32_bf16 v[12:15], v[192:195], v[176:179], v[12:15]
	s_setprio 0
	s_add_i32 vcc_lo, vcc_lo, 2
	s_add_u32 s59, s59, 0x100
	s_addc_u32 s97, s97, 0
	s_cmp_gt_u32 vcc_lo, 5
	s_mov_b64 s[44:45], s[64:65]
	s_barrier
	s_cbranch_scc0 .LBB0_263
	s_lshl_b32 s22, s33, 8
	v_mov_b32_e32 v0, v240
	v_mov_b32_e32 v2, v239
	s_add_i32 s22, s22, s51
	s_nop 0
	v_add_u32_e32 v214, s22, v2
	s_lshl_b32 s22, s42, 8
	s_or_b32 s22, s22, s76
	v_lshl_add_u32 v2, v0, 3, s22
	v_ashrrev_i32_e32 v3, 31, v2
	v_mad_i64_i32 v[132:133], s[42:43], v214, s1, v[2:3]
	v_lshl_add_u64 v[134:135], v[132:133], 1, s[56:57]
	global_load_dwordx4 v[192:195], v[134:135], off
	s_cmp_eq_u32 s48, 0
	s_cselect_b64 s[42:43], -1, 0
	s_cmp_lg_u32 s48, 0
	s_cselect_b64 s[64:65], -1, 0
	s_and_b64 vcc, exec, s[64:65]
	s_cbranch_vccnz .LBB0_266
	v_lshl_add_u64 v[136:137], v[132:133], 1, s[54:55]
	global_load_dwordx4 v[160:163], v[136:137], off

; #define PG8_STAGE(bufoff, gbase, voff) do { _Pragma("unroll") for (int _i = 0; _i < 2; ++_i) \
;         __builtin_amdgcn_global_load_lds((const unsigned*)((const char*)(gbase) + (voff)[_i]), (LAS unsigned*)(lds + (bufoff) + ldsw + _i * 8192), 16, 0, 0); } while (0)
; #define PG8_LDA(dst, b, h) do { _Pragma("unroll") for (int m = 0; m < 4; ++m) _Pragma("unroll") for (int k = 0; k < 2; ++k) dst[m][k] = *(const LAS bf16x8*)(lds + PG8_SA(b, h) + aoff + m * 2048 + k * 1024); } while (0)
; #define PG8_LDB(dst, b, h) do { _Pragma("unroll") for (int n = 0; n < 2; ++n) _Pragma("unroll") for (int k = 0; k < 2; ++k) dst[n][k] = *(const LAS bf16x8*)(lds + PG8_SB(b, h) + boff + n * 2048 + k * 1024); } while (0)
; #define PG8_MMA(ai, bj, At, Bt) do { __builtin_amdgcn_s_setprio(1); _Pragma("unroll") for (int m = 0; m < 4; ++m) _Pragma("unroll") for (int n = 0; n < 2; ++n) _Pragma("unroll") for (int k = 0; k < 2; ++k) \
;         acc[ai][bj][m][n] = __builtin_amdgcn_mfma_f32_16x16x32_bf16(Bt[n][k], At[m][k], acc[ai][bj][m][n], 0, 0, 0); __builtin_amdgcn_s_setprio(0); } while (0)
; #define PG8_WAIT_V(n) asm volatile("s_waitcnt vmcnt(" #n ")" ::: "memory")
; #define PG8_WAIT_L(n) asm volatile("s_waitcnt lgkmcnt(" #n ")" ::: "memory")
; #define PG8_BAR __builtin_amdgcn_s_barrier()
; template <class Epi>
; __device__ __forceinline__ void gemm_phase(LAS unsigned char* lds, const Gemm g, const StaticOrder& S, const Epi& E) {
;     ...
;         for (int t = 0; t < nt; t += 2) {
;             const bool last = (t == nt - 2);
;             const char* a1 = cA + (size_t)(t + 1) * kstep;
;             const char* a2 = last ? nA : cA + (size_t)(t + 2) * kstep; const char* b2 = last ? nB : cB + (size_t)(t + 2) * kstep;
;             const char* a3 = a2 + kstep; const char* b3 = b2 + kstep;
;             PG8_LDB(B0, 0, 0); PG8_SCHED; PG8_LDA(At, 0, 0); PG8_STAGE(PG8_SA(1, 1), a1 + hA, voffA);
;             PG8_WAIT_L(8); PG8_BAR; PG8_WAIT_L(0); PG8_MMA(0, 0, At, B0); PG8_BAR; PG8_SCHED;
;             PG8_LDB(B1, 0, 1); PG8_STAGE(PG8_SB(0, 0), b2, voffB);
;             PG8_BAR; PG8_WAIT_L(0); PG8_MMA(0, 1, At, B1); PG8_BAR;
;             PG8_LDA(At, 0, 1); PG8_STAGE(PG8_SA(0, 0), a2, voffA);
;             PG8_BAR; PG8_WAIT_L(0); PG8_MMA(1, 0, At, B0); PG8_BAR; PG8_SCHED;
;             PG8_STAGE(PG8_SB(0, 1), b2 + hB, voffB);
;             PG8_WAIT_V(6); PG8_BAR; PG8_MMA(1, 1, At, B1); PG8_BAR;
.LBB0_387:
	s_add_u32 s42, s60, 0x100
	s_addc_u32 s43, s61, 0
	s_add_i32 s22, 0, 0x10000
	v_add_u32_e32 v62, s22, v204
	ds_read_b128 v[38:41], v62
	ds_read_b128 v[46:49], v62 offset:1024
	ds_read_b128 v[54:57], v62 offset:2048
	ds_read_b128 v[62:65], v62 offset:3072
	s_cmp_eq_u32 s97, 4
	s_cselect_b32 s65, s57, s43
	s_cselect_b32 s64, s56, s42
	s_cselect_b32 s63, s49, s55
	s_cselect_b32 s62, s50, s51
	s_add_i32 m0, s68, 0xc000
	ds_read_b128 v[122:125], v205
	ds_read_b128 v[130:133], v205 offset:1024
	ds_read_b128 v[146:149], v205 offset:2048
	ds_read_b128 v[150:153], v205 offset:3072
	ds_read_b128 v[158:161], v205 offset:4096
	ds_read_b128 v[166:169], v205 offset:5120
	ds_read_b128 v[170:173], v205 offset:6144
	ds_read_b128 v[184:187], v205 offset:7168
	global_load_lds_dwordx4 v180, s[60:61]
	s_add_i32 m0, s68, 0xe000
	s_nop 0
	global_load_lds_dwordx4 v182, s[60:61]
	s_waitcnt lgkmcnt(8)
	s_barrier
	s_waitcnt lgkmcnt(0)
	s_setprio 1
	s_waitcnt lgkmcnt(0)
	v_mfma_f32_16x16x32_bf16 v[162:165], v[38:41], v[122:125], v[162:165]
	v_mfma_f32_16x16x32_bf16 v[154:157], v[54:57], v[122:125], v[154:157]
	v_mfma_f32_16x16x32_bf16 v[134:137], v[38:41], v[146:149], v[134:137]
	v_mfma_f32_16x16x32_bf16 v[126:129], v[54:57], v[146:149], v[126:129]
	v_mfma_f32_16x16x32_bf16 v[110:113], v[38:41], v[158:161], v[110:113]
	v_mfma_f32_16x16x32_bf16 v[106:109], v[54:57], v[158:161], v[106:109]
	v_mfma_f32_16x16x32_bf16 v[94:97], v[38:41], v[170:173], v[94:97]
	v_mfma_f32_16x16x32_bf16 v[90:93], v[54:57], v[170:173], v[90:93]
	v_mfma_f32_16x16x32_bf16 v[162:165], v[46:49], v[130:133], v[162:165]
	v_mfma_f32_16x16x32_bf16 v[154:157], v[62:65], v[130:133], v[154:157]
	v_mfma_f32_16x16x32_bf16 v[134:137], v[46:49], v[150:153], v[134:137]
	v_mfma_f32_16x16x32_bf16 v[126:129], v[62:65], v[150:153], v[126:129]
	v_mfma_f32_16x16x32_bf16 v[110:113], v[46:49], v[166:169], v[110:113]
	v_mfma_f32_16x16x32_bf16 v[106:109], v[62:65], v[166:169], v[106:109]
	v_mfma_f32_16x16x32_bf16 v[94:97], v[46:49], v[184:187], v[94:97]
	v_mfma_f32_16x16x32_bf16 v[90:93], v[62:65], v[184:187], v[90:93]
	s_setprio 0
	s_barrier
	s_add_i32 s23, 0, 0x14000
	s_add_i32 s22, s22, s67
	v_add_u32_e32 v210, s23, v204
	s_mov_b32 m0, s22
	ds_read_b128 v[188:191], v210
	ds_read_b128 v[192:195], v210 offset:1024
	ds_read_b128 v[206:209], v210 offset:2048
	ds_read_b128 v[210:213], v210 offset:3072
	global_load_lds_dwordx4 v0, s[62:63]
	s_add_i32 m0, s22, 0x2000
	s_nop 0
	global_load_lds_dwordx4 v178, s[62:63]
	s_barrier
	s_waitcnt lgkmcnt(0)
	s_setprio 1
	s_waitcnt lgkmcnt(0)
	v_mfma_f32_16x16x32_bf16 v[142:145], v[188:191], v[122:125], v[142:145]
	v_mfma_f32_16x16x32_bf16 v[118:121], v[188:191], v[146:149], v[118:121]
	v_mfma_f32_16x16x32_bf16 v[114:117], v[206:209], v[146:149], v[114:117]
	v_mfma_f32_16x16x32_bf16 v[102:105], v[188:191], v[158:161], v[102:105]
	v_mfma_f32_16x16x32_bf16 v[98:101], v[206:209], v[158:161], v[98:101]
	v_mfma_f32_16x16x32_bf16 v[86:89], v[188:191], v[170:173], v[86:89]
	v_mfma_f32_16x16x32_bf16 v[82:85], v[206:209], v[170:173], v[82:85]
	v_mfma_f32_16x16x32_bf16 v[142:145], v[192:195], v[130:133], v[142:145]
	v_mfma_f32_16x16x32_bf16 v[122:125], v[206:209], v[122:125], v[138:141]
	v_mfma_f32_16x16x32_bf16 v[118:121], v[192:195], v[150:153], v[118:121]
	v_mfma_f32_16x16x32_bf16 v[114:117], v[210:213], v[150:153], v[114:117]
	v_mfma_f32_16x16x32_bf16 v[102:105], v[192:195], v[166:169], v[102:105]
	v_mfma_f32_16x16x32_bf16 v[98:101], v[210:213], v[166:169], v[98:101]
	v_mfma_f32_16x16x32_bf16 v[86:89], v[192:195], v[184:187], v[86:89]
	v_mfma_f32_16x16x32_bf16 v[82:85], v[210:213], v[184:187], v[82:85]
	v_mfma_f32_16x16x32_bf16 v[122:125], v[210:213], v[130:133], v[122:125]
	s_setprio 0
	s_mov_b32 m0, s68
	s_barrier
	ds_read_b128 v[130:133], v205 offset:16384
	ds_read_b128 v[138:141], v205 offset:17408
	ds_read_b128 v[146:149], v205 offset:18432
	ds_read_b128 v[150:153], v205 offset:19456
	ds_read_b128 v[158:161], v205 offset:20480
	ds_read_b128 v[166:169], v205 offset:21504
	ds_read_b128 v[170:173], v205 offset:22528
	ds_read_b128 v[184:187], v205 offset:23552
	global_load_lds_dwordx4 v174, s[64:65]
	s_mov_b32 m0, s69
	s_nop 0
	global_load_lds_dwordx4 v176, s[64:65]
	s_barrier
	s_waitcnt lgkmcnt(0)
	s_setprio 1
	s_waitcnt lgkmcnt(0)
	v_mfma_f32_16x16x32_bf16 v[78:81], v[38:41], v[130:133], v[78:81]
	v_mfma_f32_16x16x32_bf16 v[74:77], v[54:57], v[130:133], v[74:77]
	v_mfma_f32_16x16x32_bf16 v[58:61], v[38:41], v[146:149], v[58:61]
	v_mfma_f32_16x16x32_bf16 v[50:53], v[54:57], v[146:149], v[50:53]
	v_mfma_f32_16x16x32_bf16 v[30:33], v[38:41], v[158:161], v[30:33]
	v_mfma_f32_16x16x32_bf16 v[26:29], v[54:57], v[158:161], v[26:29]
	v_mfma_f32_16x16x32_bf16 v[14:17], v[38:41], v[170:173], v[14:17]
	v_mfma_f32_16x16x32_bf16 v[10:13], v[54:57], v[170:173], v[10:13]
	v_mfma_f32_16x16x32_bf16 v[78:81], v[46:49], v[138:141], v[78:81]
	v_mfma_f32_16x16x32_bf16 v[74:77], v[62:65], v[138:141], v[74:77]
	v_mfma_f32_16x16x32_bf16 v[58:61], v[46:49], v[150:153], v[58:61]
	v_mfma_f32_16x16x32_bf16 v[50:53], v[62:65], v[150:153], v[50:53]
	v_mfma_f32_16x16x32_bf16 v[30:33], v[46:49], v[166:169], v[30:33]
	v_mfma_f32_16x16x32_bf16 v[26:29], v[62:65], v[166:169], v[26:29]
	v_mfma_f32_16x16x32_bf16 v[14:17], v[46:49], v[184:187], v[14:17]
	v_mfma_f32_16x16x32_bf16 v[10:13], v[62:65], v[184:187], v[10:13]
	s_setprio 0
	s_barrier
	s_add_u32 s60, s62, 0x20000
	s_addc_u32 s61, s63, 0
	s_add_i32 s22, s23, s67
	s_mov_b32 m0, s22
	s_nop 0
	global_load_lds_dwordx4 v0, s[60:61]
	s_add_i32 m0, s22, 0x2000
	s_nop 0
	global_load_lds_dwordx4 v178, s[60:61]
	s_waitcnt vmcnt(6)
	s_barrier
; #define PG8_STAGE(bufoff, gbase, voff) do { _Pragma("unroll") for (int _i = 0; _i < 2; ++_i) \
;         __builtin_amdgcn_global_load_lds((const unsigned*)((const char*)(gbase) + (voff)[_i]), (LAS unsigned*)(lds + (bufoff) + ldsw + _i * 8192), 16, 0, 0); } while (0)
; #define PG8_LDA(dst, b, h) do { _Pragma("unroll") for (int m = 0; m < 4; ++m) _Pragma("unroll") for (int k = 0; k < 2; ++k) dst[m][k] = *(const LAS bf16x8*)(lds + PG8_SA(b, h) + aoff + m * 2048 + k * 1024); } while (0)
; #define PG8_LDB(dst, b, h) do { _Pragma("unroll") for (int n = 0; n < 2; ++n) _Pragma("unroll") for (int k = 0; k < 2; ++k) dst[n][k] = *(const LAS bf16x8*)(lds + PG8_SB(b, h) + boff + n * 2048 + k * 1024); } while (0)
; #define PG8_MMA(ai, bj, At, Bt) do { __builtin_amdgcn_s_setprio(1); _Pragma("unroll") for (int m = 0; m < 4; ++m) _Pragma("unroll") for (int n = 0; n < 2; ++n) _Pragma("unroll") for (int k = 0; k < 2; ++k) \
;         acc[ai][bj][m][n] = __builtin_amdgcn_mfma_f32_16x16x32_bf16(Bt[n][k], At[m][k], acc[ai][bj][m][n], 0, 0, 0); __builtin_amdgcn_s_setprio(0); } while (0)
; #define PG8_WAIT_V(n) asm volatile("s_waitcnt vmcnt(" #n ")" ::: "memory")
; #define PG8_WAIT_L(n) asm volatile("s_waitcnt lgkmcnt(" #n ")" ::: "memory")
; #define PG8_BAR __builtin_amdgcn_s_barrier()
; #define PG8_SCHED __builtin_amdgcn_sched_barrier(0)
; template <class Epi>
; __device__ __forceinline__ void gemm_phase(LAS unsigned char* lds, const Gemm g, const StaticOrder& S, const Epi& E) {
;     ...
;             PG8_WAIT_V(6); PG8_BAR; PG8_MMA(1, 1, At, B1); PG8_BAR;
;             PG8_LDB(B0, 1, 0); PG8_SCHED; PG8_LDA(At, 1, 0); PG8_STAGE(PG8_SA(0, 1), a2 + hA, voffA);
;             PG8_WAIT_L(8); PG8_BAR; PG8_WAIT_L(0); PG8_MMA(0, 0, At, B0); PG8_BAR; PG8_SCHED;
;             PG8_LDB(B1, 1, 1); PG8_STAGE(PG8_SB(1, 0), b3, voffB);
;             PG8_BAR; PG8_WAIT_L(0); PG8_MMA(0, 1, At, B1); PG8_BAR;
;             PG8_LDA(At, 1, 1); PG8_STAGE(PG8_SA(1, 0), a3, voffA);
;             PG8_BAR; PG8_WAIT_L(0); PG8_MMA(1, 0, At, B0); PG8_BAR; PG8_SCHED;
;             PG8_STAGE(PG8_SB(1, 1), b3 + hB, voffB);
	s_setprio 1
	v_mfma_f32_16x16x32_bf16 v[42:45], v[188:191], v[146:149], v[42:45]
	v_mfma_f32_16x16x32_bf16 v[34:37], v[206:209], v[146:149], v[34:37]
	v_mfma_f32_16x16x32_bf16 v[22:25], v[188:191], v[158:161], v[22:25]
	v_mfma_f32_16x16x32_bf16 v[18:21], v[206:209], v[158:161], v[18:21]
	v_mfma_f32_16x16x32_bf16 v[6:9], v[188:191], v[170:173], v[6:9]
	v_mfma_f32_16x16x32_bf16 v[2:5], v[206:209], v[170:173], v[2:5]
	v_mfma_f32_16x16x32_bf16 v[38:41], v[188:191], v[130:133], v[70:73]
	v_mfma_f32_16x16x32_bf16 v[46:49], v[206:209], v[130:133], v[66:69]
	v_mfma_f32_16x16x32_bf16 v[42:45], v[192:195], v[150:153], v[42:45]
	v_mfma_f32_16x16x32_bf16 v[34:37], v[210:213], v[150:153], v[34:37]
	v_mfma_f32_16x16x32_bf16 v[22:25], v[192:195], v[166:169], v[22:25]
	v_mfma_f32_16x16x32_bf16 v[18:21], v[210:213], v[166:169], v[18:21]
	v_mfma_f32_16x16x32_bf16 v[6:9], v[192:195], v[184:187], v[6:9]
	v_mfma_f32_16x16x32_bf16 v[2:5], v[210:213], v[184:187], v[2:5]
	v_mfma_f32_16x16x32_bf16 v[38:41], v[192:195], v[138:141], v[38:41]
	v_mfma_f32_16x16x32_bf16 v[46:49], v[210:213], v[138:141], v[46:49]
	s_setprio 0
	s_add_i32 s22, 0, 0x18000
	v_add_u32_e32 v70, s22, v204
	s_barrier
	ds_read_b128 v[54:57], v70
	ds_read_b128 v[62:65], v70 offset:1024
	ds_read_b128 v[66:69], v70 offset:2048
	ds_read_b128 v[70:73], v70 offset:3072
	s_add_u32 s60, s64, 0x110000
	s_addc_u32 s61, s65, 0
	s_mov_b32 m0, s70
	ds_read_b128 v[130:133], v205 offset:32768
	ds_read_b128 v[138:141], v205 offset:33792
	ds_read_b128 v[146:149], v205 offset:34816
	ds_read_b128 v[150:153], v205 offset:35840
	ds_read_b128 v[158:161], v205 offset:36864
	ds_read_b128 v[166:169], v205 offset:37888
	ds_read_b128 v[170:173], v205 offset:38912
	ds_read_b128 v[184:187], v205 offset:39936
	global_load_lds_dwordx4 v174, s[60:61]
	s_mov_b32 m0, s71
	s_nop 0
	global_load_lds_dwordx4 v176, s[60:61]
	s_waitcnt lgkmcnt(8)
	s_barrier
	s_waitcnt lgkmcnt(0)
	s_setprio 1
	s_waitcnt lgkmcnt(0)
	v_mfma_f32_16x16x32_bf16 v[162:165], v[54:57], v[130:133], v[162:165]
	v_mfma_f32_16x16x32_bf16 v[154:157], v[66:69], v[130:133], v[154:157]
	v_mfma_f32_16x16x32_bf16 v[134:137], v[54:57], v[146:149], v[134:137]
	v_mfma_f32_16x16x32_bf16 v[126:129], v[66:69], v[146:149], v[126:129]
	v_mfma_f32_16x16x32_bf16 v[110:113], v[54:57], v[158:161], v[110:113]
	v_mfma_f32_16x16x32_bf16 v[106:109], v[66:69], v[158:161], v[106:109]
	v_mfma_f32_16x16x32_bf16 v[94:97], v[54:57], v[170:173], v[94:97]
	v_mfma_f32_16x16x32_bf16 v[90:93], v[66:69], v[170:173], v[90:93]
	v_mfma_f32_16x16x32_bf16 v[162:165], v[62:65], v[138:141], v[162:165]
	v_mfma_f32_16x16x32_bf16 v[154:157], v[70:73], v[138:141], v[154:157]
	v_mfma_f32_16x16x32_bf16 v[134:137], v[62:65], v[150:153], v[134:137]
	v_mfma_f32_16x16x32_bf16 v[126:129], v[70:73], v[150:153], v[126:129]
	v_mfma_f32_16x16x32_bf16 v[110:113], v[62:65], v[166:169], v[110:113]
	v_mfma_f32_16x16x32_bf16 v[106:109], v[70:73], v[166:169], v[106:109]
	v_mfma_f32_16x16x32_bf16 v[94:97], v[62:65], v[184:187], v[94:97]
	v_mfma_f32_16x16x32_bf16 v[90:93], v[70:73], v[184:187], v[90:93]
	s_setprio 0
	s_barrier
	s_add_i32 s23, 0, 0x1c000
	s_add_i32 s22, s22, s67
	v_add_u32_e32 v210, s23, v204
	s_mov_b32 m0, s22
	ds_read_b128 v[188:191], v210
	ds_read_b128 v[192:195], v210 offset:1024
	ds_read_b128 v[206:209], v210 offset:2048
	ds_read_b128 v[210:213], v210 offset:3072
	s_add_u32 s100, s62, 0x80
	s_addc_u32 s101, s63, 0
	global_load_lds_dwordx4 v0, s[100:101]
	s_add_i32 m0, s22, 0x2000
	s_nop 0
	global_load_lds_dwordx4 v178, s[100:101]
	s_barrier
	s_waitcnt lgkmcnt(0)
	s_setprio 1
	s_waitcnt lgkmcnt(0)
	v_mfma_f32_16x16x32_bf16 v[142:145], v[188:191], v[130:133], v[142:145]
	v_mfma_f32_16x16x32_bf16 v[122:125], v[206:209], v[130:133], v[122:125]
	v_mfma_f32_16x16x32_bf16 v[118:121], v[188:191], v[146:149], v[118:121]
	v_mfma_f32_16x16x32_bf16 v[114:117], v[206:209], v[146:149], v[114:117]
	v_mfma_f32_16x16x32_bf16 v[102:105], v[188:191], v[158:161], v[102:105]
	v_mfma_f32_16x16x32_bf16 v[98:101], v[206:209], v[158:161], v[98:101]
	v_mfma_f32_16x16x32_bf16 v[86:89], v[188:191], v[170:173], v[86:89]
	v_mfma_f32_16x16x32_bf16 v[82:85], v[206:209], v[170:173], v[82:85]
	v_mfma_f32_16x16x32_bf16 v[142:145], v[192:195], v[138:141], v[142:145]
	v_mfma_f32_16x16x32_bf16 v[138:141], v[210:213], v[138:141], v[122:125]
	v_mfma_f32_16x16x32_bf16 v[118:121], v[192:195], v[150:153], v[118:121]
	v_mfma_f32_16x16x32_bf16 v[114:117], v[210:213], v[150:153], v[114:117]
	v_mfma_f32_16x16x32_bf16 v[102:105], v[192:195], v[166:169], v[102:105]
	v_mfma_f32_16x16x32_bf16 v[98:101], v[210:213], v[166:169], v[98:101]
	v_mfma_f32_16x16x32_bf16 v[86:89], v[192:195], v[184:187], v[86:89]
	v_mfma_f32_16x16x32_bf16 v[82:85], v[210:213], v[184:187], v[82:85]
	s_setprio 0
	s_mov_b32 m0, s75
	s_barrier
	ds_read_b128 v[122:125], v205 offset:49152
	ds_read_b128 v[130:133], v205 offset:50176
	ds_read_b128 v[146:149], v205 offset:51200
	ds_read_b128 v[150:153], v205 offset:52224
	ds_read_b128 v[158:161], v205 offset:53248
	ds_read_b128 v[166:169], v205 offset:54272
	ds_read_b128 v[170:173], v205 offset:55296
	ds_read_b128 v[184:187], v205 offset:56320
	s_add_u32 s100, s64, 0x80
	s_addc_u32 s101, s65, 0
	global_load_lds_dwordx4 v174, s[100:101]
	s_mov_b32 m0, s76
	s_nop 0
	global_load_lds_dwordx4 v176, s[100:101]
	s_barrier
; #define PG8_STAGE(bufoff, gbase, voff) do { _Pragma("unroll") for (int _i = 0; _i < 2; ++_i) \
;         __builtin_amdgcn_global_load_lds((const unsigned*)((const char*)(gbase) + (voff)[_i]), (LAS unsigned*)(lds + (bufoff) + ldsw + _i * 8192), 16, 0, 0); } while (0)
; #define PG8_LDA(dst, b, h) do { _Pragma("unroll") for (int m = 0; m < 4; ++m) _Pragma("unroll") for (int k = 0; k < 2; ++k) dst[m][k] = *(const LAS bf16x8*)(lds + PG8_SA(b, h) + aoff + m * 2048 + k * 1024); } while (0)
; #define PG8_MMA(ai, bj, At, Bt) do { __builtin_amdgcn_s_setprio(1); _Pragma("unroll") for (int m = 0; m < 4; ++m) _Pragma("unroll") for (int n = 0; n < 2; ++n) _Pragma("unroll") for (int k = 0; k < 2; ++k) \
;         acc[ai][bj][m][n] = __builtin_amdgcn_mfma_f32_16x16x32_bf16(Bt[n][k], At[m][k], acc[ai][bj][m][n], 0, 0, 0); __builtin_amdgcn_s_setprio(0); } while (0)
; #define PG8_WAIT_V(n) asm volatile("s_waitcnt vmcnt(" #n ")" ::: "memory")
; #define PG8_WAIT_L(n) asm volatile("s_waitcnt lgkmcnt(" #n ")" ::: "memory")
; template <class Epi>
; __device__ __forceinline__ void gemm_phase(LAS unsigned char* lds, const Gemm g, const StaticOrder& S, const Epi& E) {
;     ...
;             PG8_LDA(At, 1, 1); PG8_STAGE(PG8_SA(1, 0), a3, voffA);
;             PG8_BAR; PG8_WAIT_L(0); PG8_MMA(1, 0, At, B0); PG8_BAR; PG8_SCHED;
;             PG8_STAGE(PG8_SB(1, 1), b3 + hB, voffB);
;             PG8_WAIT_V(6); PG8_BAR; PG8_MMA(1, 1, At, B1); PG8_BAR;
;         }
;         if constexpr (Epi::HAS_PRE) { E(acc, cur, wr, wc, fr, fq, pre); if (has_next) E.pre(pre, nxt, wr, fr); } else E(acc, cur, wr, wc, fr, fq);
;     __device__ __forceinline__ void operator()(const Acc& acc, const Unit& u, int wr, int wc, int fr, int fq) const {
;         asm volatile("" : "+v"(fr), "+v"(fq));
;         const int row0 = u.pm * 256 + wr * 64 + fr, col0 = u.pn * 256 + wc * 32 + 8 * fq;
;         f32x4 bv[2][2];
; #pragma unroll
;         for (int bj = 0; bj < 2; ++bj)
; #pragma unroll
;             for (int n = 0; n < 2; ++n) bv[bj][n] = *(const f32x4*)(bias + col0 + bj * 128 + 4 * n);
; #pragma unroll
;         for (int ai = 0; ai < 2; ++ai) {
;             u32x4 av[4][2];
; #pragma unroll
;             for (int m = 0; m < 4; ++m)
; #pragma unroll
;                 for (int bj = 0; bj < 2; ++bj) av[m][bj] = *(const u32x4*)(proj + (size_t)(row0 + ai * 128 + m * 16) * NPROJ + col0 + bj * 128);
	s_waitcnt lgkmcnt(0)
	s_setprio 1
	s_waitcnt lgkmcnt(0)
	v_mfma_f32_16x16x32_bf16 v[78:81], v[54:57], v[122:125], v[78:81]
	v_mfma_f32_16x16x32_bf16 v[74:77], v[66:69], v[122:125], v[74:77]
	v_mfma_f32_16x16x32_bf16 v[58:61], v[54:57], v[146:149], v[58:61]
	v_mfma_f32_16x16x32_bf16 v[50:53], v[66:69], v[146:149], v[50:53]
	v_mfma_f32_16x16x32_bf16 v[30:33], v[54:57], v[158:161], v[30:33]
	v_mfma_f32_16x16x32_bf16 v[26:29], v[66:69], v[158:161], v[26:29]
	v_mfma_f32_16x16x32_bf16 v[14:17], v[54:57], v[170:173], v[14:17]
	v_mfma_f32_16x16x32_bf16 v[10:13], v[66:69], v[170:173], v[10:13]
	v_mfma_f32_16x16x32_bf16 v[78:81], v[62:65], v[130:133], v[78:81]
	v_mfma_f32_16x16x32_bf16 v[74:77], v[70:73], v[130:133], v[74:77]
	v_mfma_f32_16x16x32_bf16 v[58:61], v[62:65], v[150:153], v[58:61]
	v_mfma_f32_16x16x32_bf16 v[50:53], v[70:73], v[150:153], v[50:53]
	v_mfma_f32_16x16x32_bf16 v[30:33], v[62:65], v[166:169], v[30:33]
	v_mfma_f32_16x16x32_bf16 v[26:29], v[70:73], v[166:169], v[26:29]
	v_mfma_f32_16x16x32_bf16 v[14:17], v[62:65], v[184:187], v[14:17]
	v_mfma_f32_16x16x32_bf16 v[10:13], v[70:73], v[184:187], v[10:13]
	s_setprio 0
	s_barrier
	s_add_u32 s60, s62, 0x20080
	s_addc_u32 s61, s63, 0
	s_add_i32 s22, s23, s67
	s_mov_b32 m0, s22
	s_nop 0
	global_load_lds_dwordx4 v0, s[60:61]
	s_add_i32 m0, s22, 0x2000
	s_nop 0
	global_load_lds_dwordx4 v178, s[60:61]
	s_waitcnt vmcnt(6)
	s_barrier
	s_setprio 1
	v_mfma_f32_16x16x32_bf16 v[38:41], v[188:191], v[122:125], v[38:41]
	v_mfma_f32_16x16x32_bf16 v[70:73], v[192:195], v[130:133], v[38:41]
	v_mfma_f32_16x16x32_bf16 v[38:41], v[206:209], v[122:125], v[46:49]
	v_mfma_f32_16x16x32_bf16 v[66:69], v[210:213], v[130:133], v[38:41]
	v_mfma_f32_16x16x32_bf16 v[38:41], v[188:191], v[146:149], v[42:45]
	v_mfma_f32_16x16x32_bf16 v[34:37], v[206:209], v[146:149], v[34:37]
	v_mfma_f32_16x16x32_bf16 v[22:25], v[188:191], v[158:161], v[22:25]
	v_mfma_f32_16x16x32_bf16 v[18:21], v[206:209], v[158:161], v[18:21]
	v_mfma_f32_16x16x32_bf16 v[6:9], v[188:191], v[170:173], v[6:9]
	v_mfma_f32_16x16x32_bf16 v[2:5], v[206:209], v[170:173], v[2:5]
	v_mfma_f32_16x16x32_bf16 v[42:45], v[192:195], v[150:153], v[38:41]
	v_mfma_f32_16x16x32_bf16 v[34:37], v[210:213], v[150:153], v[34:37]
	v_mfma_f32_16x16x32_bf16 v[22:25], v[192:195], v[166:169], v[22:25]
	v_mfma_f32_16x16x32_bf16 v[18:21], v[210:213], v[166:169], v[18:21]
	v_mfma_f32_16x16x32_bf16 v[6:9], v[192:195], v[184:187], v[6:9]
	v_mfma_f32_16x16x32_bf16 v[2:5], v[210:213], v[184:187], v[2:5]
	s_setprio 0
	s_add_i32 s97, s97, 2
	s_add_u32 s51, s51, 0x100
	s_addc_u32 s55, s55, 0
	s_cmp_gt_u32 s97, 5
	s_mov_b64 s[60:61], s[42:43]
	s_barrier
	s_cbranch_scc0 .LBB0_387
	s_lshl_b32 s23, s48, 8
	v_mov_b32_e32 v38, v203
	v_mov_b32_e32 v124, v202
	s_or_b32 s23, s23, s74
	s_lshl_b32 s22, s33, 8
	v_lshl_add_u32 v122, v38, 3, s23
	v_ashrrev_i32_e32 v123, 31, v122
	v_lshl_add_u64 v[46:47], v[122:123], 2, s[2:3]
	global_load_dwordx4 v[54:57], v[46:47], off offset:16
	global_load_dwordx4 v[62:65], v[46:47], off
	global_load_dwordx4 v[38:41], v[46:47], off offset:528
	s_nop 0
	global_load_dwordx4 v[46:49], v[46:47], off offset:512
	s_add_i32 s22, s22, s30
	v_lshlrev_b64 v[184:185], 1, v[122:123]
	v_add_u32_e32 v206, s22, v124
	v_lshl_add_u64 v[188:189], s[20:21], 0, v[184:185]
	v_mad_i64_i32 v[122:123], s[42:43], v206, s96, v[188:189]
	global_load_dwordx4 v[192:195], v[122:123], off
	global_load_dwordx4 v[170:173], v[122:123], off offset:256
	v_add_u32_e32 v209, 16, v206
	v_mad_i64_i32 v[122:123], s[42:43], v209, s96, v[188:189]
	global_load_dwordx4 v[166:169], v[122:123], off
	global_load_dwordx4 v[158:161], v[122:123], off offset:256
	v_add_u32_e32 v208, 32, v206
	v_mad_i64_i32 v[122:123], s[42:43], v208, s96, v[188:189]
	global_load_dwordx4 v[150:153], v[122:123], off
	global_load_dwordx4 v[146:149], v[122:123], off offset:256
	v_add_u32_e32 v207, 48, v206
	v_mad_i64_i32 v[122:123], s[42:43], v207, s96, v[188:189]
	global_load_dwordx4 v[130:133], v[122:123], off
	s_nop 0
	global_load_dwordx4 v[122:125], v[122:123], off offset:256
	v_mov_b64_e32 v[186:187], s[20:21]
	v_mad_i64_i32 v[190:191], s[42:43], v206, s96, v[186:187]
	v_lshl_add_u64 v[190:191], v[190:191], 0, v[184:185]
	s_and_b64 vcc, exec, s[40:41]
	s_mov_b32 s48, s54
	s_mov_b32 s33, s47
	s_mov_b64 s[62:63], s[58:59]
	s_mov_b64 s[60:61], s[56:57]
	s_waitcnt vmcnt(0)
; __device__ __forceinline__ u32x4 pack8(const f32x4 a, const f32x4 b) { u32x4 w; w.x = cvt_pk_bf16(a[0], a[1]); w.y = cvt_pk_bf16(a[2], a[3]); w.z = cvt_pk_bf16(b[0], b[1]); w.w = cvt_pk_bf16(b[2], b[3]); return w; }
; __device__ __forceinline__ void unpack8(const u32x4 w, f32x4& a, f32x4& b) { a = (f32x4){bflo(w.x), bfhi(w.x), bflo(w.y), bfhi(w.y)}; b = (f32x4){bflo(w.z), bfhi(w.z), bflo(w.w), bfhi(w.w)}; }
; __device__ __forceinline__ f32x4 sig4(const f32x4 v) { return (f32x4){sigmoidf_(v[0]), sigmoidf_(v[1]), sigmoidf_(v[2]), sigmoidf_(v[3])}; }
;     __device__ __forceinline__ void operator()(const Acc& acc, const Unit& u, int wr, int wc, int fr, int fq) const {
;     ...
;             for (int m = 0; m < 4; ++m) { bf16_t* rowp = proj + (size_t)(row0 + ai * 128 + m * 16) * NPROJ + col0;
; #pragma unroll
;                 for (int bj = 0; bj < 2; ++bj) { f32x4 a0, a1; unpack8(av[m][bj], a0, a1);
;                     const f32x4 o0 = a0 * sig4(acc[ai][bj][m][0] + bv[bj][0]), o1 = a1 * sig4(acc[ai][bj][m][1] + bv[bj][1]);
;                     *(u32x4*)(rowp + C_GLU + bj * 128) = pack8(o0, o1); } } }
	v_pk_add_f32 v[156:157], v[156:157], v[56:57]
	v_pk_add_f32 v[164:165], v[164:165], v[64:65]
	v_pk_add_f32 v[162:163], v[162:163], v[62:63]
	v_pk_add_f32 v[154:155], v[154:155], v[54:55]
	v_mul_f32_e32 v162, 0xbfb8aa3b, v162
	v_mul_f32_e32 v163, 0xbfb8aa3b, v163
	v_mul_f32_e32 v164, 0xbfb8aa3b, v164
	v_mul_f32_e32 v165, 0xbfb8aa3b, v165
	v_mul_f32_e32 v154, 0xbfb8aa3b, v154
	v_mul_f32_e32 v155, 0xbfb8aa3b, v155
	v_mul_f32_e32 v156, 0xbfb8aa3b, v156
	v_mul_f32_e32 v157, 0xbfb8aa3b, v157
	v_exp_f32_e32 v162, v162
	v_exp_f32_e32 v163, v163
	v_exp_f32_e32 v164, v164
	v_exp_f32_e32 v165, v165
	v_exp_f32_e32 v154, v154
	v_exp_f32_e32 v155, v155
	v_exp_f32_e32 v156, v156
	v_exp_f32_e32 v157, v157
	v_pk_add_f32 v[144:145], v[144:145], v[48:49]
	v_pk_add_f32 v[142:143], v[142:143], v[46:47]
	v_pk_add_f32 v[140:141], v[140:141], v[40:41]
	v_pk_add_f32 v[138:139], v[138:139], v[38:39]
	v_mul_f32_e32 v142, 0xbfb8aa3b, v142
	v_mul_f32_e32 v143, 0xbfb8aa3b, v143
	v_mul_f32_e32 v144, 0xbfb8aa3b, v144
	v_mul_f32_e32 v145, 0xbfb8aa3b, v145
	v_mul_f32_e32 v138, 0xbfb8aa3b, v138
	v_mul_f32_e32 v139, 0xbfb8aa3b, v139
	v_mul_f32_e32 v140, 0xbfb8aa3b, v140
	v_mul_f32_e32 v141, 0xbfb8aa3b, v141
	v_exp_f32_e32 v142, v142
	v_exp_f32_e32 v143, v143
	v_exp_f32_e32 v144, v144
	v_exp_f32_e32 v145, v145
	v_exp_f32_e32 v138, v138
	v_exp_f32_e32 v139, v139
	v_exp_f32_e32 v140, v140
	v_exp_f32_e32 v141, v141
	v_add_f32_e32 v162, 1.0, v162
	v_add_f32_e32 v163, 1.0, v163
	v_add_f32_e32 v164, 1.0, v164
	v_add_f32_e32 v165, 1.0, v165
	v_add_f32_e32 v154, 1.0, v154
	v_add_f32_e32 v155, 1.0, v155
	v_add_f32_e32 v156, 1.0, v156
	v_add_f32_e32 v157, 1.0, v157
	v_pk_add_f32 v[136:137], v[136:137], v[64:65]
	v_pk_add_f32 v[134:135], v[134:135], v[62:63]
	v_pk_add_f32 v[128:129], v[128:129], v[56:57]
	v_pk_add_f32 v[126:127], v[126:127], v[54:55]
	v_rcp_f32_e32 v162, v162
	v_rcp_f32_e32 v163, v163
	v_rcp_f32_e32 v164, v164
	v_rcp_f32_e32 v165, v165
	v_rcp_f32_e32 v154, v154
	v_rcp_f32_e32 v155, v155
	v_rcp_f32_e32 v156, v156
	v_rcp_f32_e32 v157, v157
	v_mul_f32_e32 v134, 0xbfb8aa3b, v134
	v_mul_f32_e32 v135, 0xbfb8aa3b, v135
	v_mul_f32_e32 v136, 0xbfb8aa3b, v136
	v_mul_f32_e32 v137, 0xbfb8aa3b, v137
	v_mul_f32_e32 v126, 0xbfb8aa3b, v126
	v_mul_f32_e32 v127, 0xbfb8aa3b, v127
	v_mul_f32_e32 v128, 0xbfb8aa3b, v128
	v_mul_f32_e32 v129, 0xbfb8aa3b, v129
	v_exp_f32_e32 v134, v134
	v_exp_f32_e32 v135, v135
	v_exp_f32_e32 v136, v136
	v_exp_f32_e32 v137, v137
	v_exp_f32_e32 v126, v126
	v_exp_f32_e32 v127, v127
	v_exp_f32_e32 v128, v128
	v_exp_f32_e32 v129, v129
	v_add_f32_e32 v142, 1.0, v142
	v_add_f32_e32 v143, 1.0, v143
	v_add_f32_e32 v144, 1.0, v144
	v_add_f32_e32 v145, 1.0, v145
	v_add_f32_e32 v138, 1.0, v138
	v_add_f32_e32 v139, 1.0, v139
	v_add_f32_e32 v140, 1.0, v140
	v_add_f32_e32 v141, 1.0, v141
	v_pk_add_f32 v[120:121], v[120:121], v[48:49]
	v_pk_add_f32 v[118:119], v[118:119], v[46:47]
	v_pk_add_f32 v[116:117], v[116:117], v[40:41]
	v_pk_add_f32 v[114:115], v[114:115], v[38:39]
	v_lshlrev_b32_e32 v210, 16, v192
	v_and_b32_e32 v211, 0xffff0000, v192
	v_lshlrev_b32_e32 v212, 16, v193
	v_and_b32_e32 v213, 0xffff0000, v193
	v_lshlrev_b32_e32 v192, 16, v194
	v_and_b32_e32 v193, 0xffff0000, v194
	v_lshlrev_b32_e32 v194, 16, v195
	v_and_b32_e32 v195, 0xffff0000, v195
	v_rcp_f32_e32 v142, v142
	v_rcp_f32_e32 v143, v143
	v_rcp_f32_e32 v144, v144
	v_rcp_f32_e32 v145, v145
	v_rcp_f32_e32 v138, v138
	v_rcp_f32_e32 v139, v139
	v_rcp_f32_e32 v140, v140
	v_rcp_f32_e32 v141, v141
	v_mul_f32_e32 v118, 0xbfb8aa3b, v118
	v_mul_f32_e32 v119, 0xbfb8aa3b, v119
	v_mul_f32_e32 v120, 0xbfb8aa3b, v120
	v_mul_f32_e32 v121, 0xbfb8aa3b, v121
	v_mul_f32_e32 v114, 0xbfb8aa3b, v114
	v_mul_f32_e32 v115, 0xbfb8aa3b, v115
	v_mul_f32_e32 v116, 0xbfb8aa3b, v116
	v_mul_f32_e32 v117, 0xbfb8aa3b, v117
	v_pk_mul_f32 v[164:165], v[164:165], v[212:213]
	v_pk_mul_f32 v[162:163], v[162:163], v[210:211]
	v_pk_mul_f32 v[194:195], v[156:157], v[194:195]
	v_pk_mul_f32 v[156:157], v[154:155], v[192:193]
	v_exp_f32_e32 v118, v118
	v_exp_f32_e32 v119, v119
	v_exp_f32_e32 v120, v120
	v_exp_f32_e32 v121, v121
	v_exp_f32_e32 v114, v114
	v_exp_f32_e32 v115, v115
	v_exp_f32_e32 v116, v116
	v_exp_f32_e32 v117, v117
	v_cvt_pk_bf16_f32 v154, v162, v163
	v_cvt_pk_bf16_f32 v155, v164, v165
	v_cvt_pk_bf16_f32 v156, v156, v157
	v_cvt_pk_bf16_f32 v157, v194, v195
	v_add_f32_e32 v134, 1.0, v134
	v_add_f32_e32 v135, 1.0, v135
	v_add_f32_e32 v136, 1.0, v136
	v_add_f32_e32 v137, 1.0, v137
	v_add_f32_e32 v126, 1.0, v126
	v_add_f32_e32 v127, 1.0, v127
	v_add_f32_e32 v128, 1.0, v128
	v_add_f32_e32 v129, 1.0, v129
	v_pk_add_f32 v[112:113], v[112:113], v[64:65]
	v_pk_add_f32 v[110:111], v[110:111], v[62:63]
	v_pk_add_f32 v[108:109], v[108:109], v[56:57]
	v_pk_add_f32 v[106:107], v[106:107], v[54:55]
	global_store_dwordx4 v[190:191], v[154:157], off offset:1024
	v_lshlrev_b32_e32 v162, 16, v170
	v_and_b32_e32 v163, 0xffff0000, v170
	v_lshlrev_b32_e32 v164, 16, v171
	v_and_b32_e32 v165, 0xffff0000, v171
	v_lshlrev_b32_e32 v154, 16, v172
	v_and_b32_e32 v155, 0xffff0000, v172
	v_lshlrev_b32_e32 v156, 16, v173
	v_and_b32_e32 v157, 0xffff0000, v173
	v_rcp_f32_e32 v134, v134
	v_rcp_f32_e32 v135, v135
	v_rcp_f32_e32 v136, v136
	v_rcp_f32_e32 v137, v137
	v_rcp_f32_e32 v126, v126
	v_rcp_f32_e32 v127, v127
	v_rcp_f32_e32 v128, v128
	v_rcp_f32_e32 v129, v129
	v_mul_f32_e32 v110, 0xbfb8aa3b, v110
	v_mul_f32_e32 v111, 0xbfb8aa3b, v111
	v_mul_f32_e32 v112, 0xbfb8aa3b, v112
	v_mul_f32_e32 v113, 0xbfb8aa3b, v113
	v_mul_f32_e32 v106, 0xbfb8aa3b, v106
	v_mul_f32_e32 v107, 0xbfb8aa3b, v107
	v_mul_f32_e32 v108, 0xbfb8aa3b, v108
	v_mul_f32_e32 v109, 0xbfb8aa3b, v109
; __device__ __forceinline__ u32x4 pack8(const f32x4 a, const f32x4 b) { u32x4 w; w.x = cvt_pk_bf16(a[0], a[1]); w.y = cvt_pk_bf16(a[2], a[3]); w.z = cvt_pk_bf16(b[0], b[1]); w.w = cvt_pk_bf16(b[2], b[3]); return w; }
; __device__ __forceinline__ void unpack8(const u32x4 w, f32x4& a, f32x4& b) { a = (f32x4){bflo(w.x), bfhi(w.x), bflo(w.y), bfhi(w.y)}; b = (f32x4){bflo(w.z), bfhi(w.z), bflo(w.w), bfhi(w.w)}; }
; __device__ __forceinline__ f32x4 sig4(const f32x4 v) { return (f32x4){sigmoidf_(v[0]), sigmoidf_(v[1]), sigmoidf_(v[2]), sigmoidf_(v[3])}; }
;     __device__ __forceinline__ void operator()(const Acc& acc, const Unit& u, int wr, int wc, int fr, int fq) const {
;     ...
;             for (int m = 0; m < 4; ++m) { bf16_t* rowp = proj + (size_t)(row0 + ai * 128 + m * 16) * NPROJ + col0;
; #pragma unroll
;                 for (int bj = 0; bj < 2; ++bj) { f32x4 a0, a1; unpack8(av[m][bj], a0, a1);
;                     const f32x4 o0 = a0 * sig4(acc[ai][bj][m][0] + bv[bj][0]), o1 = a1 * sig4(acc[ai][bj][m][1] + bv[bj][1]);
;                     *(u32x4*)(rowp + C_GLU + bj * 128) = pack8(o0, o1); } } }
	v_pk_mul_f32 v[144:145], v[144:145], v[164:165]
	v_pk_mul_f32 v[142:143], v[142:143], v[162:163]
	v_pk_mul_f32 v[156:157], v[140:141], v[156:157]
	v_pk_mul_f32 v[140:141], v[138:139], v[154:155]
	v_exp_f32_e32 v110, v110
	v_exp_f32_e32 v111, v111
	v_exp_f32_e32 v112, v112
	v_exp_f32_e32 v113, v113
	v_exp_f32_e32 v106, v106
	v_exp_f32_e32 v107, v107
	v_exp_f32_e32 v108, v108
	v_exp_f32_e32 v109, v109
	v_cvt_pk_bf16_f32 v138, v142, v143
	v_cvt_pk_bf16_f32 v139, v144, v145
	v_cvt_pk_bf16_f32 v140, v140, v141
	v_cvt_pk_bf16_f32 v141, v156, v157
	v_add_f32_e32 v118, 1.0, v118
	v_add_f32_e32 v119, 1.0, v119
	v_add_f32_e32 v120, 1.0, v120
	v_add_f32_e32 v121, 1.0, v121
	v_add_f32_e32 v114, 1.0, v114
	v_add_f32_e32 v115, 1.0, v115
	v_add_f32_e32 v116, 1.0, v116
	v_add_f32_e32 v117, 1.0, v117
	v_pk_add_f32 v[104:105], v[104:105], v[48:49]
	v_pk_add_f32 v[102:103], v[102:103], v[46:47]
	v_pk_add_f32 v[100:101], v[100:101], v[40:41]
	v_pk_add_f32 v[98:99], v[98:99], v[38:39]
	global_store_dwordx4 v[190:191], v[138:141], off offset:1280
	v_lshlrev_b32_e32 v142, 16, v167
	v_and_b32_e32 v143, 0xffff0000, v167
	v_lshlrev_b32_e32 v140, 16, v166
	v_and_b32_e32 v141, 0xffff0000, v166
	v_lshlrev_b32_e32 v144, 16, v168
	v_and_b32_e32 v145, 0xffff0000, v168
	v_lshlrev_b32_e32 v154, 16, v169
	v_and_b32_e32 v155, 0xffff0000, v169
	v_rcp_f32_e32 v118, v118
	v_rcp_f32_e32 v119, v119
	v_rcp_f32_e32 v120, v120
	v_rcp_f32_e32 v121, v121
	v_rcp_f32_e32 v114, v114
	v_rcp_f32_e32 v115, v115
	v_rcp_f32_e32 v116, v116
	v_rcp_f32_e32 v117, v117
	v_mul_f32_e32 v102, 0xbfb8aa3b, v102
	v_mul_f32_e32 v103, 0xbfb8aa3b, v103
	v_mul_f32_e32 v104, 0xbfb8aa3b, v104
	v_mul_f32_e32 v105, 0xbfb8aa3b, v105
	v_mul_f32_e32 v98, 0xbfb8aa3b, v98
	v_mul_f32_e32 v99, 0xbfb8aa3b, v99
	v_mul_f32_e32 v100, 0xbfb8aa3b, v100
	v_mul_f32_e32 v101, 0xbfb8aa3b, v101
	v_mad_i64_i32 v[138:139], s[42:43], v209, s96, v[186:187]
	v_pk_mul_f32 v[136:137], v[136:137], v[142:143]
	v_pk_mul_f32 v[134:135], v[134:135], v[140:141]
	v_pk_mul_f32 v[140:141], v[128:129], v[154:155]
	v_pk_mul_f32 v[128:129], v[126:127], v[144:145]
	v_exp_f32_e32 v102, v102
	v_exp_f32_e32 v103, v103
	v_exp_f32_e32 v104, v104
	v_exp_f32_e32 v105, v105
	v_exp_f32_e32 v98, v98
	v_exp_f32_e32 v99, v99
	v_exp_f32_e32 v100, v100
	v_exp_f32_e32 v101, v101
	v_lshl_add_u64 v[138:139], v[138:139], 0, v[184:185]
	v_cvt_pk_bf16_f32 v126, v134, v135
	v_cvt_pk_bf16_f32 v127, v136, v137
	v_cvt_pk_bf16_f32 v128, v128, v129
	v_cvt_pk_bf16_f32 v129, v140, v141
	v_add_f32_e32 v110, 1.0, v110
	v_add_f32_e32 v111, 1.0, v111
	v_add_f32_e32 v112, 1.0, v112
	v_add_f32_e32 v113, 1.0, v113
	v_add_f32_e32 v106, 1.0, v106
	v_add_f32_e32 v107, 1.0, v107
	v_add_f32_e32 v108, 1.0, v108
	v_add_f32_e32 v109, 1.0, v109
	v_pk_add_f32 v[96:97], v[96:97], v[64:65]
	v_pk_add_f32 v[94:95], v[94:95], v[62:63]
	v_pk_add_f32 v[92:93], v[92:93], v[56:57]
	v_pk_add_f32 v[90:91], v[90:91], v[54:55]
	global_store_dwordx4 v[138:139], v[126:129], off offset:1024
	v_lshlrev_b32_e32 v134, 16, v160
	v_and_b32_e32 v135, 0xffff0000, v160
	v_lshlrev_b32_e32 v126, 16, v158
	v_and_b32_e32 v127, 0xffff0000, v158
	v_lshlrev_b32_e32 v128, 16, v159
	v_and_b32_e32 v129, 0xffff0000, v159
	v_lshlrev_b32_e32 v136, 16, v161
	v_and_b32_e32 v137, 0xffff0000, v161
	v_rcp_f32_e32 v110, v110
	v_rcp_f32_e32 v111, v111
	v_rcp_f32_e32 v112, v112
	v_rcp_f32_e32 v113, v113
	v_rcp_f32_e32 v106, v106
	v_rcp_f32_e32 v107, v107
	v_rcp_f32_e32 v108, v108
	v_rcp_f32_e32 v109, v109
	v_mul_f32_e32 v94, 0xbfb8aa3b, v94
	v_mul_f32_e32 v95, 0xbfb8aa3b, v95
	v_mul_f32_e32 v96, 0xbfb8aa3b, v96
	v_mul_f32_e32 v97, 0xbfb8aa3b, v97
	v_mul_f32_e32 v90, 0xbfb8aa3b, v90
	v_mul_f32_e32 v91, 0xbfb8aa3b, v91
	v_mul_f32_e32 v92, 0xbfb8aa3b, v92
	v_mul_f32_e32 v93, 0xbfb8aa3b, v93
	v_pk_mul_f32 v[120:121], v[120:121], v[128:129]
	v_pk_mul_f32 v[118:119], v[118:119], v[126:127]
	v_pk_mul_f32 v[126:127], v[116:117], v[136:137]
	v_pk_mul_f32 v[116:117], v[114:115], v[134:135]
	v_exp_f32_e32 v94, v94
	v_exp_f32_e32 v95, v95
	v_exp_f32_e32 v96, v96
	v_exp_f32_e32 v97, v97
	v_exp_f32_e32 v90, v90
	v_exp_f32_e32 v91, v91
	v_exp_f32_e32 v92, v92
	v_exp_f32_e32 v93, v93
	v_cvt_pk_bf16_f32 v114, v118, v119
	v_cvt_pk_bf16_f32 v115, v120, v121
	v_cvt_pk_bf16_f32 v116, v116, v117
	v_cvt_pk_bf16_f32 v117, v126, v127
	v_add_f32_e32 v102, 1.0, v102
	v_add_f32_e32 v103, 1.0, v103
	v_add_f32_e32 v104, 1.0, v104
	v_add_f32_e32 v105, 1.0, v105
	v_add_f32_e32 v98, 1.0, v98
	v_add_f32_e32 v99, 1.0, v99
	v_add_f32_e32 v100, 1.0, v100
	v_add_f32_e32 v101, 1.0, v101
	v_pk_add_f32 v[88:89], v[88:89], v[48:49]
	v_pk_add_f32 v[86:87], v[86:87], v[46:47]
	v_pk_add_f32 v[84:85], v[84:85], v[40:41]
	v_pk_add_f32 v[82:83], v[82:83], v[38:39]
	global_store_dwordx4 v[138:139], v[114:117], off offset:1280
	v_lshlrev_b32_e32 v118, 16, v151
	v_and_b32_e32 v119, 0xffff0000, v151
	v_lshlrev_b32_e32 v116, 16, v150
	v_and_b32_e32 v117, 0xffff0000, v150
	v_lshlrev_b32_e32 v120, 16, v152
	v_and_b32_e32 v121, 0xffff0000, v152
	v_lshlrev_b32_e32 v126, 16, v153
	v_and_b32_e32 v127, 0xffff0000, v153
	v_rcp_f32_e32 v102, v102
	v_rcp_f32_e32 v103, v103
	v_rcp_f32_e32 v104, v104
	v_rcp_f32_e32 v105, v105
	v_rcp_f32_e32 v98, v98
	v_rcp_f32_e32 v99, v99
	v_rcp_f32_e32 v100, v100
	v_rcp_f32_e32 v101, v101
	v_mul_f32_e32 v86, 0xbfb8aa3b, v86
	v_mul_f32_e32 v87, 0xbfb8aa3b, v87
	v_mul_f32_e32 v88, 0xbfb8aa3b, v88
	v_mul_f32_e32 v89, 0xbfb8aa3b, v89
	v_mul_f32_e32 v82, 0xbfb8aa3b, v82
	v_mul_f32_e32 v83, 0xbfb8aa3b, v83
	v_mul_f32_e32 v84, 0xbfb8aa3b, v84
	v_mul_f32_e32 v85, 0xbfb8aa3b, v85
	v_mad_i64_i32 v[114:115], s[42:43], v208, s96, v[186:187]
	v_pk_mul_f32 v[112:113], v[112:113], v[118:119]
; __device__ __forceinline__ u32x4 pack8(const f32x4 a, const f32x4 b) { u32x4 w; w.x = cvt_pk_bf16(a[0], a[1]); w.y = cvt_pk_bf16(a[2], a[3]); w.z = cvt_pk_bf16(b[0], b[1]); w.w = cvt_pk_bf16(b[2], b[3]); return w; }
; __device__ __forceinline__ void unpack8(const u32x4 w, f32x4& a, f32x4& b) { a = (f32x4){bflo(w.x), bfhi(w.x), bflo(w.y), bfhi(w.y)}; b = (f32x4){bflo(w.z), bfhi(w.z), bflo(w.w), bfhi(w.w)}; }
; __device__ __forceinline__ f32x4 sig4(const f32x4 v) { return (f32x4){sigmoidf_(v[0]), sigmoidf_(v[1]), sigmoidf_(v[2]), sigmoidf_(v[3])}; }
;     __device__ __forceinline__ void operator()(const Acc& acc, const Unit& u, int wr, int wc, int fr, int fq) const {
;     ...
;         for (int ai = 0; ai < 2; ++ai) {
;             u32x4 av[4][2];
; #pragma unroll
;             for (int m = 0; m < 4; ++m)
; #pragma unroll
;                 for (int bj = 0; bj < 2; ++bj) av[m][bj] = *(const u32x4*)(proj + (size_t)(row0 + ai * 128 + m * 16) * NPROJ + col0 + bj * 128);
; #pragma unroll
;             for (int m = 0; m < 4; ++m) { bf16_t* rowp = proj + (size_t)(row0 + ai * 128 + m * 16) * NPROJ + col0;
; #pragma unroll
;                 for (int bj = 0; bj < 2; ++bj) { f32x4 a0, a1; unpack8(av[m][bj], a0, a1);
;                     const f32x4 o0 = a0 * sig4(acc[ai][bj][m][0] + bv[bj][0]), o1 = a1 * sig4(acc[ai][bj][m][1] + bv[bj][1]);
;                     *(u32x4*)(rowp + C_GLU + bj * 128) = pack8(o0, o1); } } }
	v_pk_mul_f32 v[110:111], v[110:111], v[116:117]
	v_pk_mul_f32 v[116:117], v[108:109], v[126:127]
	v_pk_mul_f32 v[108:109], v[106:107], v[120:121]
	v_exp_f32_e32 v86, v86
	v_exp_f32_e32 v87, v87
	v_exp_f32_e32 v88, v88
	v_exp_f32_e32 v89, v89
	v_exp_f32_e32 v82, v82
	v_exp_f32_e32 v83, v83
	v_exp_f32_e32 v84, v84
	v_exp_f32_e32 v85, v85
	v_lshl_add_u64 v[114:115], v[114:115], 0, v[184:185]
	v_cvt_pk_bf16_f32 v106, v110, v111
	v_cvt_pk_bf16_f32 v107, v112, v113
	v_cvt_pk_bf16_f32 v108, v108, v109
	v_cvt_pk_bf16_f32 v109, v116, v117
	v_add_f32_e32 v94, 1.0, v94
	v_add_f32_e32 v95, 1.0, v95
	v_add_f32_e32 v96, 1.0, v96
	v_add_f32_e32 v97, 1.0, v97
	v_add_f32_e32 v90, 1.0, v90
	v_add_f32_e32 v91, 1.0, v91
	v_add_f32_e32 v92, 1.0, v92
	v_add_f32_e32 v93, 1.0, v93
	global_store_dwordx4 v[114:115], v[106:109], off offset:1024
	v_lshlrev_b32_e32 v110, 16, v148
	v_and_b32_e32 v111, 0xffff0000, v148
	v_lshlrev_b32_e32 v106, 16, v146
	v_and_b32_e32 v107, 0xffff0000, v146
	v_lshlrev_b32_e32 v108, 16, v147
	v_and_b32_e32 v109, 0xffff0000, v147
	v_lshlrev_b32_e32 v112, 16, v149
	v_and_b32_e32 v113, 0xffff0000, v149
	v_rcp_f32_e32 v94, v94
	v_rcp_f32_e32 v95, v95
	v_rcp_f32_e32 v96, v96
	v_rcp_f32_e32 v97, v97
	v_rcp_f32_e32 v90, v90
	v_rcp_f32_e32 v91, v91
	v_rcp_f32_e32 v92, v92
	v_rcp_f32_e32 v93, v93
	v_pk_mul_f32 v[104:105], v[104:105], v[108:109]
	v_pk_mul_f32 v[102:103], v[102:103], v[106:107]
	v_pk_mul_f32 v[106:107], v[100:101], v[112:113]
	v_pk_mul_f32 v[100:101], v[98:99], v[110:111]
	v_cvt_pk_bf16_f32 v98, v102, v103
	v_cvt_pk_bf16_f32 v99, v104, v105
	v_cvt_pk_bf16_f32 v100, v100, v101
	v_cvt_pk_bf16_f32 v101, v106, v107
	v_add_f32_e32 v86, 1.0, v86
	v_add_f32_e32 v87, 1.0, v87
	v_add_f32_e32 v88, 1.0, v88
	v_add_f32_e32 v89, 1.0, v89
	v_add_f32_e32 v82, 1.0, v82
	v_add_f32_e32 v83, 1.0, v83
	v_add_f32_e32 v84, 1.0, v84
	v_add_f32_e32 v85, 1.0, v85
	global_store_dwordx4 v[114:115], v[98:101], off offset:1280
	v_lshlrev_b32_e32 v102, 16, v131
	v_and_b32_e32 v103, 0xffff0000, v131
	v_lshlrev_b32_e32 v100, 16, v130
	v_and_b32_e32 v101, 0xffff0000, v130
	v_lshlrev_b32_e32 v104, 16, v132
	v_and_b32_e32 v105, 0xffff0000, v132
	v_lshlrev_b32_e32 v106, 16, v133
	v_and_b32_e32 v107, 0xffff0000, v133
	v_rcp_f32_e32 v86, v86
	v_rcp_f32_e32 v87, v87
	v_rcp_f32_e32 v88, v88
	v_rcp_f32_e32 v89, v89
	v_rcp_f32_e32 v82, v82
	v_rcp_f32_e32 v83, v83
	v_rcp_f32_e32 v84, v84
	v_rcp_f32_e32 v85, v85
	v_mad_i64_i32 v[98:99], s[42:43], v207, s96, v[186:187]
	v_pk_mul_f32 v[96:97], v[96:97], v[102:103]
	v_pk_mul_f32 v[94:95], v[94:95], v[100:101]
	v_pk_mul_f32 v[100:101], v[92:93], v[106:107]
	v_pk_mul_f32 v[92:93], v[90:91], v[104:105]
	v_lshl_add_u64 v[98:99], v[98:99], 0, v[184:185]
	v_cvt_pk_bf16_f32 v90, v94, v95
	v_cvt_pk_bf16_f32 v91, v96, v97
	v_cvt_pk_bf16_f32 v92, v92, v93
	v_cvt_pk_bf16_f32 v93, v100, v101
	global_store_dwordx4 v[98:99], v[90:93], off offset:1024
	v_lshlrev_b32_e32 v94, 16, v124
	v_and_b32_e32 v95, 0xffff0000, v124
	v_lshlrev_b32_e32 v90, 16, v122
	v_and_b32_e32 v91, 0xffff0000, v122
	v_lshlrev_b32_e32 v92, 16, v123
	v_and_b32_e32 v93, 0xffff0000, v123
	v_lshlrev_b32_e32 v96, 16, v125
	v_and_b32_e32 v97, 0xffff0000, v125
	v_pk_mul_f32 v[88:89], v[88:89], v[92:93]
	v_pk_mul_f32 v[86:87], v[86:87], v[90:91]
	v_pk_mul_f32 v[90:91], v[84:85], v[96:97]
	v_pk_mul_f32 v[84:85], v[82:83], v[94:95]
	v_cvt_pk_bf16_f32 v82, v86, v87
	v_cvt_pk_bf16_f32 v83, v88, v89
	v_cvt_pk_bf16_f32 v84, v84, v85
	v_cvt_pk_bf16_f32 v85, v90, v91
	v_add_u32_e32 v110, 0x80, v206
	global_store_dwordx4 v[98:99], v[82:85], off offset:1280
	v_add_u32_e32 v122, 0x90, v206
	v_add_u32_e32 v113, 0xa0, v206
	v_mad_i64_i32 v[82:83], s[42:43], v110, s96, v[188:189]
	global_load_dwordx4 v[106:109], v[82:83], off
	global_load_dwordx4 v[114:117], v[82:83], off offset:256
	v_mad_i64_i32 v[82:83], s[42:43], v122, s96, v[188:189]
	global_load_dwordx4 v[102:105], v[82:83], off
	global_load_dwordx4 v[98:101], v[82:83], off offset:256
	v_mad_i64_i32 v[82:83], s[42:43], v113, s96, v[188:189]
	global_load_dwordx4 v[94:97], v[82:83], off
	global_load_dwordx4 v[90:93], v[82:83], off offset:256
	v_add_u32_e32 v112, 0xb0, v206
	v_mad_i64_i32 v[82:83], s[42:43], v112, s96, v[188:189]
	global_load_dwordx4 v[86:89], v[82:83], off
	s_nop 0
	global_load_dwordx4 v[82:85], v[82:83], off offset:256
	v_pk_add_f32 v[80:81], v[80:81], v[64:65]
	v_pk_add_f32 v[78:79], v[78:79], v[62:63]
	v_pk_add_f32 v[76:77], v[76:77], v[56:57]
	v_pk_add_f32 v[74:75], v[74:75], v[54:55]
	v_mul_f32_e32 v78, 0xbfb8aa3b, v78
	v_mul_f32_e32 v79, 0xbfb8aa3b, v79
	v_mul_f32_e32 v80, 0xbfb8aa3b, v80
	v_mul_f32_e32 v81, 0xbfb8aa3b, v81
	v_mul_f32_e32 v74, 0xbfb8aa3b, v74
	v_mul_f32_e32 v75, 0xbfb8aa3b, v75
	v_mul_f32_e32 v76, 0xbfb8aa3b, v76
	v_mul_f32_e32 v77, 0xbfb8aa3b, v77
	v_exp_f32_e32 v78, v78
	v_exp_f32_e32 v79, v79
	v_exp_f32_e32 v80, v80
	v_exp_f32_e32 v81, v81
	v_exp_f32_e32 v74, v74
	v_exp_f32_e32 v75, v75
	v_exp_f32_e32 v76, v76
	v_exp_f32_e32 v77, v77
	v_pk_add_f32 v[72:73], v[72:73], v[48:49]
	v_pk_add_f32 v[70:71], v[70:71], v[46:47]
	v_pk_add_f32 v[68:69], v[68:69], v[40:41]
	v_pk_add_f32 v[66:67], v[66:67], v[38:39]
	v_mul_f32_e32 v70, 0xbfb8aa3b, v70
	v_mul_f32_e32 v71, 0xbfb8aa3b, v71
	v_mul_f32_e32 v72, 0xbfb8aa3b, v72
	v_mul_f32_e32 v73, 0xbfb8aa3b, v73
	v_mul_f32_e32 v66, 0xbfb8aa3b, v66
	v_mul_f32_e32 v67, 0xbfb8aa3b, v67
	v_mul_f32_e32 v68, 0xbfb8aa3b, v68
	v_mul_f32_e32 v69, 0xbfb8aa3b, v69
	v_exp_f32_e32 v70, v70
	v_exp_f32_e32 v71, v71
	v_exp_f32_e32 v72, v72
	v_exp_f32_e32 v73, v73
	v_exp_f32_e32 v66, v66
	v_exp_f32_e32 v67, v67
	v_exp_f32_e32 v68, v68
	v_exp_f32_e32 v69, v69
	v_add_f32_e32 v78, 1.0, v78
; __device__ __forceinline__ u32x4 pack8(const f32x4 a, const f32x4 b) { u32x4 w; w.x = cvt_pk_bf16(a[0], a[1]); w.y = cvt_pk_bf16(a[2], a[3]); w.z = cvt_pk_bf16(b[0], b[1]); w.w = cvt_pk_bf16(b[2], b[3]); return w; }
; __device__ __forceinline__ void unpack8(const u32x4 w, f32x4& a, f32x4& b) { a = (f32x4){bflo(w.x), bfhi(w.x), bflo(w.y), bfhi(w.y)}; b = (f32x4){bflo(w.z), bfhi(w.z), bflo(w.w), bfhi(w.w)}; }
; __device__ __forceinline__ f32x4 sig4(const f32x4 v) { return (f32x4){sigmoidf_(v[0]), sigmoidf_(v[1]), sigmoidf_(v[2]), sigmoidf_(v[3])}; }
;     __device__ __forceinline__ void operator()(const Acc& acc, const Unit& u, int wr, int wc, int fr, int fq) const {
;     ...
;             for (int m = 0; m < 4; ++m) { bf16_t* rowp = proj + (size_t)(row0 + ai * 128 + m * 16) * NPROJ + col0;
; #pragma unroll
;                 for (int bj = 0; bj < 2; ++bj) { f32x4 a0, a1; unpack8(av[m][bj], a0, a1);
;                     const f32x4 o0 = a0 * sig4(acc[ai][bj][m][0] + bv[bj][0]), o1 = a1 * sig4(acc[ai][bj][m][1] + bv[bj][1]);
;                     *(u32x4*)(rowp + C_GLU + bj * 128) = pack8(o0, o1); } } }
	v_add_f32_e32 v79, 1.0, v79
	v_add_f32_e32 v80, 1.0, v80
	v_add_f32_e32 v81, 1.0, v81
	v_add_f32_e32 v74, 1.0, v74
	v_add_f32_e32 v75, 1.0, v75
	v_add_f32_e32 v76, 1.0, v76
	v_add_f32_e32 v77, 1.0, v77
	v_pk_add_f32 v[60:61], v[60:61], v[64:65]
	v_pk_add_f32 v[58:59], v[58:59], v[62:63]
	v_pk_add_f32 v[52:53], v[52:53], v[56:57]
	v_pk_add_f32 v[50:51], v[50:51], v[54:55]
	v_rcp_f32_e32 v78, v78
	v_rcp_f32_e32 v79, v79
	v_rcp_f32_e32 v80, v80
	v_rcp_f32_e32 v81, v81
	v_rcp_f32_e32 v74, v74
	v_rcp_f32_e32 v75, v75
	v_rcp_f32_e32 v76, v76
	v_rcp_f32_e32 v77, v77
	v_mul_f32_e32 v58, 0xbfb8aa3b, v58
	v_mul_f32_e32 v59, 0xbfb8aa3b, v59
	v_mul_f32_e32 v60, 0xbfb8aa3b, v60
	v_mul_f32_e32 v61, 0xbfb8aa3b, v61
	v_mul_f32_e32 v50, 0xbfb8aa3b, v50
	v_mul_f32_e32 v51, 0xbfb8aa3b, v51
	v_mul_f32_e32 v52, 0xbfb8aa3b, v52
	v_mul_f32_e32 v53, 0xbfb8aa3b, v53
	v_exp_f32_e32 v58, v58
	v_exp_f32_e32 v59, v59
	v_exp_f32_e32 v60, v60
	v_exp_f32_e32 v61, v61
	v_exp_f32_e32 v50, v50
	v_exp_f32_e32 v51, v51
	v_exp_f32_e32 v52, v52
	v_exp_f32_e32 v53, v53
	v_add_f32_e32 v70, 1.0, v70
	v_add_f32_e32 v71, 1.0, v71
	v_add_f32_e32 v72, 1.0, v72
	v_add_f32_e32 v73, 1.0, v73
	v_add_f32_e32 v66, 1.0, v66
	v_add_f32_e32 v67, 1.0, v67
	v_add_f32_e32 v68, 1.0, v68
	v_add_f32_e32 v69, 1.0, v69
	v_pk_add_f32 v[44:45], v[44:45], v[48:49]
	v_pk_add_f32 v[42:43], v[42:43], v[46:47]
	v_pk_add_f32 v[36:37], v[36:37], v[40:41]
	v_pk_add_f32 v[34:35], v[34:35], v[38:39]
	s_waitcnt vmcnt(0)
	v_lshlrev_b32_e32 v118, 16, v106
	v_and_b32_e32 v119, 0xffff0000, v106
	v_lshlrev_b32_e32 v106, 16, v107
	v_and_b32_e32 v107, 0xffff0000, v107
	v_lshlrev_b32_e32 v120, 16, v108
	v_and_b32_e32 v121, 0xffff0000, v108
	v_lshlrev_b32_e32 v108, 16, v109
	v_and_b32_e32 v109, 0xffff0000, v109
	v_rcp_f32_e32 v70, v70
	v_rcp_f32_e32 v71, v71
	v_rcp_f32_e32 v72, v72
	v_rcp_f32_e32 v73, v73
	v_rcp_f32_e32 v66, v66
	v_rcp_f32_e32 v67, v67
	v_rcp_f32_e32 v68, v68
	v_rcp_f32_e32 v69, v69
	v_mul_f32_e32 v42, 0xbfb8aa3b, v42
	v_mul_f32_e32 v43, 0xbfb8aa3b, v43
	v_mul_f32_e32 v44, 0xbfb8aa3b, v44
	v_mul_f32_e32 v45, 0xbfb8aa3b, v45
	v_mul_f32_e32 v34, 0xbfb8aa3b, v34
	v_mul_f32_e32 v35, 0xbfb8aa3b, v35
	v_mul_f32_e32 v36, 0xbfb8aa3b, v36
	v_mul_f32_e32 v37, 0xbfb8aa3b, v37
	v_mad_i64_i32 v[110:111], s[42:43], v110, s96, v[186:187]
	v_pk_mul_f32 v[80:81], v[80:81], v[106:107]
	v_pk_mul_f32 v[78:79], v[78:79], v[118:119]
	v_pk_mul_f32 v[106:107], v[76:77], v[108:109]
	v_pk_mul_f32 v[76:77], v[74:75], v[120:121]
	v_exp_f32_e32 v42, v42
	v_exp_f32_e32 v43, v43
	v_exp_f32_e32 v44, v44
	v_exp_f32_e32 v45, v45
	v_exp_f32_e32 v34, v34
	v_exp_f32_e32 v35, v35
	v_exp_f32_e32 v36, v36
	v_exp_f32_e32 v37, v37
	v_lshl_add_u64 v[110:111], v[110:111], 0, v[184:185]
	v_cvt_pk_bf16_f32 v74, v78, v79
	v_cvt_pk_bf16_f32 v75, v80, v81
	v_cvt_pk_bf16_f32 v76, v76, v77
	v_cvt_pk_bf16_f32 v77, v106, v107
	v_add_f32_e32 v58, 1.0, v58
	v_add_f32_e32 v59, 1.0, v59
	v_add_f32_e32 v60, 1.0, v60
	v_add_f32_e32 v61, 1.0, v61
	v_add_f32_e32 v50, 1.0, v50
	v_add_f32_e32 v51, 1.0, v51
	v_add_f32_e32 v52, 1.0, v52
	v_add_f32_e32 v53, 1.0, v53
	v_pk_add_f32 v[32:33], v[32:33], v[64:65]
	v_pk_add_f32 v[30:31], v[30:31], v[62:63]
	v_pk_add_f32 v[28:29], v[28:29], v[56:57]
	v_pk_add_f32 v[26:27], v[26:27], v[54:55]
	global_store_dwordx4 v[110:111], v[74:77], off offset:1024
	v_lshlrev_b32_e32 v78, 16, v116
	v_and_b32_e32 v79, 0xffff0000, v116
	v_lshlrev_b32_e32 v74, 16, v114
	v_and_b32_e32 v75, 0xffff0000, v114
	v_lshlrev_b32_e32 v76, 16, v115
	v_and_b32_e32 v77, 0xffff0000, v115
	v_lshlrev_b32_e32 v80, 16, v117
	v_and_b32_e32 v81, 0xffff0000, v117
	v_rcp_f32_e32 v58, v58
	v_rcp_f32_e32 v59, v59
	v_rcp_f32_e32 v60, v60
	v_rcp_f32_e32 v61, v61
	v_rcp_f32_e32 v50, v50
	v_rcp_f32_e32 v51, v51
	v_rcp_f32_e32 v52, v52
	v_rcp_f32_e32 v53, v53
	v_mul_f32_e32 v30, 0xbfb8aa3b, v30
	v_mul_f32_e32 v31, 0xbfb8aa3b, v31
	v_mul_f32_e32 v32, 0xbfb8aa3b, v32
	v_mul_f32_e32 v33, 0xbfb8aa3b, v33
	v_mul_f32_e32 v26, 0xbfb8aa3b, v26
	v_mul_f32_e32 v27, 0xbfb8aa3b, v27
	v_mul_f32_e32 v28, 0xbfb8aa3b, v28
	v_mul_f32_e32 v29, 0xbfb8aa3b, v29
	v_pk_mul_f32 v[72:73], v[72:73], v[76:77]
	v_pk_mul_f32 v[70:71], v[70:71], v[74:75]
	v_pk_mul_f32 v[74:75], v[68:69], v[80:81]
	v_pk_mul_f32 v[68:69], v[66:67], v[78:79]
	v_exp_f32_e32 v30, v30
	v_exp_f32_e32 v31, v31
	v_exp_f32_e32 v32, v32
	v_exp_f32_e32 v33, v33
	v_exp_f32_e32 v26, v26
	v_exp_f32_e32 v27, v27
	v_exp_f32_e32 v28, v28
	v_exp_f32_e32 v29, v29
	v_cvt_pk_bf16_f32 v66, v70, v71
	v_cvt_pk_bf16_f32 v67, v72, v73
	v_cvt_pk_bf16_f32 v68, v68, v69
	v_cvt_pk_bf16_f32 v69, v74, v75
	v_add_f32_e32 v42, 1.0, v42
	v_add_f32_e32 v43, 1.0, v43
	v_add_f32_e32 v44, 1.0, v44
	v_add_f32_e32 v45, 1.0, v45
	v_add_f32_e32 v34, 1.0, v34
	v_add_f32_e32 v35, 1.0, v35
	v_add_f32_e32 v36, 1.0, v36
	v_add_f32_e32 v37, 1.0, v37
	v_pk_add_f32 v[24:25], v[24:25], v[48:49]
	v_pk_add_f32 v[22:23], v[22:23], v[46:47]
	v_pk_add_f32 v[20:21], v[20:21], v[40:41]
	v_pk_add_f32 v[18:19], v[18:19], v[38:39]
	global_store_dwordx4 v[110:111], v[66:69], off offset:1280
	v_lshlrev_b32_e32 v70, 16, v103
	v_and_b32_e32 v71, 0xffff0000, v103
	v_lshlrev_b32_e32 v68, 16, v102
	v_and_b32_e32 v69, 0xffff0000, v102
	v_lshlrev_b32_e32 v72, 16, v104
	v_and_b32_e32 v73, 0xffff0000, v104
	v_lshlrev_b32_e32 v74, 16, v105
	v_and_b32_e32 v75, 0xffff0000, v105
	v_rcp_f32_e32 v42, v42
	v_rcp_f32_e32 v43, v43
	v_rcp_f32_e32 v44, v44
	v_rcp_f32_e32 v45, v45
	v_rcp_f32_e32 v34, v34
	v_rcp_f32_e32 v35, v35
	v_rcp_f32_e32 v36, v36
	v_rcp_f32_e32 v37, v37
	v_mul_f32_e32 v22, 0xbfb8aa3b, v22
	v_mul_f32_e32 v23, 0xbfb8aa3b, v23
	v_mul_f32_e32 v24, 0xbfb8aa3b, v24
; __device__ __forceinline__ u32x4 pack8(const f32x4 a, const f32x4 b) { u32x4 w; w.x = cvt_pk_bf16(a[0], a[1]); w.y = cvt_pk_bf16(a[2], a[3]); w.z = cvt_pk_bf16(b[0], b[1]); w.w = cvt_pk_bf16(b[2], b[3]); return w; }
; __device__ __forceinline__ void unpack8(const u32x4 w, f32x4& a, f32x4& b) { a = (f32x4){bflo(w.x), bfhi(w.x), bflo(w.y), bfhi(w.y)}; b = (f32x4){bflo(w.z), bfhi(w.z), bflo(w.w), bfhi(w.w)}; }
; __device__ __forceinline__ f32x4 sig4(const f32x4 v) { return (f32x4){sigmoidf_(v[0]), sigmoidf_(v[1]), sigmoidf_(v[2]), sigmoidf_(v[3])}; }
;     __device__ __forceinline__ void operator()(const Acc& acc, const Unit& u, int wr, int wc, int fr, int fq) const {
;     ...
;             for (int m = 0; m < 4; ++m) { bf16_t* rowp = proj + (size_t)(row0 + ai * 128 + m * 16) * NPROJ + col0;
; #pragma unroll
;                 for (int bj = 0; bj < 2; ++bj) { f32x4 a0, a1; unpack8(av[m][bj], a0, a1);
;                     const f32x4 o0 = a0 * sig4(acc[ai][bj][m][0] + bv[bj][0]), o1 = a1 * sig4(acc[ai][bj][m][1] + bv[bj][1]);
;                     *(u32x4*)(rowp + C_GLU + bj * 128) = pack8(o0, o1); } } }
	v_mul_f32_e32 v25, 0xbfb8aa3b, v25
	v_mul_f32_e32 v18, 0xbfb8aa3b, v18
	v_mul_f32_e32 v19, 0xbfb8aa3b, v19
	v_mul_f32_e32 v20, 0xbfb8aa3b, v20
	v_mul_f32_e32 v21, 0xbfb8aa3b, v21
	v_mad_i64_i32 v[66:67], s[42:43], v122, s96, v[186:187]
	v_pk_mul_f32 v[60:61], v[60:61], v[70:71]
	v_pk_mul_f32 v[58:59], v[58:59], v[68:69]
	v_pk_mul_f32 v[68:69], v[52:53], v[74:75]
	v_pk_mul_f32 v[52:53], v[50:51], v[72:73]
	v_exp_f32_e32 v22, v22
	v_exp_f32_e32 v23, v23
	v_exp_f32_e32 v24, v24
	v_exp_f32_e32 v25, v25
	v_exp_f32_e32 v18, v18
	v_exp_f32_e32 v19, v19
	v_exp_f32_e32 v20, v20
	v_exp_f32_e32 v21, v21
	v_lshl_add_u64 v[66:67], v[66:67], 0, v[184:185]
	v_cvt_pk_bf16_f32 v50, v58, v59
	v_cvt_pk_bf16_f32 v51, v60, v61
	v_cvt_pk_bf16_f32 v52, v52, v53
	v_cvt_pk_bf16_f32 v53, v68, v69
	v_add_f32_e32 v30, 1.0, v30
	v_add_f32_e32 v31, 1.0, v31
	v_add_f32_e32 v32, 1.0, v32
	v_add_f32_e32 v33, 1.0, v33
	v_add_f32_e32 v26, 1.0, v26
	v_add_f32_e32 v27, 1.0, v27
	v_add_f32_e32 v28, 1.0, v28
	v_add_f32_e32 v29, 1.0, v29
	v_pk_add_f32 v[16:17], v[16:17], v[64:65]
	v_pk_add_f32 v[14:15], v[14:15], v[62:63]
	v_pk_add_f32 v[12:13], v[12:13], v[56:57]
	v_pk_add_f32 v[10:11], v[10:11], v[54:55]
	global_store_dwordx4 v[66:67], v[50:53], off offset:1024
	v_lshlrev_b32_e32 v58, 16, v100
	v_and_b32_e32 v59, 0xffff0000, v100
	v_lshlrev_b32_e32 v50, 16, v98
	v_and_b32_e32 v51, 0xffff0000, v98
	v_lshlrev_b32_e32 v52, 16, v99
	v_and_b32_e32 v53, 0xffff0000, v99
	v_lshlrev_b32_e32 v60, 16, v101
	v_and_b32_e32 v61, 0xffff0000, v101
	v_rcp_f32_e32 v30, v30
	v_rcp_f32_e32 v31, v31
	v_rcp_f32_e32 v32, v32
	v_rcp_f32_e32 v33, v33
	v_rcp_f32_e32 v26, v26
	v_rcp_f32_e32 v27, v27
	v_rcp_f32_e32 v28, v28
	v_rcp_f32_e32 v29, v29
	v_mul_f32_e32 v14, 0xbfb8aa3b, v14
	v_mul_f32_e32 v15, 0xbfb8aa3b, v15
	v_mul_f32_e32 v16, 0xbfb8aa3b, v16
	v_mul_f32_e32 v17, 0xbfb8aa3b, v17
	v_mul_f32_e32 v10, 0xbfb8aa3b, v10
	v_mul_f32_e32 v11, 0xbfb8aa3b, v11
	v_mul_f32_e32 v12, 0xbfb8aa3b, v12
	v_mul_f32_e32 v13, 0xbfb8aa3b, v13
	v_pk_mul_f32 v[44:45], v[44:45], v[52:53]
	v_pk_mul_f32 v[42:43], v[42:43], v[50:51]
	v_pk_mul_f32 v[50:51], v[36:37], v[60:61]
	v_pk_mul_f32 v[36:37], v[34:35], v[58:59]
	v_exp_f32_e32 v14, v14
	v_exp_f32_e32 v15, v15
	v_exp_f32_e32 v16, v16
	v_exp_f32_e32 v17, v17
	v_exp_f32_e32 v10, v10
	v_exp_f32_e32 v11, v11
	v_exp_f32_e32 v12, v12
	v_exp_f32_e32 v13, v13
	v_cvt_pk_bf16_f32 v34, v42, v43
	v_cvt_pk_bf16_f32 v35, v44, v45
	v_cvt_pk_bf16_f32 v36, v36, v37
	v_cvt_pk_bf16_f32 v37, v50, v51
	v_add_f32_e32 v22, 1.0, v22
	v_add_f32_e32 v23, 1.0, v23
	v_add_f32_e32 v24, 1.0, v24
	v_add_f32_e32 v25, 1.0, v25
	v_add_f32_e32 v18, 1.0, v18
	v_add_f32_e32 v19, 1.0, v19
	v_add_f32_e32 v20, 1.0, v20
	v_add_f32_e32 v21, 1.0, v21
	v_pk_add_f32 v[8:9], v[8:9], v[48:49]
	v_pk_add_f32 v[6:7], v[6:7], v[46:47]
	v_pk_add_f32 v[4:5], v[4:5], v[40:41]
	v_pk_add_f32 v[2:3], v[2:3], v[38:39]
	global_store_dwordx4 v[66:67], v[34:37], off offset:1280
	v_lshlrev_b32_e32 v42, 16, v95
	v_and_b32_e32 v43, 0xffff0000, v95
	v_lshlrev_b32_e32 v36, 16, v94
	v_and_b32_e32 v37, 0xffff0000, v94
	v_lshlrev_b32_e32 v44, 16, v96
	v_and_b32_e32 v45, 0xffff0000, v96
	v_lshlrev_b32_e32 v50, 16, v97
	v_and_b32_e32 v51, 0xffff0000, v97
	v_rcp_f32_e32 v22, v22
	v_rcp_f32_e32 v23, v23
	v_rcp_f32_e32 v24, v24
	v_rcp_f32_e32 v25, v25
	v_rcp_f32_e32 v18, v18
	v_rcp_f32_e32 v19, v19
	v_rcp_f32_e32 v20, v20
	v_rcp_f32_e32 v21, v21
	v_mul_f32_e32 v6, 0xbfb8aa3b, v6
	v_mul_f32_e32 v7, 0xbfb8aa3b, v7
	v_mul_f32_e32 v8, 0xbfb8aa3b, v8
	v_mul_f32_e32 v9, 0xbfb8aa3b, v9
	v_mul_f32_e32 v2, 0xbfb8aa3b, v2
	v_mul_f32_e32 v3, 0xbfb8aa3b, v3
; #define PG8_WAIT_V(n) asm volatile("s_waitcnt vmcnt(" #n ")" ::: "memory")
; #define PG8_BAR __builtin_amdgcn_s_barrier()
; __device__ __forceinline__ u32x4 pack8(const f32x4 a, const f32x4 b) { u32x4 w; w.x = cvt_pk_bf16(a[0], a[1]); w.y = cvt_pk_bf16(a[2], a[3]); w.z = cvt_pk_bf16(b[0], b[1]); w.w = cvt_pk_bf16(b[2], b[3]); return w; }
; __device__ __forceinline__ void unpack8(const u32x4 w, f32x4& a, f32x4& b) { a = (f32x4){bflo(w.x), bfhi(w.x), bflo(w.y), bfhi(w.y)}; b = (f32x4){bflo(w.z), bfhi(w.z), bflo(w.w), bfhi(w.w)}; }
; __device__ __forceinline__ f32x4 sig4(const f32x4 v) { return (f32x4){sigmoidf_(v[0]), sigmoidf_(v[1]), sigmoidf_(v[2]), sigmoidf_(v[3])}; }
; template <class Epi>
; __device__ __forceinline__ void gemm_phase(LAS unsigned char* lds, const Gemm g, const StaticOrder& S, const Epi& E) {
;     ...
;     PG8_WAIT_V(0);
;     if (wr == 0) PG8_BAR;
;     PG8_BAR;
;     __device__ __forceinline__ void operator()(const Acc& acc, const Unit& u, int wr, int wc, int fr, int fq) const {
;     ...
;             for (int m = 0; m < 4; ++m) { bf16_t* rowp = proj + (size_t)(row0 + ai * 128 + m * 16) * NPROJ + col0;
; #pragma unroll
;                 for (int bj = 0; bj < 2; ++bj) { f32x4 a0, a1; unpack8(av[m][bj], a0, a1);
;                     const f32x4 o0 = a0 * sig4(acc[ai][bj][m][0] + bv[bj][0]), o1 = a1 * sig4(acc[ai][bj][m][1] + bv[bj][1]);
;                     *(u32x4*)(rowp + C_GLU + bj * 128) = pack8(o0, o1); } } }
	v_mul_f32_e32 v4, 0xbfb8aa3b, v4
	v_mul_f32_e32 v5, 0xbfb8aa3b, v5
	v_mad_i64_i32 v[34:35], s[42:43], v113, s96, v[186:187]
	v_pk_mul_f32 v[32:33], v[32:33], v[42:43]
	v_pk_mul_f32 v[30:31], v[30:31], v[36:37]
	v_pk_mul_f32 v[36:37], v[28:29], v[50:51]
	v_pk_mul_f32 v[28:29], v[26:27], v[44:45]
	v_exp_f32_e32 v6, v6
	v_exp_f32_e32 v7, v7
	v_exp_f32_e32 v8, v8
	v_exp_f32_e32 v9, v9
	v_exp_f32_e32 v2, v2
	v_exp_f32_e32 v3, v3
	v_exp_f32_e32 v4, v4
	v_exp_f32_e32 v5, v5
	v_lshl_add_u64 v[34:35], v[34:35], 0, v[184:185]
	v_cvt_pk_bf16_f32 v26, v30, v31
	v_cvt_pk_bf16_f32 v27, v32, v33
	v_cvt_pk_bf16_f32 v28, v28, v29
	v_cvt_pk_bf16_f32 v29, v36, v37
	v_add_f32_e32 v14, 1.0, v14
	v_add_f32_e32 v15, 1.0, v15
	v_add_f32_e32 v16, 1.0, v16
	v_add_f32_e32 v17, 1.0, v17
	v_add_f32_e32 v10, 1.0, v10
	v_add_f32_e32 v11, 1.0, v11
	v_add_f32_e32 v12, 1.0, v12
	v_add_f32_e32 v13, 1.0, v13
	global_store_dwordx4 v[34:35], v[26:29], off offset:1024
	v_lshlrev_b32_e32 v30, 16, v92
	v_and_b32_e32 v31, 0xffff0000, v92
	v_lshlrev_b32_e32 v26, 16, v90
	v_and_b32_e32 v27, 0xffff0000, v90
	v_lshlrev_b32_e32 v28, 16, v91
	v_and_b32_e32 v29, 0xffff0000, v91
	v_lshlrev_b32_e32 v32, 16, v93
	v_and_b32_e32 v33, 0xffff0000, v93
	v_rcp_f32_e32 v14, v14
	v_rcp_f32_e32 v15, v15
	v_rcp_f32_e32 v16, v16
	v_rcp_f32_e32 v17, v17
	v_rcp_f32_e32 v10, v10
	v_rcp_f32_e32 v11, v11
	v_rcp_f32_e32 v12, v12
	v_rcp_f32_e32 v13, v13
	v_pk_mul_f32 v[24:25], v[24:25], v[28:29]
	v_pk_mul_f32 v[22:23], v[22:23], v[26:27]
	v_pk_mul_f32 v[26:27], v[20:21], v[32:33]
	v_pk_mul_f32 v[20:21], v[18:19], v[30:31]
	v_cvt_pk_bf16_f32 v18, v22, v23
	v_cvt_pk_bf16_f32 v19, v24, v25
	v_cvt_pk_bf16_f32 v20, v20, v21
	v_cvt_pk_bf16_f32 v21, v26, v27
	v_add_f32_e32 v6, 1.0, v6
	v_add_f32_e32 v7, 1.0, v7
	v_add_f32_e32 v8, 1.0, v8
	v_add_f32_e32 v9, 1.0, v9
	v_add_f32_e32 v2, 1.0, v2
	v_add_f32_e32 v3, 1.0, v3
	v_add_f32_e32 v4, 1.0, v4
	v_add_f32_e32 v5, 1.0, v5
	global_store_dwordx4 v[34:35], v[18:21], off offset:1280
	v_lshlrev_b32_e32 v22, 16, v87
	v_and_b32_e32 v23, 0xffff0000, v87
	v_lshlrev_b32_e32 v20, 16, v86
	v_and_b32_e32 v21, 0xffff0000, v86
	v_lshlrev_b32_e32 v24, 16, v88
	v_and_b32_e32 v25, 0xffff0000, v88
	v_lshlrev_b32_e32 v26, 16, v89
	v_and_b32_e32 v27, 0xffff0000, v89
	v_rcp_f32_e32 v6, v6
	v_rcp_f32_e32 v7, v7
	v_rcp_f32_e32 v8, v8
	v_rcp_f32_e32 v9, v9
	v_rcp_f32_e32 v2, v2
	v_rcp_f32_e32 v3, v3
	v_rcp_f32_e32 v4, v4
	v_rcp_f32_e32 v5, v5
	v_mad_i64_i32 v[18:19], s[42:43], v112, s96, v[186:187]
	v_pk_mul_f32 v[16:17], v[16:17], v[22:23]
	v_pk_mul_f32 v[14:15], v[14:15], v[20:21]
	v_pk_mul_f32 v[20:21], v[12:13], v[26:27]
	v_pk_mul_f32 v[12:13], v[10:11], v[24:25]
	v_lshl_add_u64 v[18:19], v[18:19], 0, v[184:185]
	v_cvt_pk_bf16_f32 v10, v14, v15
	v_cvt_pk_bf16_f32 v11, v16, v17
	v_cvt_pk_bf16_f32 v12, v12, v13
	v_cvt_pk_bf16_f32 v13, v20, v21
	global_store_dwordx4 v[18:19], v[10:13], off offset:1024
	v_lshlrev_b32_e32 v14, 16, v84
	v_and_b32_e32 v15, 0xffff0000, v84
	v_lshlrev_b32_e32 v10, 16, v82
	v_and_b32_e32 v11, 0xffff0000, v82
	v_lshlrev_b32_e32 v12, 16, v83
	v_and_b32_e32 v13, 0xffff0000, v83
	v_lshlrev_b32_e32 v16, 16, v85
	v_and_b32_e32 v17, 0xffff0000, v85
	v_pk_mul_f32 v[8:9], v[8:9], v[12:13]
	v_pk_mul_f32 v[6:7], v[6:7], v[10:11]
	v_pk_mul_f32 v[10:11], v[4:5], v[16:17]
	v_pk_mul_f32 v[4:5], v[2:3], v[14:15]
	v_cvt_pk_bf16_f32 v2, v6, v7
	v_cvt_pk_bf16_f32 v3, v8, v9
	v_cvt_pk_bf16_f32 v4, v4, v5
	v_cvt_pk_bf16_f32 v5, v10, v11
	global_store_dwordx4 v[18:19], v[2:5], off offset:1280
	s_cbranch_vccz .LBB0_378
	s_waitcnt vmcnt(0)
	s_cmpk_gt_u32 s29, 0xff
	s_cbranch_scc1 .LBB0_391
	s_barrier

; #define PG8_STAGE(bufoff, gbase, voff) do { _Pragma("unroll") for (int _i = 0; _i < 2; ++_i) \
;         __builtin_amdgcn_global_load_lds((const unsigned*)((const char*)(gbase) + (voff)[_i]), (LAS unsigned*)(lds + (bufoff) + ldsw + _i * 8192), 16, 0, 0); } while (0)
; #define PG8_LDA(dst, b, h) do { _Pragma("unroll") for (int m = 0; m < 4; ++m) _Pragma("unroll") for (int k = 0; k < 2; ++k) dst[m][k] = *(const LAS bf16x8*)(lds + PG8_SA(b, h) + aoff + m * 2048 + k * 1024); } while (0)
; #define PG8_LDB(dst, b, h) do { _Pragma("unroll") for (int n = 0; n < 2; ++n) _Pragma("unroll") for (int k = 0; k < 2; ++k) dst[n][k] = *(const LAS bf16x8*)(lds + PG8_SB(b, h) + boff + n * 2048 + k * 1024); } while (0)
; #define PG8_MMA(ai, bj, At, Bt) do { __builtin_amdgcn_s_setprio(1); _Pragma("unroll") for (int m = 0; m < 4; ++m) _Pragma("unroll") for (int n = 0; n < 2; ++n) _Pragma("unroll") for (int k = 0; k < 2; ++k) \
;         acc[ai][bj][m][n] = __builtin_amdgcn_mfma_f32_16x16x32_bf16(Bt[n][k], At[m][k], acc[ai][bj][m][n], 0, 0, 0); __builtin_amdgcn_s_setprio(0); } while (0)
; #define PG8_WAIT_V(n) asm volatile("s_waitcnt vmcnt(" #n ")" ::: "memory")
; #define PG8_WAIT_L(n) asm volatile("s_waitcnt lgkmcnt(" #n ")" ::: "memory")
; #define PG8_BAR __builtin_amdgcn_s_barrier()
; template <class Epi>
; __device__ __forceinline__ void gemm_phase(LAS unsigned char* lds, const Gemm g, const StaticOrder& S, const Epi& E) {
;     ...
;         for (int t = 0; t < nt; t += 2) {
;             const bool last = (t == nt - 2);
;             const char* a1 = cA + (size_t)(t + 1) * kstep;
;             const char* a2 = last ? nA : cA + (size_t)(t + 2) * kstep; const char* b2 = last ? nB : cB + (size_t)(t + 2) * kstep;
;             const char* a3 = a2 + kstep; const char* b3 = b2 + kstep;
;             PG8_LDB(B0, 0, 0); PG8_SCHED; PG8_LDA(At, 0, 0); PG8_STAGE(PG8_SA(1, 1), a1 + hA, voffA);
;             PG8_WAIT_L(8); PG8_BAR; PG8_WAIT_L(0); PG8_MMA(0, 0, At, B0); PG8_BAR; PG8_SCHED;
;             PG8_LDB(B1, 0, 1); PG8_STAGE(PG8_SB(0, 0), b2, voffB);
;             PG8_BAR; PG8_WAIT_L(0); PG8_MMA(0, 1, At, B1); PG8_BAR;
;             PG8_LDA(At, 0, 1); PG8_STAGE(PG8_SA(0, 0), a2, voffA);
;             PG8_BAR; PG8_WAIT_L(0); PG8_MMA(1, 0, At, B0); PG8_BAR; PG8_SCHED;
;             PG8_STAGE(PG8_SB(0, 1), b2 + hB, voffB);
;             PG8_WAIT_V(6); PG8_BAR; PG8_MMA(1, 1, At, B1); PG8_BAR;
.LBB0_623:
	s_add_u32 s48, s46, 0xfffc0080
	s_addc_u32 s49, s47, -1
	s_add_i32 s67, 0, 0x10000
	v_add_u32_e32 v151, s67, v143
	ds_read_b128 v[156:159], v151
	ds_read_b128 v[160:163], v151 offset:1024
	ds_read_b128 v[164:167], v151 offset:2048
	ds_read_b128 v[168:171], v151 offset:3072
	s_cmp_eq_u32 s66, 12
	s_cselect_b32 s51, s23, s49
	s_cselect_b32 s50, s62, s48
	s_cselect_b32 s49, s15, s65
	s_cselect_b32 s48, s63, s64
	s_add_i32 m0, s53, 0xc000
	ds_read_b128 v[172:175], v149
	ds_read_b128 v[176:179], v149 offset:1024
	ds_read_b128 v[180:183], v149 offset:2048
	ds_read_b128 v[184:187], v149 offset:3072
	ds_read_b128 v[188:191], v149 offset:4096
	ds_read_b128 v[192:195], v149 offset:5120
	ds_read_b128 v[202:205], v149 offset:6144
	ds_read_b128 v[206:209], v149 offset:7168
	global_load_lds_dwordx4 v144, s[46:47]
	s_add_i32 m0, s53, 0xe000
	s_nop 0
	global_load_lds_dwordx4 v146, s[46:47]
	s_waitcnt lgkmcnt(8)
	s_barrier
	s_waitcnt lgkmcnt(0)
	s_setprio 1
	s_waitcnt lgkmcnt(0)
	v_mfma_f32_16x16x32_bf16 v[126:129], v[156:159], v[172:175], v[126:129]
	v_mfma_f32_16x16x32_bf16 v[122:125], v[164:167], v[172:175], v[122:125]
	v_mfma_f32_16x16x32_bf16 v[118:121], v[156:159], v[180:183], v[118:121]
	v_mfma_f32_16x16x32_bf16 v[110:113], v[164:167], v[180:183], v[110:113]
	v_mfma_f32_16x16x32_bf16 v[102:105], v[156:159], v[188:191], v[102:105]
	v_mfma_f32_16x16x32_bf16 v[94:97], v[164:167], v[188:191], v[94:97]
	v_mfma_f32_16x16x32_bf16 v[86:89], v[156:159], v[202:205], v[86:89]
	v_mfma_f32_16x16x32_bf16 v[78:81], v[164:167], v[202:205], v[78:81]
	v_mfma_f32_16x16x32_bf16 v[126:129], v[160:163], v[176:179], v[126:129]
	v_mfma_f32_16x16x32_bf16 v[122:125], v[168:171], v[176:179], v[122:125]
	v_mfma_f32_16x16x32_bf16 v[118:121], v[160:163], v[184:187], v[118:121]
	v_mfma_f32_16x16x32_bf16 v[110:113], v[168:171], v[184:187], v[110:113]
	v_mfma_f32_16x16x32_bf16 v[102:105], v[160:163], v[192:195], v[102:105]
	v_mfma_f32_16x16x32_bf16 v[94:97], v[168:171], v[192:195], v[94:97]
	v_mfma_f32_16x16x32_bf16 v[86:89], v[160:163], v[206:209], v[86:89]
	v_mfma_f32_16x16x32_bf16 v[78:81], v[168:171], v[206:209], v[78:81]
	s_setprio 0
	s_barrier
	s_add_i32 s70, 0, 0x14000
	s_add_i32 s67, s67, s33
	v_add_u32_e32 v151, s70, v143
	s_mov_b32 m0, s67
	ds_read_b128 v[210:213], v151
	ds_read_b128 v[214:217], v151 offset:1024
	ds_read_b128 v[218:221], v151 offset:2048
	ds_read_b128 v[222:225], v151 offset:3072
	global_load_lds_dwordx4 v0, s[48:49]
	s_add_i32 m0, s67, 0x2000
	s_nop 0
	global_load_lds_dwordx4 v134, s[48:49]
	s_barrier
	s_waitcnt lgkmcnt(0)
	s_setprio 1
	s_waitcnt lgkmcnt(0)
	v_mfma_f32_16x16x32_bf16 v[114:117], v[210:213], v[172:175], v[114:117]
	v_mfma_f32_16x16x32_bf16 v[106:109], v[218:221], v[172:175], v[106:109]
	v_mfma_f32_16x16x32_bf16 v[98:101], v[210:213], v[180:183], v[98:101]
	v_mfma_f32_16x16x32_bf16 v[90:93], v[218:221], v[180:183], v[90:93]
	v_mfma_f32_16x16x32_bf16 v[82:85], v[210:213], v[188:191], v[82:85]
	v_mfma_f32_16x16x32_bf16 v[74:77], v[218:221], v[188:191], v[74:77]
	v_mfma_f32_16x16x32_bf16 v[70:73], v[210:213], v[202:205], v[70:73]
	v_mfma_f32_16x16x32_bf16 v[66:69], v[218:221], v[202:205], v[66:69]
	v_mfma_f32_16x16x32_bf16 v[114:117], v[214:217], v[176:179], v[114:117]
	v_mfma_f32_16x16x32_bf16 v[106:109], v[222:225], v[176:179], v[106:109]
	v_mfma_f32_16x16x32_bf16 v[98:101], v[214:217], v[184:187], v[98:101]
	v_mfma_f32_16x16x32_bf16 v[90:93], v[222:225], v[184:187], v[90:93]
	v_mfma_f32_16x16x32_bf16 v[82:85], v[214:217], v[192:195], v[82:85]
	v_mfma_f32_16x16x32_bf16 v[74:77], v[222:225], v[192:195], v[74:77]
	v_mfma_f32_16x16x32_bf16 v[70:73], v[214:217], v[206:209], v[70:73]
	v_mfma_f32_16x16x32_bf16 v[66:69], v[222:225], v[206:209], v[66:69]
	s_setprio 0
	s_mov_b32 m0, s53
	s_barrier
	ds_read_b128 v[172:175], v149 offset:16384
	ds_read_b128 v[176:179], v149 offset:17408
	ds_read_b128 v[180:183], v149 offset:18432
	ds_read_b128 v[184:187], v149 offset:19456
	ds_read_b128 v[188:191], v149 offset:20480
	ds_read_b128 v[192:195], v149 offset:21504
	ds_read_b128 v[202:205], v149 offset:22528
	ds_read_b128 v[206:209], v149 offset:23552
	global_load_lds_dwordx4 v130, s[50:51]
	s_mov_b32 m0, s54
	s_nop 0
	global_load_lds_dwordx4 v132, s[50:51]
	s_barrier
	s_waitcnt lgkmcnt(0)
	s_setprio 1
	s_waitcnt lgkmcnt(0)
	v_mfma_f32_16x16x32_bf16 v[62:65], v[156:159], v[172:175], v[62:65]
	v_mfma_f32_16x16x32_bf16 v[58:61], v[164:167], v[172:175], v[58:61]
	v_mfma_f32_16x16x32_bf16 v[54:57], v[156:159], v[180:183], v[54:57]
	v_mfma_f32_16x16x32_bf16 v[46:49], v[164:167], v[180:183], v[46:49]
	v_mfma_f32_16x16x32_bf16 v[38:41], v[156:159], v[188:191], v[38:41]
	v_mfma_f32_16x16x32_bf16 v[30:33], v[164:167], v[188:191], v[30:33]
	v_mfma_f32_16x16x32_bf16 v[22:25], v[156:159], v[202:205], v[22:25]
	v_mfma_f32_16x16x32_bf16 v[14:17], v[164:167], v[202:205], v[14:17]
	v_mfma_f32_16x16x32_bf16 v[62:65], v[160:163], v[176:179], v[62:65]
	v_mfma_f32_16x16x32_bf16 v[58:61], v[168:171], v[176:179], v[58:61]
	v_mfma_f32_16x16x32_bf16 v[54:57], v[160:163], v[184:187], v[54:57]
	v_mfma_f32_16x16x32_bf16 v[46:49], v[168:171], v[184:187], v[46:49]
	v_mfma_f32_16x16x32_bf16 v[38:41], v[160:163], v[192:195], v[38:41]
	v_mfma_f32_16x16x32_bf16 v[30:33], v[168:171], v[192:195], v[30:33]
	v_mfma_f32_16x16x32_bf16 v[22:25], v[160:163], v[206:209], v[22:25]
	v_mfma_f32_16x16x32_bf16 v[14:17], v[168:171], v[206:209], v[14:17]
	s_setprio 0
	s_barrier
	s_add_u32 s68, s48, 0x40000
	s_addc_u32 s69, s49, 0
	s_add_i32 s67, s70, s33
	s_mov_b32 m0, s67
	s_nop 0
	global_load_lds_dwordx4 v0, s[68:69]
	s_add_i32 m0, s67, 0x2000
	s_nop 0
	global_load_lds_dwordx4 v134, s[68:69]
	s_waitcnt vmcnt(6)
	s_barrier
; #define PG8_STAGE(bufoff, gbase, voff) do { _Pragma("unroll") for (int _i = 0; _i < 2; ++_i) \
;         __builtin_amdgcn_global_load_lds((const unsigned*)((const char*)(gbase) + (voff)[_i]), (LAS unsigned*)(lds + (bufoff) + ldsw + _i * 8192), 16, 0, 0); } while (0)
; #define PG8_LDA(dst, b, h) do { _Pragma("unroll") for (int m = 0; m < 4; ++m) _Pragma("unroll") for (int k = 0; k < 2; ++k) dst[m][k] = *(const LAS bf16x8*)(lds + PG8_SA(b, h) + aoff + m * 2048 + k * 1024); } while (0)
; #define PG8_LDB(dst, b, h) do { _Pragma("unroll") for (int n = 0; n < 2; ++n) _Pragma("unroll") for (int k = 0; k < 2; ++k) dst[n][k] = *(const LAS bf16x8*)(lds + PG8_SB(b, h) + boff + n * 2048 + k * 1024); } while (0)
; #define PG8_MMA(ai, bj, At, Bt) do { __builtin_amdgcn_s_setprio(1); _Pragma("unroll") for (int m = 0; m < 4; ++m) _Pragma("unroll") for (int n = 0; n < 2; ++n) _Pragma("unroll") for (int k = 0; k < 2; ++k) \
;         acc[ai][bj][m][n] = __builtin_amdgcn_mfma_f32_16x16x32_bf16(Bt[n][k], At[m][k], acc[ai][bj][m][n], 0, 0, 0); __builtin_amdgcn_s_setprio(0); } while (0)
; #define PG8_WAIT_V(n) asm volatile("s_waitcnt vmcnt(" #n ")" ::: "memory")
; #define PG8_WAIT_L(n) asm volatile("s_waitcnt lgkmcnt(" #n ")" ::: "memory")
; #define PG8_BAR __builtin_amdgcn_s_barrier()
; #define PG8_SCHED __builtin_amdgcn_sched_barrier(0)
; template <class Epi>
; __device__ __forceinline__ void gemm_phase(LAS unsigned char* lds, const Gemm g, const StaticOrder& S, const Epi& E) {
;     ...
;             PG8_WAIT_V(6); PG8_BAR; PG8_MMA(1, 1, At, B1); PG8_BAR;
;             PG8_LDB(B0, 1, 0); PG8_SCHED; PG8_LDA(At, 1, 0); PG8_STAGE(PG8_SA(0, 1), a2 + hA, voffA);
;             PG8_WAIT_L(8); PG8_BAR; PG8_WAIT_L(0); PG8_MMA(0, 0, At, B0); PG8_BAR; PG8_SCHED;
;             PG8_LDB(B1, 1, 1); PG8_STAGE(PG8_SB(1, 0), b3, voffB);
;             PG8_BAR; PG8_WAIT_L(0); PG8_MMA(0, 1, At, B1); PG8_BAR;
;             PG8_LDA(At, 1, 1); PG8_STAGE(PG8_SA(1, 0), a3, voffA);
;             PG8_BAR; PG8_WAIT_L(0); PG8_MMA(1, 0, At, B0); PG8_BAR; PG8_SCHED;
;             PG8_STAGE(PG8_SB(1, 1), b3 + hB, voffB);
	s_setprio 1
	v_mfma_f32_16x16x32_bf16 v[50:53], v[210:213], v[172:175], v[50:53]
	v_mfma_f32_16x16x32_bf16 v[42:45], v[218:221], v[172:175], v[42:45]
	v_mfma_f32_16x16x32_bf16 v[34:37], v[210:213], v[180:183], v[34:37]
	v_mfma_f32_16x16x32_bf16 v[26:29], v[218:221], v[180:183], v[26:29]
	v_mfma_f32_16x16x32_bf16 v[18:21], v[210:213], v[188:191], v[18:21]
	v_mfma_f32_16x16x32_bf16 v[10:13], v[218:221], v[188:191], v[10:13]
	v_mfma_f32_16x16x32_bf16 v[6:9], v[210:213], v[202:205], v[6:9]
	v_mfma_f32_16x16x32_bf16 v[2:5], v[218:221], v[202:205], v[2:5]
	v_mfma_f32_16x16x32_bf16 v[50:53], v[214:217], v[176:179], v[50:53]
	v_mfma_f32_16x16x32_bf16 v[42:45], v[222:225], v[176:179], v[42:45]
	v_mfma_f32_16x16x32_bf16 v[34:37], v[214:217], v[184:187], v[34:37]
	v_mfma_f32_16x16x32_bf16 v[26:29], v[222:225], v[184:187], v[26:29]
	v_mfma_f32_16x16x32_bf16 v[18:21], v[214:217], v[192:195], v[18:21]
	v_mfma_f32_16x16x32_bf16 v[10:13], v[222:225], v[192:195], v[10:13]
	v_mfma_f32_16x16x32_bf16 v[6:9], v[214:217], v[206:209], v[6:9]
	v_mfma_f32_16x16x32_bf16 v[2:5], v[222:225], v[206:209], v[2:5]
	s_setprio 0
	s_add_i32 s67, 0, 0x18000
	v_add_u32_e32 v151, s67, v143
	s_barrier
	ds_read_b128 v[156:159], v151
	ds_read_b128 v[160:163], v151 offset:1024
	ds_read_b128 v[164:167], v151 offset:2048
	ds_read_b128 v[168:171], v151 offset:3072
	s_add_u32 s68, s50, 0x40000
	s_addc_u32 s69, s51, 0
	s_mov_b32 m0, s55
	ds_read_b128 v[172:175], v149 offset:32768
	ds_read_b128 v[176:179], v149 offset:33792
	ds_read_b128 v[180:183], v149 offset:34816
	ds_read_b128 v[184:187], v149 offset:35840
	ds_read_b128 v[188:191], v149 offset:36864
	ds_read_b128 v[192:195], v149 offset:37888
	ds_read_b128 v[202:205], v149 offset:38912
	ds_read_b128 v[206:209], v149 offset:39936
	global_load_lds_dwordx4 v130, s[68:69]
	s_mov_b32 m0, s56
	s_nop 0
	global_load_lds_dwordx4 v132, s[68:69]
	s_waitcnt lgkmcnt(8)
	s_barrier
	s_waitcnt lgkmcnt(0)
	s_setprio 1
	s_waitcnt lgkmcnt(0)
	v_mfma_f32_16x16x32_bf16 v[126:129], v[156:159], v[172:175], v[126:129]
	v_mfma_f32_16x16x32_bf16 v[122:125], v[164:167], v[172:175], v[122:125]
	v_mfma_f32_16x16x32_bf16 v[118:121], v[156:159], v[180:183], v[118:121]
	v_mfma_f32_16x16x32_bf16 v[110:113], v[164:167], v[180:183], v[110:113]
	v_mfma_f32_16x16x32_bf16 v[102:105], v[156:159], v[188:191], v[102:105]
	v_mfma_f32_16x16x32_bf16 v[94:97], v[164:167], v[188:191], v[94:97]
	v_mfma_f32_16x16x32_bf16 v[86:89], v[156:159], v[202:205], v[86:89]
	v_mfma_f32_16x16x32_bf16 v[78:81], v[164:167], v[202:205], v[78:81]
	v_mfma_f32_16x16x32_bf16 v[126:129], v[160:163], v[176:179], v[126:129]
	v_mfma_f32_16x16x32_bf16 v[122:125], v[168:171], v[176:179], v[122:125]
	v_mfma_f32_16x16x32_bf16 v[118:121], v[160:163], v[184:187], v[118:121]
	v_mfma_f32_16x16x32_bf16 v[110:113], v[168:171], v[184:187], v[110:113]
	v_mfma_f32_16x16x32_bf16 v[102:105], v[160:163], v[192:195], v[102:105]
	v_mfma_f32_16x16x32_bf16 v[94:97], v[168:171], v[192:195], v[94:97]
	v_mfma_f32_16x16x32_bf16 v[86:89], v[160:163], v[206:209], v[86:89]
	v_mfma_f32_16x16x32_bf16 v[78:81], v[168:171], v[206:209], v[78:81]
	s_setprio 0
	s_barrier
	s_add_i32 s100, 0, 0x1c000
	s_add_i32 s101, s67, s33
	v_add_u32_e32 v151, s100, v143
	s_add_u32 s68, s48, 0x80
	s_addc_u32 s69, s49, 0
	s_mov_b32 m0, s101
	ds_read_b128 v[210:213], v151
	ds_read_b128 v[214:217], v151 offset:1024
	ds_read_b128 v[218:221], v151 offset:2048
	ds_read_b128 v[222:225], v151 offset:3072
	global_load_lds_dwordx4 v0, s[68:69]
	s_add_i32 m0, s101, 0x2000
	s_nop 0
	global_load_lds_dwordx4 v134, s[68:69]
	s_barrier
	s_waitcnt lgkmcnt(0)
	s_setprio 1
	s_waitcnt lgkmcnt(0)
	v_mfma_f32_16x16x32_bf16 v[114:117], v[210:213], v[172:175], v[114:117]
	v_mfma_f32_16x16x32_bf16 v[106:109], v[218:221], v[172:175], v[106:109]
	v_mfma_f32_16x16x32_bf16 v[98:101], v[210:213], v[180:183], v[98:101]
	v_mfma_f32_16x16x32_bf16 v[90:93], v[218:221], v[180:183], v[90:93]
	v_mfma_f32_16x16x32_bf16 v[82:85], v[210:213], v[188:191], v[82:85]
	v_mfma_f32_16x16x32_bf16 v[74:77], v[218:221], v[188:191], v[74:77]
	v_mfma_f32_16x16x32_bf16 v[70:73], v[210:213], v[202:205], v[70:73]
	v_mfma_f32_16x16x32_bf16 v[66:69], v[218:221], v[202:205], v[66:69]
	v_mfma_f32_16x16x32_bf16 v[114:117], v[214:217], v[176:179], v[114:117]
	v_mfma_f32_16x16x32_bf16 v[106:109], v[222:225], v[176:179], v[106:109]
	v_mfma_f32_16x16x32_bf16 v[98:101], v[214:217], v[184:187], v[98:101]
	v_mfma_f32_16x16x32_bf16 v[90:93], v[222:225], v[184:187], v[90:93]
	v_mfma_f32_16x16x32_bf16 v[82:85], v[214:217], v[192:195], v[82:85]
	v_mfma_f32_16x16x32_bf16 v[74:77], v[222:225], v[192:195], v[74:77]
	v_mfma_f32_16x16x32_bf16 v[70:73], v[214:217], v[206:209], v[70:73]
	v_mfma_f32_16x16x32_bf16 v[66:69], v[222:225], v[206:209], v[66:69]
	s_setprio 0
	s_mov_b32 m0, s58
	s_add_u32 s68, s50, 0x80
	s_addc_u32 s69, s51, 0
	s_barrier
	ds_read_b128 v[172:175], v149 offset:49152
	ds_read_b128 v[176:179], v149 offset:50176
	ds_read_b128 v[180:183], v149 offset:51200
	ds_read_b128 v[184:187], v149 offset:52224
	ds_read_b128 v[188:191], v149 offset:53248
	ds_read_b128 v[192:195], v149 offset:54272
	ds_read_b128 v[202:205], v149 offset:55296
	ds_read_b128 v[206:209], v149 offset:56320
	global_load_lds_dwordx4 v130, s[68:69]
	s_mov_b32 m0, s59
	s_nop 0
	global_load_lds_dwordx4 v132, s[68:69]
	s_barrier
; #define PG8_STAGE(bufoff, gbase, voff) do { _Pragma("unroll") for (int _i = 0; _i < 2; ++_i) \
;         __builtin_amdgcn_global_load_lds((const unsigned*)((const char*)(gbase) + (voff)[_i]), (LAS unsigned*)(lds + (bufoff) + ldsw + _i * 8192), 16, 0, 0); } while (0)
; #define PG8_LDA(dst, b, h) do { _Pragma("unroll") for (int m = 0; m < 4; ++m) _Pragma("unroll") for (int k = 0; k < 2; ++k) dst[m][k] = *(const LAS bf16x8*)(lds + PG8_SA(b, h) + aoff + m * 2048 + k * 1024); } while (0)
; #define PG8_MMA(ai, bj, At, Bt) do { __builtin_amdgcn_s_setprio(1); _Pragma("unroll") for (int m = 0; m < 4; ++m) _Pragma("unroll") for (int n = 0; n < 2; ++n) _Pragma("unroll") for (int k = 0; k < 2; ++k) \
;         acc[ai][bj][m][n] = __builtin_amdgcn_mfma_f32_16x16x32_bf16(Bt[n][k], At[m][k], acc[ai][bj][m][n], 0, 0, 0); __builtin_amdgcn_s_setprio(0); } while (0)
; #define PG8_WAIT_V(n) asm volatile("s_waitcnt vmcnt(" #n ")" ::: "memory")
; #define PG8_WAIT_L(n) asm volatile("s_waitcnt lgkmcnt(" #n ")" ::: "memory")
; #define PG8_BAR __builtin_amdgcn_s_barrier()
; #define PG8_SCHED __builtin_amdgcn_sched_barrier(0)
; template <class Epi>
; __device__ __forceinline__ void gemm_phase(LAS unsigned char* lds, const Gemm g, const StaticOrder& S, const Epi& E) {
;     ...
;             PG8_LDA(At, 1, 1); PG8_STAGE(PG8_SA(1, 0), a3, voffA);
;             PG8_BAR; PG8_WAIT_L(0); PG8_MMA(1, 0, At, B0); PG8_BAR; PG8_SCHED;
;             PG8_STAGE(PG8_SB(1, 1), b3 + hB, voffB);
;             PG8_WAIT_V(6); PG8_BAR; PG8_MMA(1, 1, At, B1); PG8_BAR;
;         }
;         if constexpr (Epi::HAS_PRE) { E(acc, cur, wr, wc, fr, fq, pre); if (has_next) E.pre(pre, nxt, wr, fr); } else E(acc, cur, wr, wc, fr, fq);
;     __device__ __forceinline__ void operator()(const Acc& acc, const Unit& u, int wr, int wc, int fr, int fq, const RsPre& pr) const {
;         asm volatile("" : "+v"(fr), "+v"(fq));
;         const int row0 = u.pm * 256 + wr * 64 + fr, col0 = u.pn * 256 + wc * 32 + 8 * fq;
;         const float (&rs)[2][4] = pr.rs;
; #pragma unroll
;         for (int ai = 0; ai < 2; ++ai)
; #pragma unroll
;             for (int m = 0; m < 4; ++m) { bf16_t* rowp = O + (size_t)(row0 + ai * 128 + m * 16) * ldc + col0;
; #pragma unroll
;                 for (int bj = 0; bj < 2; ++bj) *(u32x4*)(rowp + bj * 128) = pack8(acc[ai][bj][m][0] * rs[ai][m], acc[ai][bj][m][1] * rs[ai][m]); }
	s_waitcnt lgkmcnt(0)
	s_setprio 1
	s_waitcnt lgkmcnt(0)
	v_mfma_f32_16x16x32_bf16 v[62:65], v[156:159], v[172:175], v[62:65]
	v_mfma_f32_16x16x32_bf16 v[58:61], v[164:167], v[172:175], v[58:61]
	v_mfma_f32_16x16x32_bf16 v[54:57], v[156:159], v[180:183], v[54:57]
	v_mfma_f32_16x16x32_bf16 v[46:49], v[164:167], v[180:183], v[46:49]
	v_mfma_f32_16x16x32_bf16 v[38:41], v[156:159], v[188:191], v[38:41]
	v_mfma_f32_16x16x32_bf16 v[30:33], v[164:167], v[188:191], v[30:33]
	v_mfma_f32_16x16x32_bf16 v[22:25], v[156:159], v[202:205], v[22:25]
	v_mfma_f32_16x16x32_bf16 v[14:17], v[164:167], v[202:205], v[14:17]
	v_mfma_f32_16x16x32_bf16 v[62:65], v[160:163], v[176:179], v[62:65]
	v_mfma_f32_16x16x32_bf16 v[58:61], v[168:171], v[176:179], v[58:61]
	v_mfma_f32_16x16x32_bf16 v[54:57], v[160:163], v[184:187], v[54:57]
	v_mfma_f32_16x16x32_bf16 v[46:49], v[168:171], v[184:187], v[46:49]
	v_mfma_f32_16x16x32_bf16 v[38:41], v[160:163], v[192:195], v[38:41]
	v_mfma_f32_16x16x32_bf16 v[30:33], v[168:171], v[192:195], v[30:33]
	v_mfma_f32_16x16x32_bf16 v[22:25], v[160:163], v[206:209], v[22:25]
	v_mfma_f32_16x16x32_bf16 v[14:17], v[168:171], v[206:209], v[14:17]
	s_setprio 0
	s_barrier
	s_add_u32 s48, s48, 0x40080
	s_addc_u32 s49, s49, 0
	s_add_i32 s100, s100, s33
	s_mov_b32 m0, s100
	s_nop 0
	global_load_lds_dwordx4 v0, s[48:49]
	s_add_i32 m0, s100, 0x2000
	s_nop 0
	global_load_lds_dwordx4 v134, s[48:49]
	s_waitcnt vmcnt(6)
	s_barrier
	s_setprio 1
	v_mfma_f32_16x16x32_bf16 v[50:53], v[210:213], v[172:175], v[50:53]
	v_mfma_f32_16x16x32_bf16 v[42:45], v[218:221], v[172:175], v[42:45]
	v_mfma_f32_16x16x32_bf16 v[34:37], v[210:213], v[180:183], v[34:37]
	v_mfma_f32_16x16x32_bf16 v[26:29], v[218:221], v[180:183], v[26:29]
	v_mfma_f32_16x16x32_bf16 v[18:21], v[210:213], v[188:191], v[18:21]
	v_mfma_f32_16x16x32_bf16 v[10:13], v[218:221], v[188:191], v[10:13]
	v_mfma_f32_16x16x32_bf16 v[6:9], v[210:213], v[202:205], v[6:9]
	v_mfma_f32_16x16x32_bf16 v[2:5], v[218:221], v[202:205], v[2:5]
	v_mfma_f32_16x16x32_bf16 v[50:53], v[214:217], v[176:179], v[50:53]
	v_mfma_f32_16x16x32_bf16 v[42:45], v[222:225], v[176:179], v[42:45]
	v_mfma_f32_16x16x32_bf16 v[34:37], v[214:217], v[184:187], v[34:37]
	v_mfma_f32_16x16x32_bf16 v[26:29], v[222:225], v[184:187], v[26:29]
	v_mfma_f32_16x16x32_bf16 v[18:21], v[214:217], v[192:195], v[18:21]
	v_mfma_f32_16x16x32_bf16 v[10:13], v[222:225], v[192:195], v[10:13]
	v_mfma_f32_16x16x32_bf16 v[6:9], v[214:217], v[206:209], v[6:9]
	v_mfma_f32_16x16x32_bf16 v[2:5], v[222:225], v[206:209], v[2:5]
	s_setprio 0
	s_add_i32 s66, s66, 2
	s_add_u32 s46, s46, 0x100
	s_addc_u32 s47, s47, 0
	s_add_u32 s64, s64, 0x100
	s_addc_u32 s65, s65, 0
	s_cmp_gt_u32 s66, 13
	s_barrier
	s_cbranch_scc0 .LBB0_623
	v_mov_b32_e32 v151, v137
	v_mov_b32_e32 v153, v139
	s_lshl_b32 s15, s44, 8
	s_add_i32 s15, s15, s52
	v_add_u32_e32 v151, s15, v151
	s_lshl_b32 s15, s45, 8
	s_or_b32 s15, s15, s57
	v_lshl_add_u32 v158, v153, 3, s15
	v_lshlrev_b32_e32 v158, 1, v158
	v_mad_u32_u24 v160, v151, s96, v158
	s_waitcnt vmcnt(0)
	v_pk_mul_f32 v[128:129], v[154:155], v[128:129] op_sel_hi:[0,1]
	v_pk_mul_f32 v[126:127], v[154:155], v[126:127] op_sel_hi:[0,1]
	v_pk_mul_f32 v[162:163], v[154:155], v[124:125] op_sel_hi:[0,1]
	v_pk_mul_f32 v[124:125], v[154:155], v[122:123] op_sel_hi:[0,1]
	v_cvt_pk_bf16_f32 v122, v126, v127
	v_cvt_pk_bf16_f32 v123, v128, v129
	v_cvt_pk_bf16_f32 v124, v124, v125
	v_cvt_pk_bf16_f32 v125, v162, v163
	global_store_dwordx4 v160, v[122:125], s[20:21]
	v_pk_mul_f32 v[116:117], v[154:155], v[116:117] op_sel_hi:[0,1]
	v_pk_mul_f32 v[114:115], v[154:155], v[114:115] op_sel_hi:[0,1]
	v_pk_mul_f32 v[122:123], v[154:155], v[108:109] op_sel_hi:[0,1]
	v_pk_mul_f32 v[108:109], v[154:155], v[106:107] op_sel_hi:[0,1]
	v_cvt_pk_bf16_f32 v106, v114, v115
	v_cvt_pk_bf16_f32 v107, v116, v117
	v_cvt_pk_bf16_f32 v108, v108, v109
	v_cvt_pk_bf16_f32 v109, v122, v123
	global_store_dwordx4 v160, v[106:109], s[20:21] offset:256
	v_pk_mul_f32 v[112:113], v[152:153], v[112:113] op_sel_hi:[0,1]
	v_pk_mul_f32 v[110:111], v[152:153], v[110:111] op_sel_hi:[0,1]
	v_add_u32_e32 v114, 0x22000, v160
	v_pk_mul_f32 v[108:109], v[152:153], v[120:121] op_sel_hi:[0,1]
	v_pk_mul_f32 v[106:107], v[152:153], v[118:119] op_sel_hi:[0,1]
	v_cvt_pk_bf16_f32 v106, v106, v107
	v_cvt_pk_bf16_f32 v107, v108, v109
	v_cvt_pk_bf16_f32 v108, v110, v111
	v_cvt_pk_bf16_f32 v109, v112, v113
	global_store_dwordx4 v114, v[106:109], s[20:21]
	v_pk_mul_f32 v[100:101], v[152:153], v[100:101] op_sel_hi:[0,1]
	v_pk_mul_f32 v[98:99], v[152:153], v[98:99] op_sel_hi:[0,1]
	v_pk_mul_f32 v[106:107], v[152:153], v[92:93] op_sel_hi:[0,1]
	v_pk_mul_f32 v[92:93], v[152:153], v[90:91] op_sel_hi:[0,1]
	v_cvt_pk_bf16_f32 v90, v98, v99
	v_cvt_pk_bf16_f32 v91, v100, v101
	v_cvt_pk_bf16_f32 v92, v92, v93
	v_cvt_pk_bf16_f32 v93, v106, v107
	global_store_dwordx4 v114, v[90:93], s[20:21] offset:256
	v_pk_mul_f32 v[96:97], v[150:151], v[96:97] op_sel_hi:[0,1]
	v_pk_mul_f32 v[94:95], v[150:151], v[94:95] op_sel_hi:[0,1]
	v_add_u32_e32 v98, 0x44000, v160
	v_pk_mul_f32 v[92:93], v[150:151], v[104:105] op_sel_hi:[0,1]
	v_pk_mul_f32 v[90:91], v[150:151], v[102:103] op_sel_hi:[0,1]
	v_cvt_pk_bf16_f32 v90, v90, v91
	v_cvt_pk_bf16_f32 v91, v92, v93
	v_cvt_pk_bf16_f32 v92, v94, v95
	v_cvt_pk_bf16_f32 v93, v96, v97
	global_store_dwordx4 v98, v[90:93], s[20:21]
	v_pk_mul_f32 v[84:85], v[150:151], v[84:85] op_sel_hi:[0,1]
; __device__ __forceinline__ u32x4 pack8(const f32x4 a, const f32x4 b) { u32x4 w; w.x = cvt_pk_bf16(a[0], a[1]); w.y = cvt_pk_bf16(a[2], a[3]); w.z = cvt_pk_bf16(b[0], b[1]); w.w = cvt_pk_bf16(b[2], b[3]); return w; }
; template <class Epi>
; __device__ __forceinline__ void gemm_phase(LAS unsigned char* lds, const Gemm g, const StaticOrder& S, const Epi& E) {
;     ...
;         if constexpr (Epi::HAS_PRE) { E(acc, cur, wr, wc, fr, fq, pre); if (has_next) E.pre(pre, nxt, wr, fr); } else E(acc, cur, wr, wc, fr, fq);
;     __device__ __forceinline__ void pre(RsPre& r, const Unit& u, int wr, int fr) const {
; #pragma unroll
;         for (int ai = 0; ai < 2; ++ai)
; #pragma unroll
;             for (int m = 0; m < 4; ++m) r.rs[ai][m] = rsv[u.pm * 256 + wr * 64 + fr + ai * 128 + m * 16]; }
;     __device__ __forceinline__ void operator()(const Acc& acc, const Unit& u, int wr, int wc, int fr, int fq, const RsPre& pr) const {
;     ...
;         for (int ai = 0; ai < 2; ++ai)
; #pragma unroll
;             for (int m = 0; m < 4; ++m) { bf16_t* rowp = O + (size_t)(row0 + ai * 128 + m * 16) * ldc + col0;
; #pragma unroll
;                 for (int bj = 0; bj < 2; ++bj) *(u32x4*)(rowp + bj * 128) = pack8(acc[ai][bj][m][0] * rs[ai][m], acc[ai][bj][m][1] * rs[ai][m]); }
	v_pk_mul_f32 v[82:83], v[150:151], v[82:83] op_sel_hi:[0,1]
	v_pk_mul_f32 v[90:91], v[150:151], v[76:77] op_sel_hi:[0,1]
	v_pk_mul_f32 v[76:77], v[150:151], v[74:75] op_sel_hi:[0,1]
	v_cvt_pk_bf16_f32 v74, v82, v83
	v_cvt_pk_bf16_f32 v75, v84, v85
	v_cvt_pk_bf16_f32 v76, v76, v77
	v_cvt_pk_bf16_f32 v77, v90, v91
	global_store_dwordx4 v98, v[74:77], s[20:21] offset:256
	v_pk_mul_f32 v[80:81], v[148:149], v[80:81] op_sel_hi:[0,1]
	v_pk_mul_f32 v[78:79], v[148:149], v[78:79] op_sel_hi:[0,1]
	v_add_u32_e32 v82, 0x66000, v160
	v_pk_mul_f32 v[76:77], v[148:149], v[88:89] op_sel_hi:[0,1]
	v_pk_mul_f32 v[74:75], v[148:149], v[86:87] op_sel_hi:[0,1]
	v_cvt_pk_bf16_f32 v74, v74, v75
	v_cvt_pk_bf16_f32 v75, v76, v77
	v_cvt_pk_bf16_f32 v76, v78, v79
	v_cvt_pk_bf16_f32 v77, v80, v81
	global_store_dwordx4 v82, v[74:77], s[20:21]
	v_pk_mul_f32 v[72:73], v[148:149], v[72:73] op_sel_hi:[0,1]
	v_pk_mul_f32 v[70:71], v[148:149], v[70:71] op_sel_hi:[0,1]
	v_pk_mul_f32 v[74:75], v[148:149], v[68:69] op_sel_hi:[0,1]
	v_pk_mul_f32 v[68:69], v[148:149], v[66:67] op_sel_hi:[0,1]
	v_cvt_pk_bf16_f32 v66, v70, v71
	v_cvt_pk_bf16_f32 v67, v72, v73
	v_cvt_pk_bf16_f32 v68, v68, v69
	v_cvt_pk_bf16_f32 v69, v74, v75
	global_store_dwordx4 v82, v[66:69], s[20:21] offset:256
	v_pk_mul_f32 v[64:65], v[142:143], v[64:65] op_sel_hi:[0,1]
	v_pk_mul_f32 v[62:63], v[142:143], v[62:63] op_sel_hi:[0,1]
	v_pk_mul_f32 v[68:69], v[142:143], v[60:61] op_sel_hi:[0,1]
	v_pk_mul_f32 v[60:61], v[142:143], v[58:59] op_sel_hi:[0,1]
	v_add_u32_e32 v66, 0x110000, v160
	v_cvt_pk_bf16_f32 v58, v62, v63
	v_cvt_pk_bf16_f32 v59, v64, v65
	v_cvt_pk_bf16_f32 v60, v60, v61
	v_cvt_pk_bf16_f32 v61, v68, v69
	global_store_dwordx4 v66, v[58:61], s[20:21]
	v_pk_mul_f32 v[52:53], v[142:143], v[52:53] op_sel_hi:[0,1]
	v_pk_mul_f32 v[50:51], v[142:143], v[50:51] op_sel_hi:[0,1]
	v_pk_mul_f32 v[58:59], v[142:143], v[44:45] op_sel_hi:[0,1]
	v_pk_mul_f32 v[44:45], v[142:143], v[42:43] op_sel_hi:[0,1]
	v_cvt_pk_bf16_f32 v42, v50, v51
	v_cvt_pk_bf16_f32 v43, v52, v53
	v_cvt_pk_bf16_f32 v44, v44, v45
	v_cvt_pk_bf16_f32 v45, v58, v59
	global_store_dwordx4 v66, v[42:45], s[20:21] offset:256
	v_pk_mul_f32 v[48:49], v[140:141], v[48:49] op_sel_hi:[0,1]
	v_pk_mul_f32 v[46:47], v[140:141], v[46:47] op_sel_hi:[0,1]
	v_add_u32_e32 v50, 0x132000, v160
	v_pk_mul_f32 v[44:45], v[140:141], v[56:57] op_sel_hi:[0,1]
	v_pk_mul_f32 v[42:43], v[140:141], v[54:55] op_sel_hi:[0,1]
	v_cvt_pk_bf16_f32 v42, v42, v43
	v_cvt_pk_bf16_f32 v43, v44, v45
	v_cvt_pk_bf16_f32 v44, v46, v47
	v_cvt_pk_bf16_f32 v45, v48, v49
	global_store_dwordx4 v50, v[42:45], s[20:21]
	v_pk_mul_f32 v[36:37], v[140:141], v[36:37] op_sel_hi:[0,1]
	v_pk_mul_f32 v[34:35], v[140:141], v[34:35] op_sel_hi:[0,1]
	v_pk_mul_f32 v[42:43], v[140:141], v[28:29] op_sel_hi:[0,1]
	v_pk_mul_f32 v[28:29], v[140:141], v[26:27] op_sel_hi:[0,1]
	v_cvt_pk_bf16_f32 v26, v34, v35
	v_cvt_pk_bf16_f32 v27, v36, v37
	v_cvt_pk_bf16_f32 v28, v28, v29
	v_cvt_pk_bf16_f32 v29, v42, v43
	global_store_dwordx4 v50, v[26:29], s[20:21] offset:256
	v_pk_mul_f32 v[32:33], v[138:139], v[32:33] op_sel_hi:[0,1]
	v_pk_mul_f32 v[30:31], v[138:139], v[30:31] op_sel_hi:[0,1]
	v_add_u32_e32 v34, 0x154000, v160
	v_pk_mul_f32 v[28:29], v[138:139], v[40:41] op_sel_hi:[0,1]
	v_pk_mul_f32 v[26:27], v[138:139], v[38:39] op_sel_hi:[0,1]
	v_cvt_pk_bf16_f32 v26, v26, v27
	v_cvt_pk_bf16_f32 v27, v28, v29
	v_cvt_pk_bf16_f32 v28, v30, v31
	v_cvt_pk_bf16_f32 v29, v32, v33
	global_store_dwordx4 v34, v[26:29], s[20:21]
	v_pk_mul_f32 v[20:21], v[138:139], v[20:21] op_sel_hi:[0,1]
	v_pk_mul_f32 v[18:19], v[138:139], v[18:19] op_sel_hi:[0,1]
	v_pk_mul_f32 v[26:27], v[138:139], v[12:13] op_sel_hi:[0,1]
	v_pk_mul_f32 v[12:13], v[138:139], v[10:11] op_sel_hi:[0,1]
	v_cvt_pk_bf16_f32 v10, v18, v19
	v_cvt_pk_bf16_f32 v11, v20, v21
	v_cvt_pk_bf16_f32 v12, v12, v13
	v_cvt_pk_bf16_f32 v13, v26, v27
	global_store_dwordx4 v34, v[10:13], s[20:21] offset:256
	v_pk_mul_f32 v[16:17], v[136:137], v[16:17] op_sel_hi:[0,1]
	v_pk_mul_f32 v[14:15], v[136:137], v[14:15] op_sel_hi:[0,1]
	v_add_u32_e32 v18, 0x176000, v160
	v_pk_mul_f32 v[12:13], v[136:137], v[24:25] op_sel_hi:[0,1]
	v_pk_mul_f32 v[10:11], v[136:137], v[22:23] op_sel_hi:[0,1]
	v_cvt_pk_bf16_f32 v10, v10, v11
	v_cvt_pk_bf16_f32 v11, v12, v13
	v_cvt_pk_bf16_f32 v12, v14, v15
	v_cvt_pk_bf16_f32 v13, v16, v17
	global_store_dwordx4 v18, v[10:13], s[20:21]
	v_pk_mul_f32 v[8:9], v[136:137], v[8:9] op_sel_hi:[0,1]
	v_pk_mul_f32 v[6:7], v[136:137], v[6:7] op_sel_hi:[0,1]
	v_pk_mul_f32 v[10:11], v[136:137], v[4:5] op_sel_hi:[0,1]
	v_pk_mul_f32 v[4:5], v[136:137], v[2:3] op_sel_hi:[0,1]
	v_cvt_pk_bf16_f32 v2, v6, v7
	v_cvt_pk_bf16_f32 v3, v8, v9
	v_cvt_pk_bf16_f32 v4, v4, v5
	v_cvt_pk_bf16_f32 v5, v10, v11
	s_mov_b64 s[44:45], -1
	s_and_b64 vcc, vcc, exec
	global_store_dwordx4 v18, v[2:5], s[20:21] offset:256
	s_cbranch_vccz .LBB0_615
	s_nop 0
	v_lshl_add_u32 v2, s22, 8, v141
	v_ashrrev_i32_e32 v3, 31, v2
	v_lshl_add_u64 v[2:3], v[2:3], 2, s[10:11]
	global_load_dword v154, v[2:3], off
	global_load_dword v152, v[2:3], off offset:64
	global_load_dword v150, v[2:3], off offset:128
	global_load_dword v148, v[2:3], off offset:192
	global_load_dword v142, v[2:3], off offset:512
	global_load_dword v140, v[2:3], off offset:576
	global_load_dword v138, v[2:3], off offset:640
	global_load_dword v136, v[2:3], off offset:704
	s_mov_b64 s[44:45], 0
	s_branch .LBB0_615

; __global__ void __launch_bounds__(512, 2) hybrid_fwd(Params p0) {
;     extern __shared__ __attribute__((aligned(16))) unsigned char shm[];
	.amdhsa_kernel _Z10hybrid_fwd6Params
		.amdhsa_group_segment_fixed_size 0
		.amdhsa_private_segment_fixed_size 0
		.amdhsa_kernarg_size 496
		.amdhsa_user_sgpr_count 2
		.amdhsa_user_sgpr_dispatch_ptr 0
		.amdhsa_user_sgpr_queue_ptr 0
		.amdhsa_user_sgpr_kernarg_segment_ptr 1
		.amdhsa_user_sgpr_dispatch_id 0
		.amdhsa_user_sgpr_kernarg_preload_length 0
		.amdhsa_user_sgpr_kernarg_preload_offset 0
		.amdhsa_user_sgpr_private_segment_size 0
		.amdhsa_uses_dynamic_stack 0
		.amdhsa_enable_private_segment 0
		.amdhsa_system_sgpr_workgroup_id_x 1
		.amdhsa_system_sgpr_workgroup_id_y 0
		.amdhsa_system_sgpr_workgroup_id_z 0
		.amdhsa_system_sgpr_workgroup_info 0
		.amdhsa_system_vgpr_workitem_id 2
		.amdhsa_next_free_vgpr 254
		.amdhsa_next_free_sgpr 102
		.amdhsa_accum_offset 256
		.amdhsa_reserve_vcc 1
		.amdhsa_float_round_mode_32 0
		.amdhsa_float_round_mode_16_64 0
		.amdhsa_float_denorm_mode_32 3
		.amdhsa_float_denorm_mode_16_64 3
		.amdhsa_dx10_clamp 1
		.amdhsa_ieee_mode 1
		.amdhsa_fp16_overflow 0
		.amdhsa_tg_split 0
		.amdhsa_exception_fp_ieee_invalid_op 0
		.amdhsa_exception_fp_denorm_src 0
		.amdhsa_exception_fp_ieee_div_zero 0
		.amdhsa_exception_fp_ieee_overflow 0
		.amdhsa_exception_fp_ieee_underflow 0
		.amdhsa_exception_fp_ieee_inexact 0
		.amdhsa_exception_int_div_zero 0
	.end_amdhsa_kernel

; #define LAS __attribute__((address_space(3)))
; __global__ void __launch_bounds__(512, 2) hybrid_fwd(Params p0) {
;     extern __shared__ __attribute__((aligned(16))) unsigned char shm[];
;     LAS unsigned char* lds = (LAS unsigned char*)shm;
amdhsa.kernels:
  - .agpr_count:     0
    .args:
      - .offset:         0
        .size:           240
        .value_kind:     by_value
      - .offset:         240
        .size:           4
        .value_kind:     hidden_block_count_x
      - .offset:         244
        .size:           4
        .value_kind:     hidden_block_count_y
      - .offset:         248
        .size:           4
        .value_kind:     hidden_block_count_z
      - .offset:         252
        .size:           2
        .value_kind:     hidden_group_size_x
      - .offset:         254
        .size:           2
        .value_kind:     hidden_group_size_y
      - .offset:         256
        .size:           2
        .value_kind:     hidden_group_size_z
      - .offset:         258
        .size:           2
        .value_kind:     hidden_remainder_x
      - .offset:         260
        .size:           2
        .value_kind:     hidden_remainder_y
      - .offset:         262
        .size:           2
        .value_kind:     hidden_remainder_z
      - .offset:         280
        .size:           8
        .value_kind:     hidden_global_offset_x
      - .offset:         288
        .size:           8
        .value_kind:     hidden_global_offset_y
      - .offset:         296
        .size:           8
        .value_kind:     hidden_global_offset_z
      - .offset:         304
        .size:           2
        .value_kind:     hidden_grid_dims
      - .offset:         328
        .size:           8
        .value_kind:     hidden_multigrid_sync_arg
      - .offset:         360
        .size:           4
        .value_kind:     hidden_dynamic_lds_size
    .group_segment_fixed_size: 0
    .kernarg_segment_align: 8
    .kernarg_segment_size: 496
    .language:       OpenCL C
    .language_version:
      - 2
      - 0
    .max_flat_workgroup_size: 512
    .name:           _Z10hybrid_fwd6Params
    .private_segment_fixed_size: 0
    .sgpr_count:     108
    .sgpr_spill_count: 117
    .symbol:         _Z10hybrid_fwd6Params.kd
    .uniform_work_group_size: 1
    .uses_dynamic_stack: false
    .vgpr_count:     254
    .vgpr_spill_count: 0
    .wavefront_size: 64
